# GEMM mainloops: same-accumulator k-step pairs back to back, pairs grouped by shared A fragment
# speedup vs baseline: 1.0123x; 1.0019x over previous
.LBB0_298:
	s_lshl_b64 s[4:5], s[20:21], 17
	s_add_u32 s24, s2, s4
	s_addc_u32 s25, s19, s5
	s_and_b64 s[4:5], s[36:37], exec
	s_cselect_b32 s37, s25, s31
	s_cselect_b32 s36, s24, s30
	s_add_u32 s56, s30, 0x100
	s_addc_u32 s57, s31, 0
	s_add_u32 s80, s34, 0x100
	s_addc_u32 s81, s35, 0
	s_add_u32 s38, s30, 0x180
	s_addc_u32 s39, s31, 0
	s_add_i32 s4, 0, 0x10000
	s_add_i32 s17, 0, 0x14000
	v_add_u32_e32 v128, s4, v134
	v_add_u32_e32 v129, s17, v134
	ds_read_b128 v[0:3], v128
	ds_read_b128 v[4:7], v128 offset:1024
	ds_read_b128 v[8:11], v128 offset:2048
	ds_read_b128 v[12:15], v128 offset:3072
	ds_read_b128 v[16:19], v129
	ds_read_b128 v[20:23], v129 offset:1024
	ds_read_b128 v[24:27], v129 offset:2048
	ds_read_b128 v[28:31], v129 offset:3072
	s_add_u32 s70, s30, 0x10080
	s_addc_u32 s71, s31, 0
	s_add_i32 s5, s13, 0xc000
	s_mov_b32 m0, s5
	s_add_i32 s15, s13, 0xe000
	ds_read_b128 v[32:35], v135
	ds_read_b128 v[36:39], v135 offset:1024
	ds_read_b128 v[40:43], v135 offset:2048
	ds_read_b128 v[44:47], v135 offset:3072
	ds_read_b128 v[48:51], v135 offset:4096
	ds_read_b128 v[52:55], v135 offset:5120
	ds_read_b128 v[56:59], v135 offset:6144
	ds_read_b128 v[60:63], v135 offset:7168
	s_nop 0
	global_load_lds_dwordx4 v130, s[70:71]
	s_mov_b32 m0, s15
	s_nop 0
	global_load_lds_dwordx4 v132, s[70:71]
	s_waitcnt vmcnt(8)
	s_waitcnt lgkmcnt(0)
	s_barrier
	s_setprio 1
	s_waitcnt lgkmcnt(0)
	v_mfma_f32_16x16x32_bf16 v[64:67], v[0:3], v[32:35], 0
	v_mfma_f32_16x16x32_bf16 v[68:71], v[8:11], v[32:35], 0
	v_mfma_f32_16x16x32_bf16 v[72:75], v[0:3], v[40:43], 0
	v_mfma_f32_16x16x32_bf16 v[76:79], v[8:11], v[40:43], 0
	v_mfma_f32_16x16x32_bf16 v[80:83], v[0:3], v[48:51], 0
	v_mfma_f32_16x16x32_bf16 v[84:87], v[8:11], v[48:51], 0
	v_mfma_f32_16x16x32_bf16 v[88:91], v[0:3], v[56:59], 0
	v_mfma_f32_16x16x32_bf16 v[92:95], v[8:11], v[56:59], 0
	v_mfma_f32_16x16x32_bf16 v[64:67], v[4:7], v[36:39], v[64:67]
	v_mfma_f32_16x16x32_bf16 v[68:71], v[12:15], v[36:39], v[68:71]
	v_mfma_f32_16x16x32_bf16 v[72:75], v[4:7], v[44:47], v[72:75]
	v_mfma_f32_16x16x32_bf16 v[76:79], v[12:15], v[44:47], v[76:79]
	v_mfma_f32_16x16x32_bf16 v[80:83], v[4:7], v[52:55], v[80:83]
	v_mfma_f32_16x16x32_bf16 v[84:87], v[12:15], v[52:55], v[84:87]
	v_mfma_f32_16x16x32_bf16 v[88:91], v[4:7], v[60:63], v[88:91]
	v_mfma_f32_16x16x32_bf16 v[92:95], v[12:15], v[60:63], v[92:95]
	s_setprio 0
	s_setprio 1
	v_mfma_f32_16x16x32_bf16 v[96:99], v[16:19], v[32:35], 0
	v_mfma_f32_16x16x32_bf16 v[32:35], v[24:27], v[32:35], 0
	v_mfma_f32_16x16x32_bf16 v[96:99], v[20:23], v[36:39], v[96:99]
	v_mfma_f32_16x16x32_bf16 v[32:35], v[28:31], v[36:39], v[32:35]
	v_mfma_f32_16x16x32_bf16 v[36:39], v[16:19], v[40:43], 0
	v_mfma_f32_16x16x32_bf16 v[40:43], v[24:27], v[40:43], 0
	v_mfma_f32_16x16x32_bf16 v[36:39], v[20:23], v[44:47], v[36:39]
	v_mfma_f32_16x16x32_bf16 v[40:43], v[28:31], v[44:47], v[40:43]
	v_mfma_f32_16x16x32_bf16 v[44:47], v[16:19], v[48:51], 0
	v_mfma_f32_16x16x32_bf16 v[48:51], v[24:27], v[48:51], 0
	v_mfma_f32_16x16x32_bf16 v[44:47], v[20:23], v[52:55], v[44:47]
	v_mfma_f32_16x16x32_bf16 v[48:51], v[28:31], v[52:55], v[48:51]
	v_mfma_f32_16x16x32_bf16 v[52:55], v[16:19], v[56:59], 0
	v_mfma_f32_16x16x32_bf16 v[56:59], v[24:27], v[56:59], 0
	v_mfma_f32_16x16x32_bf16 v[52:55], v[20:23], v[60:63], v[52:55]
	v_mfma_f32_16x16x32_bf16 v[56:59], v[28:31], v[60:63], v[56:59]
	s_setprio 0
	s_barrier
	s_add_i32 s70, s4, s97
	s_add_i32 s4, s70, 0x2000
	s_mov_b32 m0, s70
	s_add_u32 s74, s34, 0x80100
	ds_read_b128 v[60:63], v135 offset:16384
	ds_read_b128 v[100:103], v135 offset:17408
	ds_read_b128 v[104:107], v135 offset:18432
	ds_read_b128 v[108:111], v135 offset:19456
	ds_read_b128 v[112:115], v135 offset:20480
	ds_read_b128 v[116:119], v135 offset:21504
	ds_read_b128 v[120:123], v135 offset:22528
	ds_read_b128 v[124:127], v135 offset:23552
	s_addc_u32 s75, s35, 0
	global_load_lds_dwordx4 v131, s[80:81]
	s_mov_b32 m0, s4
	s_add_i32 s17, s17, s97
	s_add_i32 s21, s17, 0x2000
	global_load_lds_dwordx4 v133, s[80:81]
	s_mov_b32 m0, s17
	s_nop 0
	global_load_lds_dwordx4 v131, s[74:75]
	s_mov_b32 m0, s21
	s_nop 0
	global_load_lds_dwordx4 v133, s[74:75]
	s_mov_b32 m0, s13
	s_nop 0
	global_load_lds_dwordx4 v130, s[56:57]
	s_mov_b32 m0, s27
	s_nop 0
	global_load_lds_dwordx4 v132, s[56:57]
	s_waitcnt vmcnt(8)
	s_waitcnt lgkmcnt(0)
	s_barrier
	s_setprio 1
	s_waitcnt lgkmcnt(0)
	v_mfma_f32_16x16x32_bf16 v[136:139], v[0:3], v[60:63], 0
	v_mfma_f32_16x16x32_bf16 v[144:147], v[0:3], v[104:107], 0
	v_mfma_f32_16x16x32_bf16 v[152:155], v[0:3], v[112:115], 0
	v_mfma_f32_16x16x32_bf16 v[0:3], v[0:3], v[120:123], 0
	v_mfma_f32_16x16x32_bf16 v[136:139], v[4:7], v[100:103], v[136:139]
	v_mfma_f32_16x16x32_bf16 v[144:147], v[4:7], v[108:111], v[144:147]
	v_mfma_f32_16x16x32_bf16 v[152:155], v[4:7], v[116:119], v[152:155]
	v_mfma_f32_16x16x32_bf16 v[0:3], v[4:7], v[124:127], v[0:3]
	v_mfma_f32_16x16x32_bf16 v[4:7], v[8:11], v[120:123], 0
	v_mfma_f32_16x16x32_bf16 v[140:143], v[8:11], v[60:63], 0
	v_mfma_f32_16x16x32_bf16 v[148:151], v[8:11], v[104:107], 0
	v_mfma_f32_16x16x32_bf16 v[156:159], v[8:11], v[112:115], 0
	v_mfma_f32_16x16x32_bf16 v[4:7], v[12:15], v[124:127], v[4:7]
	v_mfma_f32_16x16x32_bf16 v[140:143], v[12:15], v[100:103], v[140:143]
	v_mfma_f32_16x16x32_bf16 v[148:151], v[12:15], v[108:111], v[148:151]
	v_mfma_f32_16x16x32_bf16 v[156:159], v[12:15], v[116:119], v[156:159]
	s_setprio 0
	s_setprio 1
	v_mfma_f32_16x16x32_bf16 v[8:11], v[16:19], v[60:63], 0
	v_mfma_f32_16x16x32_bf16 v[12:15], v[24:27], v[60:63], 0
	v_mfma_f32_16x16x32_bf16 v[8:11], v[20:23], v[100:103], v[8:11]
	v_mfma_f32_16x16x32_bf16 v[12:15], v[28:31], v[100:103], v[12:15]
	v_mfma_f32_16x16x32_bf16 v[60:63], v[16:19], v[104:107], 0
	v_mfma_f32_16x16x32_bf16 v[100:103], v[24:27], v[104:107], 0
	v_mfma_f32_16x16x32_bf16 v[104:107], v[16:19], v[112:115], 0
	v_mfma_f32_16x16x32_bf16 v[16:19], v[16:19], v[120:123], 0
	v_mfma_f32_16x16x32_bf16 v[60:63], v[20:23], v[108:111], v[60:63]
	v_mfma_f32_16x16x32_bf16 v[100:103], v[28:31], v[108:111], v[100:103]
	v_mfma_f32_16x16x32_bf16 v[104:107], v[20:23], v[116:119], v[104:107]
	v_mfma_f32_16x16x32_bf16 v[108:111], v[24:27], v[112:115], 0
	v_mfma_f32_16x16x32_bf16 v[16:19], v[20:23], v[124:127], v[16:19]
	v_mfma_f32_16x16x32_bf16 v[20:23], v[24:27], v[120:123], 0
	v_mfma_f32_16x16x32_bf16 v[108:111], v[28:31], v[116:119], v[108:111]
	v_mfma_f32_16x16x32_bf16 v[20:23], v[28:31], v[124:127], v[20:23]
	s_setprio 0
	s_barrier
	s_add_i32 s71, 0, 0x18000
	s_add_i32 s69, 0, 0x1c000
	v_add_u32_e32 v196, s71, v134
	v_add_u32_e32 v198, s69, v134
	ds_read_b128 v[24:27], v196
	ds_read_b128 v[28:31], v196 offset:1024
	ds_read_b128 v[112:115], v196 offset:2048
	ds_read_b128 v[116:119], v196 offset:3072
	ds_read_b128 v[120:123], v198
	ds_read_b128 v[124:127], v198 offset:1024
	ds_read_b128 v[160:163], v198 offset:2048
	ds_read_b128 v[164:167], v198 offset:3072
	s_add_u32 s56, s30, 0x10100
	s_addc_u32 s57, s31, 0
	s_mov_b32 m0, s29
	ds_read_b128 v[168:171], v135 offset:32768
	ds_read_b128 v[172:175], v135 offset:33792
	ds_read_b128 v[176:179], v135 offset:34816
	ds_read_b128 v[180:183], v135 offset:35840
	ds_read_b128 v[184:187], v135 offset:36864
	ds_read_b128 v[188:191], v135 offset:37888
	ds_read_b128 v[192:195], v135 offset:38912
	ds_read_b128 v[200:203], v135 offset:39936
	s_nop 0
	global_load_lds_dwordx4 v130, s[56:57]
	s_mov_b32 m0, s47
	s_nop 0
	global_load_lds_dwordx4 v132, s[56:57]
	s_waitcnt vmcnt(8)
	s_waitcnt lgkmcnt(0)
	s_barrier
	s_setprio 1
	s_waitcnt lgkmcnt(0)
	v_mfma_f32_16x16x32_bf16 v[64:67], v[24:27], v[168:171], v[64:67]
	v_mfma_f32_16x16x32_bf16 v[64:67], v[28:31], v[172:175], v[64:67]
	v_mfma_f32_16x16x32_bf16 v[72:75], v[24:27], v[176:179], v[72:75]
	v_mfma_f32_16x16x32_bf16 v[72:75], v[28:31], v[180:183], v[72:75]
	v_mfma_f32_16x16x32_bf16 v[80:83], v[24:27], v[184:187], v[80:83]
	v_mfma_f32_16x16x32_bf16 v[80:83], v[28:31], v[188:191], v[80:83]
	v_mfma_f32_16x16x32_bf16 v[88:91], v[24:27], v[192:195], v[88:91]
	v_mfma_f32_16x16x32_bf16 v[88:91], v[28:31], v[200:203], v[88:91]
	v_mfma_f32_16x16x32_bf16 v[68:71], v[112:115], v[168:171], v[68:71]
	v_mfma_f32_16x16x32_bf16 v[68:71], v[116:119], v[172:175], v[68:71]
	v_mfma_f32_16x16x32_bf16 v[76:79], v[112:115], v[176:179], v[76:79]
	v_mfma_f32_16x16x32_bf16 v[76:79], v[116:119], v[180:183], v[76:79]
	v_mfma_f32_16x16x32_bf16 v[84:87], v[112:115], v[184:187], v[84:87]
	v_mfma_f32_16x16x32_bf16 v[84:87], v[116:119], v[188:191], v[84:87]
	v_mfma_f32_16x16x32_bf16 v[92:95], v[112:115], v[192:195], v[92:95]
	v_mfma_f32_16x16x32_bf16 v[92:95], v[116:119], v[200:203], v[92:95]
	s_setprio 0
	s_setprio 1
	v_mfma_f32_16x16x32_bf16 v[96:99], v[120:123], v[168:171], v[96:99]
	v_mfma_f32_16x16x32_bf16 v[96:99], v[124:127], v[172:175], v[96:99]
	v_mfma_f32_16x16x32_bf16 v[36:39], v[120:123], v[176:179], v[36:39]
	v_mfma_f32_16x16x32_bf16 v[36:39], v[124:127], v[180:183], v[36:39]
	v_mfma_f32_16x16x32_bf16 v[44:47], v[120:123], v[184:187], v[44:47]
	v_mfma_f32_16x16x32_bf16 v[44:47], v[124:127], v[188:191], v[44:47]
	v_mfma_f32_16x16x32_bf16 v[52:55], v[120:123], v[192:195], v[52:55]
	v_mfma_f32_16x16x32_bf16 v[52:55], v[124:127], v[200:203], v[52:55]
	v_mfma_f32_16x16x32_bf16 v[32:35], v[160:163], v[168:171], v[32:35]
	v_mfma_f32_16x16x32_bf16 v[32:35], v[164:167], v[172:175], v[32:35]
	v_mfma_f32_16x16x32_bf16 v[40:43], v[160:163], v[176:179], v[40:43]
	v_mfma_f32_16x16x32_bf16 v[40:43], v[164:167], v[180:183], v[40:43]
	v_mfma_f32_16x16x32_bf16 v[48:51], v[160:163], v[184:187], v[48:51]
	v_mfma_f32_16x16x32_bf16 v[48:51], v[164:167], v[188:191], v[48:51]
	v_mfma_f32_16x16x32_bf16 v[56:59], v[160:163], v[192:195], v[56:59]
	v_mfma_f32_16x16x32_bf16 v[56:59], v[164:167], v[200:203], v[56:59]
	s_setprio 0
	s_barrier
	s_add_u32 s74, s34, 0x180
	s_addc_u32 s75, s35, 0
	s_add_i32 s71, s71, s97
	s_add_i32 s56, s71, 0x2000
	s_mov_b32 m0, s71
	s_add_u32 s34, s34, 0x80180
	ds_read_b128 v[168:171], v135 offset:49152
	ds_read_b128 v[172:175], v135 offset:50176
	ds_read_b128 v[176:179], v135 offset:51200
	ds_read_b128 v[180:183], v135 offset:52224
	ds_read_b128 v[184:187], v135 offset:53248
	ds_read_b128 v[188:191], v135 offset:54272
	ds_read_b128 v[192:195], v135 offset:55296
	ds_read_b128 v[200:203], v135 offset:56320
	s_addc_u32 s35, s35, 0
	global_load_lds_dwordx4 v131, s[74:75]
	s_mov_b32 m0, s56
	s_add_i32 s57, s69, s97
	s_add_i32 s69, s57, 0x2000
	global_load_lds_dwordx4 v133, s[74:75]
	s_mov_b32 m0, s57
	s_nop 0
	global_load_lds_dwordx4 v131, s[34:35]
	s_mov_b32 m0, s69
	s_nop 0
	global_load_lds_dwordx4 v133, s[34:35]
	s_mov_b32 m0, s48
	s_nop 0
	global_load_lds_dwordx4 v130, s[38:39]
	s_mov_b32 m0, s49
	s_nop 0
	global_load_lds_dwordx4 v132, s[38:39]
	s_waitcnt vmcnt(8)
	s_waitcnt lgkmcnt(0)
	s_barrier
	s_setprio 1
	s_waitcnt lgkmcnt(0)
	v_mfma_f32_16x16x32_bf16 v[0:3], v[24:27], v[192:195], v[0:3]
	v_mfma_f32_16x16x32_bf16 v[0:3], v[28:31], v[200:203], v[0:3]
	v_mfma_f32_16x16x32_bf16 v[136:139], v[24:27], v[168:171], v[136:139]
	v_mfma_f32_16x16x32_bf16 v[136:139], v[28:31], v[172:175], v[136:139]
	v_mfma_f32_16x16x32_bf16 v[144:147], v[24:27], v[176:179], v[144:147]
	v_mfma_f32_16x16x32_bf16 v[144:147], v[28:31], v[180:183], v[144:147]
	v_mfma_f32_16x16x32_bf16 v[152:155], v[24:27], v[184:187], v[152:155]
	v_mfma_f32_16x16x32_bf16 v[152:155], v[28:31], v[188:191], v[152:155]
	v_mfma_f32_16x16x32_bf16 v[4:7], v[112:115], v[192:195], v[4:7]
	v_mfma_f32_16x16x32_bf16 v[4:7], v[116:119], v[200:203], v[4:7]
	v_mfma_f32_16x16x32_bf16 v[140:143], v[112:115], v[168:171], v[140:143]
	v_mfma_f32_16x16x32_bf16 v[140:143], v[116:119], v[172:175], v[140:143]
	v_mfma_f32_16x16x32_bf16 v[148:151], v[112:115], v[176:179], v[148:151]
	v_mfma_f32_16x16x32_bf16 v[148:151], v[116:119], v[180:183], v[148:151]
	v_mfma_f32_16x16x32_bf16 v[156:159], v[112:115], v[184:187], v[156:159]
	v_mfma_f32_16x16x32_bf16 v[156:159], v[116:119], v[188:191], v[156:159]
	s_setprio 0
	s_setprio 1
	v_mfma_f32_16x16x32_bf16 v[8:11], v[120:123], v[168:171], v[8:11]
	v_mfma_f32_16x16x32_bf16 v[12:15], v[160:163], v[168:171], v[12:15]
	v_mfma_f32_16x16x32_bf16 v[24:27], v[120:123], v[176:179], v[60:63]
	v_mfma_f32_16x16x32_bf16 v[28:31], v[160:163], v[176:179], v[100:103]
	v_mfma_f32_16x16x32_bf16 v[60:63], v[120:123], v[184:187], v[104:107]
	v_mfma_f32_16x16x32_bf16 v[100:103], v[160:163], v[184:187], v[108:111]
	v_mfma_f32_16x16x32_bf16 v[16:19], v[120:123], v[192:195], v[16:19]
	v_mfma_f32_16x16x32_bf16 v[20:23], v[160:163], v[192:195], v[20:23]
	v_mfma_f32_16x16x32_bf16 v[8:11], v[124:127], v[172:175], v[8:11]
	v_mfma_f32_16x16x32_bf16 v[12:15], v[164:167], v[172:175], v[12:15]
	v_mfma_f32_16x16x32_bf16 v[24:27], v[124:127], v[180:183], v[24:27]
	v_mfma_f32_16x16x32_bf16 v[28:31], v[164:167], v[180:183], v[28:31]
	v_mfma_f32_16x16x32_bf16 v[60:63], v[124:127], v[188:191], v[60:63]
	v_mfma_f32_16x16x32_bf16 v[100:103], v[164:167], v[188:191], v[100:103]
	v_mfma_f32_16x16x32_bf16 v[16:19], v[124:127], v[200:203], v[16:19]
	v_mfma_f32_16x16x32_bf16 v[20:23], v[164:167], v[200:203], v[20:23]
	s_setprio 0
	s_barrier
	ds_read_b128 v[104:107], v128
	ds_read_b128 v[108:111], v128 offset:1024
	ds_read_b128 v[112:115], v128 offset:2048
	ds_read_b128 v[116:119], v128 offset:3072
	ds_read_b128 v[120:123], v129
	ds_read_b128 v[124:127], v129 offset:1024
	ds_read_b128 v[160:163], v129 offset:2048
	ds_read_b128 v[164:167], v129 offset:3072
	s_add_u32 s34, s36, 0x80
	s_addc_u32 s35, s37, 0
	s_add_u32 s30, s30, 0x10180
	s_addc_u32 s31, s31, 0
	s_mov_b32 m0, s5
	ds_read_b128 v[168:171], v135
	ds_read_b128 v[172:175], v135 offset:1024
	ds_read_b128 v[176:179], v135 offset:2048
	ds_read_b128 v[180:183], v135 offset:3072
	ds_read_b128 v[184:187], v135 offset:4096
	ds_read_b128 v[188:191], v135 offset:5120
	ds_read_b128 v[192:195], v135 offset:6144
	ds_read_b128 v[200:203], v135 offset:7168
	s_nop 0
	global_load_lds_dwordx4 v130, s[30:31]
	s_mov_b32 m0, s15
	s_nop 0
	global_load_lds_dwordx4 v132, s[30:31]
	s_waitcnt vmcnt(8)
	s_waitcnt lgkmcnt(0)
	s_barrier
	s_setprio 1
	s_waitcnt lgkmcnt(0)
	v_mfma_f32_16x16x32_bf16 v[64:67], v[104:107], v[168:171], v[64:67]
	v_mfma_f32_16x16x32_bf16 v[64:67], v[108:111], v[172:175], v[64:67]
	v_mfma_f32_16x16x32_bf16 v[72:75], v[104:107], v[176:179], v[72:75]
	v_mfma_f32_16x16x32_bf16 v[72:75], v[108:111], v[180:183], v[72:75]
	v_mfma_f32_16x16x32_bf16 v[80:83], v[104:107], v[184:187], v[80:83]
	v_mfma_f32_16x16x32_bf16 v[80:83], v[108:111], v[188:191], v[80:83]
	v_mfma_f32_16x16x32_bf16 v[88:91], v[104:107], v[192:195], v[88:91]
	v_mfma_f32_16x16x32_bf16 v[88:91], v[108:111], v[200:203], v[88:91]
	v_mfma_f32_16x16x32_bf16 v[68:71], v[112:115], v[168:171], v[68:71]
	v_mfma_f32_16x16x32_bf16 v[68:71], v[116:119], v[172:175], v[68:71]
	v_mfma_f32_16x16x32_bf16 v[76:79], v[112:115], v[176:179], v[76:79]
	v_mfma_f32_16x16x32_bf16 v[76:79], v[116:119], v[180:183], v[76:79]
	v_mfma_f32_16x16x32_bf16 v[84:87], v[112:115], v[184:187], v[84:87]
	v_mfma_f32_16x16x32_bf16 v[84:87], v[116:119], v[188:191], v[84:87]
	v_mfma_f32_16x16x32_bf16 v[92:95], v[112:115], v[192:195], v[92:95]
	v_mfma_f32_16x16x32_bf16 v[92:95], v[116:119], v[200:203], v[92:95]
	s_setprio 0
	s_setprio 1
	v_mfma_f32_16x16x32_bf16 v[32:35], v[160:163], v[168:171], v[32:35]
	v_mfma_f32_16x16x32_bf16 v[96:99], v[120:123], v[168:171], v[96:99]
	v_mfma_f32_16x16x32_bf16 v[168:171], v[164:167], v[172:175], v[32:35]
	v_mfma_f32_16x16x32_bf16 v[32:35], v[120:123], v[176:179], v[36:39]
	v_mfma_f32_16x16x32_bf16 v[36:39], v[124:127], v[180:183], v[32:35]
	v_mfma_f32_16x16x32_bf16 v[32:35], v[160:163], v[176:179], v[40:43]
	v_mfma_f32_16x16x32_bf16 v[204:207], v[124:127], v[172:175], v[96:99]
	v_mfma_f32_16x16x32_bf16 v[172:175], v[164:167], v[180:183], v[32:35]
	v_mfma_f32_16x16x32_bf16 v[32:35], v[120:123], v[184:187], v[44:47]
	v_mfma_f32_16x16x32_bf16 v[44:47], v[124:127], v[188:191], v[32:35]
	v_mfma_f32_16x16x32_bf16 v[32:35], v[160:163], v[184:187], v[48:51]
	v_mfma_f32_16x16x32_bf16 v[48:51], v[164:167], v[188:191], v[32:35]
	v_mfma_f32_16x16x32_bf16 v[32:35], v[120:123], v[192:195], v[52:55]
	v_mfma_f32_16x16x32_bf16 v[52:55], v[124:127], v[200:203], v[32:35]
	v_mfma_f32_16x16x32_bf16 v[32:35], v[160:163], v[192:195], v[56:59]
	v_mfma_f32_16x16x32_bf16 v[56:59], v[164:167], v[200:203], v[32:35]
	s_setprio 0
	s_barrier
	s_mov_b32 m0, s70
	s_mov_b64 s[30:31], s[22:23]
	s_nop 2
	ds_read_b128 v[32:35], v135 offset:16384
	ds_read_b128 v[40:43], v135 offset:17408
	ds_read_b128 v[96:99], v135 offset:18432
	ds_read_b128 v[176:179], v135 offset:19456
	ds_read_b128 v[180:183], v135 offset:20480
	ds_read_b128 v[184:187], v135 offset:21504
	ds_read_b128 v[188:191], v135 offset:22528
	ds_read_b128 v[192:195], v135 offset:23552
	s_nop 0
	global_load_lds_dwordx4 v131, s[30:31]
	s_mov_b32 m0, s4
	s_add_u32 s4, s22, 0x80000
	s_addc_u32 s5, s23, 0
	global_load_lds_dwordx4 v133, s[30:31]
	s_mov_b32 m0, s17
	s_nop 0
	global_load_lds_dwordx4 v131, s[4:5]
	s_mov_b32 m0, s21
	s_nop 0
	global_load_lds_dwordx4 v133, s[4:5]
	s_mov_b64 s[4:5], s[36:37]
	s_mov_b32 m0, s13
	s_nop 0
	global_load_lds_dwordx4 v130, s[4:5]
	s_mov_b32 m0, s27
	s_nop 0
	global_load_lds_dwordx4 v132, s[4:5]
	s_waitcnt vmcnt(8)
	s_waitcnt lgkmcnt(0)
	s_barrier
	s_setprio 1
	s_waitcnt lgkmcnt(0)
	v_mfma_f32_16x16x32_bf16 v[0:3], v[104:107], v[188:191], v[0:3]
	v_mfma_f32_16x16x32_bf16 v[0:3], v[108:111], v[192:195], v[0:3]
	v_mfma_f32_16x16x32_bf16 v[136:139], v[104:107], v[32:35], v[136:139]
	v_mfma_f32_16x16x32_bf16 v[136:139], v[108:111], v[40:43], v[136:139]
	v_mfma_f32_16x16x32_bf16 v[144:147], v[104:107], v[96:99], v[144:147]
	v_mfma_f32_16x16x32_bf16 v[144:147], v[108:111], v[176:179], v[144:147]
	v_mfma_f32_16x16x32_bf16 v[152:155], v[104:107], v[180:183], v[152:155]
	v_mfma_f32_16x16x32_bf16 v[152:155], v[108:111], v[184:187], v[152:155]
	v_mfma_f32_16x16x32_bf16 v[4:7], v[112:115], v[188:191], v[4:7]
	v_mfma_f32_16x16x32_bf16 v[4:7], v[116:119], v[192:195], v[4:7]
	v_mfma_f32_16x16x32_bf16 v[140:143], v[112:115], v[32:35], v[140:143]
	v_mfma_f32_16x16x32_bf16 v[140:143], v[116:119], v[40:43], v[140:143]
	v_mfma_f32_16x16x32_bf16 v[148:151], v[112:115], v[96:99], v[148:151]
	v_mfma_f32_16x16x32_bf16 v[148:151], v[116:119], v[176:179], v[148:151]
	v_mfma_f32_16x16x32_bf16 v[156:159], v[112:115], v[180:183], v[156:159]
	v_mfma_f32_16x16x32_bf16 v[156:159], v[116:119], v[184:187], v[156:159]
	s_setprio 0
	s_setprio 1
	v_mfma_f32_16x16x32_bf16 v[12:15], v[160:163], v[32:35], v[12:15]
	v_mfma_f32_16x16x32_bf16 v[200:203], v[164:167], v[40:43], v[12:15]
	v_mfma_f32_16x16x32_bf16 v[12:15], v[120:123], v[96:99], v[24:27]
	v_mfma_f32_16x16x32_bf16 v[24:27], v[124:127], v[176:179], v[12:15]
	v_mfma_f32_16x16x32_bf16 v[12:15], v[160:163], v[96:99], v[28:31]
	v_mfma_f32_16x16x32_bf16 v[176:179], v[164:167], v[176:179], v[12:15]
	v_mfma_f32_16x16x32_bf16 v[12:15], v[120:123], v[180:183], v[60:63]
	v_mfma_f32_16x16x32_bf16 v[208:211], v[124:127], v[184:187], v[12:15]
	v_mfma_f32_16x16x32_bf16 v[12:15], v[160:163], v[180:183], v[100:103]
	v_mfma_f32_16x16x32_bf16 v[8:11], v[120:123], v[32:35], v[8:11]
	v_mfma_f32_16x16x32_bf16 v[180:183], v[164:167], v[184:187], v[12:15]
	v_mfma_f32_16x16x32_bf16 v[12:15], v[120:123], v[188:191], v[16:19]
	v_mfma_f32_16x16x32_bf16 v[8:11], v[124:127], v[40:43], v[8:11]
	v_mfma_f32_16x16x32_bf16 v[184:187], v[124:127], v[192:195], v[12:15]
	v_mfma_f32_16x16x32_bf16 v[12:15], v[160:163], v[188:191], v[20:23]
	v_mfma_f32_16x16x32_bf16 v[160:163], v[164:167], v[192:195], v[12:15]
	s_setprio 0
	s_barrier
	s_nop 4
	ds_read_b128 v[12:15], v196
	ds_read_b128 v[16:19], v196 offset:1024
	ds_read_b128 v[164:167], v196 offset:2048
	ds_read_b128 v[188:191], v196 offset:3072
	ds_read_b128 v[192:195], v198
	ds_read_b128 v[220:223], v198 offset:1024
	ds_read_b128 v[224:227], v198 offset:2048
	ds_read_b128 v[228:231], v198 offset:3072
	s_add_u32 s4, s36, 0x10000
	s_addc_u32 s5, s37, 0
	s_mov_b32 m0, s29
	ds_read_b128 v[20:23], v135 offset:32768
	ds_read_b128 v[28:31], v135 offset:33792
	ds_read_b128 v[60:63], v135 offset:34816
	ds_read_b128 v[100:103], v135 offset:35840
	ds_read_b128 v[232:235], v135 offset:36864
	ds_read_b128 v[236:239], v135 offset:37888
	ds_read_b128 v[240:243], v135 offset:38912
	ds_read_b128 v[244:247], v135 offset:39936
	s_nop 0
	global_load_lds_dwordx4 v130, s[4:5]
	s_mov_b32 m0, s47
	s_nop 0
	global_load_lds_dwordx4 v132, s[4:5]
	s_waitcnt vmcnt(8)
	s_waitcnt lgkmcnt(0)
	s_barrier
	s_setprio 1
	s_waitcnt lgkmcnt(0)
	v_mfma_f32_16x16x32_bf16 v[32:35], v[12:15], v[20:23], v[64:67]
	v_mfma_f32_16x16x32_bf16 v[120:123], v[16:19], v[28:31], v[32:35]
	v_mfma_f32_16x16x32_bf16 v[32:35], v[164:167], v[20:23], v[68:71]
	v_mfma_f32_16x16x32_bf16 v[112:115], v[188:191], v[28:31], v[32:35]
	v_mfma_f32_16x16x32_bf16 v[32:35], v[12:15], v[60:63], v[72:75]
	v_mfma_f32_16x16x32_bf16 v[104:107], v[16:19], v[100:103], v[32:35]
	v_mfma_f32_16x16x32_bf16 v[32:35], v[164:167], v[60:63], v[76:79]
	v_mfma_f32_16x16x32_bf16 v[96:99], v[188:191], v[100:103], v[32:35]
	v_mfma_f32_16x16x32_bf16 v[32:35], v[12:15], v[232:235], v[80:83]
	v_mfma_f32_16x16x32_bf16 v[72:75], v[16:19], v[236:239], v[32:35]
	v_mfma_f32_16x16x32_bf16 v[32:35], v[164:167], v[232:235], v[84:87]
	v_mfma_f32_16x16x32_bf16 v[64:67], v[188:191], v[236:239], v[32:35]
	v_mfma_f32_16x16x32_bf16 v[32:35], v[12:15], v[240:243], v[88:91]
	v_mfma_f32_16x16x32_bf16 v[40:43], v[16:19], v[244:247], v[32:35]
	v_mfma_f32_16x16x32_bf16 v[32:35], v[164:167], v[240:243], v[92:95]
	v_mfma_f32_16x16x32_bf16 v[32:35], v[188:191], v[244:247], v[32:35]
	s_setprio 0
	s_setprio 1
	v_mfma_f32_16x16x32_bf16 v[68:71], v[192:195], v[20:23], v[204:207]
	v_mfma_f32_16x16x32_bf16 v[20:23], v[224:227], v[20:23], v[168:171]
	v_mfma_f32_16x16x32_bf16 v[116:119], v[228:231], v[28:31], v[20:23]
	v_mfma_f32_16x16x32_bf16 v[20:23], v[192:195], v[60:63], v[36:39]
	v_mfma_f32_16x16x32_bf16 v[108:111], v[220:223], v[100:103], v[20:23]
	v_mfma_f32_16x16x32_bf16 v[20:23], v[224:227], v[60:63], v[172:175]
	v_mfma_f32_16x16x32_bf16 v[100:103], v[228:231], v[100:103], v[20:23]
	v_mfma_f32_16x16x32_bf16 v[20:23], v[192:195], v[232:235], v[44:47]
	v_mfma_f32_16x16x32_bf16 v[76:79], v[220:223], v[236:239], v[20:23]
	v_mfma_f32_16x16x32_bf16 v[20:23], v[224:227], v[232:235], v[48:51]
	v_mfma_f32_16x16x32_bf16 v[124:127], v[220:223], v[28:31], v[68:71]
	v_mfma_f32_16x16x32_bf16 v[68:71], v[228:231], v[236:239], v[20:23]
	v_mfma_f32_16x16x32_bf16 v[20:23], v[192:195], v[240:243], v[52:55]
	v_mfma_f32_16x16x32_bf16 v[44:47], v[220:223], v[244:247], v[20:23]
	v_mfma_f32_16x16x32_bf16 v[20:23], v[224:227], v[240:243], v[56:59]
	v_mfma_f32_16x16x32_bf16 v[36:39], v[228:231], v[244:247], v[20:23]
	s_setprio 0
	s_barrier
	s_add_u32 s4, s22, 0x80
	s_mov_b32 m0, s71
	s_addc_u32 s5, s23, 0
	ds_read_b128 v[48:51], v135 offset:49152
	ds_read_b128 v[56:59], v135 offset:50176
	ds_read_b128 v[168:171], v135 offset:51200
	ds_read_b128 v[172:175], v135 offset:52224
	ds_read_b128 v[204:207], v135 offset:53248
	ds_read_b128 v[232:235], v135 offset:54272
	ds_read_b128 v[236:239], v135 offset:55296
	ds_read_b128 v[240:243], v135 offset:56320
	s_nop 0
	global_load_lds_dwordx4 v131, s[4:5]
	s_mov_b32 m0, s56
	s_nop 0
	global_load_lds_dwordx4 v133, s[4:5]
	s_add_u32 s4, s22, 0x80080
	s_addc_u32 s5, s23, 0
	s_mov_b32 m0, s57
	s_nop 0
	global_load_lds_dwordx4 v131, s[4:5]
	s_mov_b32 m0, s69
	s_nop 0
	global_load_lds_dwordx4 v133, s[4:5]
	s_mov_b32 m0, s48
	s_nop 0
	global_load_lds_dwordx4 v130, s[34:35]
	s_mov_b32 m0, s49
	s_nop 0
	global_load_lds_dwordx4 v132, s[34:35]
	s_waitcnt vmcnt(8)
	s_waitcnt lgkmcnt(0)
	s_barrier
	s_setprio 1
	s_waitcnt lgkmcnt(0)
	v_mfma_f32_16x16x32_bf16 v[20:23], v[12:15], v[48:51], v[136:139]
	v_mfma_f32_16x16x32_bf16 v[92:95], v[16:19], v[56:59], v[20:23]
	v_mfma_f32_16x16x32_bf16 v[20:23], v[164:167], v[48:51], v[140:143]
	v_mfma_f32_16x16x32_bf16 v[84:87], v[188:191], v[56:59], v[20:23]
	v_mfma_f32_16x16x32_bf16 v[20:23], v[12:15], v[168:171], v[144:147]
	v_mfma_f32_16x16x32_bf16 v[60:63], v[16:19], v[172:175], v[20:23]
	v_mfma_f32_16x16x32_bf16 v[20:23], v[164:167], v[168:171], v[148:151]
	v_mfma_f32_16x16x32_bf16 v[52:55], v[188:191], v[172:175], v[20:23]
	v_mfma_f32_16x16x32_bf16 v[20:23], v[12:15], v[204:207], v[152:155]
	v_mfma_f32_16x16x32_bf16 v[0:3], v[12:15], v[236:239], v[0:3]
	v_mfma_f32_16x16x32_bf16 v[28:31], v[16:19], v[232:235], v[20:23]
	v_mfma_f32_16x16x32_bf16 v[20:23], v[164:167], v[204:207], v[156:159]
	v_mfma_f32_16x16x32_bf16 v[12:15], v[16:19], v[240:243], v[0:3]
	v_mfma_f32_16x16x32_bf16 v[0:3], v[164:167], v[236:239], v[4:7]
	v_mfma_f32_16x16x32_bf16 v[20:23], v[188:191], v[232:235], v[20:23]
	v_mfma_f32_16x16x32_bf16 v[4:7], v[188:191], v[240:243], v[0:3]
	s_setprio 0
	s_setprio 1
	v_mfma_f32_16x16x32_bf16 v[0:3], v[192:195], v[48:51], v[8:11]
	v_mfma_f32_16x16x32_bf16 v[88:91], v[220:223], v[56:59], v[0:3]
	v_mfma_f32_16x16x32_bf16 v[0:3], v[224:227], v[48:51], v[200:203]
	v_mfma_f32_16x16x32_bf16 v[80:83], v[228:231], v[56:59], v[0:3]
	v_mfma_f32_16x16x32_bf16 v[0:3], v[192:195], v[168:171], v[24:27]
	v_mfma_f32_16x16x32_bf16 v[56:59], v[220:223], v[172:175], v[0:3]
	v_mfma_f32_16x16x32_bf16 v[0:3], v[224:227], v[168:171], v[176:179]
	v_mfma_f32_16x16x32_bf16 v[48:51], v[228:231], v[172:175], v[0:3]
	v_mfma_f32_16x16x32_bf16 v[0:3], v[192:195], v[204:207], v[208:211]
	v_mfma_f32_16x16x32_bf16 v[24:27], v[220:223], v[232:235], v[0:3]
	v_mfma_f32_16x16x32_bf16 v[0:3], v[224:227], v[204:207], v[180:183]
	v_mfma_f32_16x16x32_bf16 v[16:19], v[228:231], v[232:235], v[0:3]
	v_mfma_f32_16x16x32_bf16 v[0:3], v[192:195], v[236:239], v[184:187]
	v_mfma_f32_16x16x32_bf16 v[8:11], v[220:223], v[240:243], v[0:3]
	v_mfma_f32_16x16x32_bf16 v[0:3], v[224:227], v[236:239], v[160:163]
	v_mfma_f32_16x16x32_bf16 v[0:3], v[228:231], v[240:243], v[0:3]
	s_setprio 0
	s_barrier
	s_andn2_b64 vcc, exec, s[60:61]
	s_cbranch_vccnz .LBB0_300
	s_barrier

.LBB0_313:
	s_ashr_i32 s15, s14, 31
	s_lshl_b64 s[4:5], s[14:15], 17
	s_add_u32 s20, s2, s4
	s_addc_u32 s21, s19, s5
	s_and_b64 s[4:5], s[16:17], exec
	s_cselect_b32 s39, s21, s31
	s_cselect_b32 s38, s20, s30
	s_ashr_i32 s11, s10, 31
	s_lshl_b64 s[4:5], s[10:11], 9
	s_add_u32 s11, s44, s4
	s_addc_u32 s15, s46, s5
	s_ashr_i32 s13, s12, 31
	s_lshl_b64 s[4:5], s[12:13], 20
	s_add_u32 s22, s11, s4
	s_addc_u32 s23, s15, s5
	s_and_b64 s[4:5], s[16:17], exec
	s_cselect_b32 s35, s23, s37
	s_cselect_b32 s34, s22, s36
	s_add_u32 s56, s30, 0x100
	s_addc_u32 s57, s31, 0
	s_add_u32 s82, s36, 0x100
	s_addc_u32 s83, s37, 0
	s_add_u32 s80, s30, 0x180
	s_addc_u32 s81, s31, 0
	s_add_i32 s4, 0, 0x10000
	s_add_i32 s13, 0, 0x14000
	v_add_u32_e32 v128, s4, v134
	v_add_u32_e32 v129, s13, v134
	ds_read_b128 v[0:3], v128
	ds_read_b128 v[4:7], v128 offset:1024
	ds_read_b128 v[8:11], v128 offset:2048
	ds_read_b128 v[12:15], v128 offset:3072
	ds_read_b128 v[16:19], v129
	ds_read_b128 v[20:23], v129 offset:1024
	ds_read_b128 v[24:27], v129 offset:2048
	ds_read_b128 v[28:31], v129 offset:3072
	s_add_u32 s70, s30, 0x10080
	s_addc_u32 s71, s31, 0
	s_add_i32 s5, s25, 0xc000
	s_mov_b32 m0, s5
	s_add_i32 s11, s25, 0xe000
	ds_read_b128 v[32:35], v135
	ds_read_b128 v[36:39], v135 offset:1024
	ds_read_b128 v[40:43], v135 offset:2048
	ds_read_b128 v[44:47], v135 offset:3072
	ds_read_b128 v[48:51], v135 offset:4096
	ds_read_b128 v[52:55], v135 offset:5120
	ds_read_b128 v[56:59], v135 offset:6144
	ds_read_b128 v[60:63], v135 offset:7168
	s_nop 0
	global_load_lds_dwordx4 v133, s[70:71]
	s_mov_b32 m0, s11
	s_nop 0
	global_load_lds_dwordx4 v131, s[70:71]
	s_waitcnt vmcnt(8)
	s_waitcnt lgkmcnt(0)
	s_barrier
	s_setprio 1
	s_waitcnt lgkmcnt(0)
	v_mfma_f32_16x16x32_bf16 v[64:67], v[0:3], v[32:35], 0
	v_mfma_f32_16x16x32_bf16 v[68:71], v[8:11], v[32:35], 0
	v_mfma_f32_16x16x32_bf16 v[72:75], v[0:3], v[40:43], 0
	v_mfma_f32_16x16x32_bf16 v[76:79], v[8:11], v[40:43], 0
	v_mfma_f32_16x16x32_bf16 v[80:83], v[0:3], v[48:51], 0
	v_mfma_f32_16x16x32_bf16 v[84:87], v[8:11], v[48:51], 0
	v_mfma_f32_16x16x32_bf16 v[88:91], v[0:3], v[56:59], 0
	v_mfma_f32_16x16x32_bf16 v[92:95], v[8:11], v[56:59], 0
	v_mfma_f32_16x16x32_bf16 v[64:67], v[4:7], v[36:39], v[64:67]
	v_mfma_f32_16x16x32_bf16 v[68:71], v[12:15], v[36:39], v[68:71]
	v_mfma_f32_16x16x32_bf16 v[72:75], v[4:7], v[44:47], v[72:75]
	v_mfma_f32_16x16x32_bf16 v[76:79], v[12:15], v[44:47], v[76:79]
	v_mfma_f32_16x16x32_bf16 v[80:83], v[4:7], v[52:55], v[80:83]
	v_mfma_f32_16x16x32_bf16 v[84:87], v[12:15], v[52:55], v[84:87]
	v_mfma_f32_16x16x32_bf16 v[88:91], v[4:7], v[60:63], v[88:91]
	v_mfma_f32_16x16x32_bf16 v[92:95], v[12:15], v[60:63], v[92:95]
	s_setprio 0
	s_setprio 1
	v_mfma_f32_16x16x32_bf16 v[96:99], v[16:19], v[32:35], 0
	v_mfma_f32_16x16x32_bf16 v[32:35], v[24:27], v[32:35], 0
	v_mfma_f32_16x16x32_bf16 v[96:99], v[20:23], v[36:39], v[96:99]
	v_mfma_f32_16x16x32_bf16 v[32:35], v[28:31], v[36:39], v[32:35]
	v_mfma_f32_16x16x32_bf16 v[36:39], v[16:19], v[40:43], 0
	v_mfma_f32_16x16x32_bf16 v[40:43], v[24:27], v[40:43], 0
	v_mfma_f32_16x16x32_bf16 v[36:39], v[20:23], v[44:47], v[36:39]
	v_mfma_f32_16x16x32_bf16 v[40:43], v[28:31], v[44:47], v[40:43]
	v_mfma_f32_16x16x32_bf16 v[44:47], v[16:19], v[48:51], 0
	v_mfma_f32_16x16x32_bf16 v[48:51], v[24:27], v[48:51], 0
	v_mfma_f32_16x16x32_bf16 v[44:47], v[20:23], v[52:55], v[44:47]
	v_mfma_f32_16x16x32_bf16 v[48:51], v[28:31], v[52:55], v[48:51]
	v_mfma_f32_16x16x32_bf16 v[52:55], v[16:19], v[56:59], 0
	v_mfma_f32_16x16x32_bf16 v[56:59], v[24:27], v[56:59], 0
	v_mfma_f32_16x16x32_bf16 v[52:55], v[20:23], v[60:63], v[52:55]
	v_mfma_f32_16x16x32_bf16 v[56:59], v[28:31], v[60:63], v[56:59]
	s_setprio 0
	s_barrier
	s_add_i32 s70, s4, s97
	s_add_i32 s4, s70, 0x2000
	s_mov_b32 m0, s70
	s_add_u32 s74, s36, 0x80100
	ds_read_b128 v[60:63], v135 offset:16384
	ds_read_b128 v[100:103], v135 offset:17408
	ds_read_b128 v[104:107], v135 offset:18432
	ds_read_b128 v[108:111], v135 offset:19456
	ds_read_b128 v[112:115], v135 offset:20480
	ds_read_b128 v[116:119], v135 offset:21504
	ds_read_b128 v[120:123], v135 offset:22528
	ds_read_b128 v[124:127], v135 offset:23552
	s_addc_u32 s75, s37, 0
	global_load_lds_dwordx4 v132, s[82:83]
	s_mov_b32 m0, s4
	s_add_i32 s13, s13, s97
	s_add_i32 s15, s13, 0x2000
	global_load_lds_dwordx4 v130, s[82:83]
	s_mov_b32 m0, s13
	s_nop 0
	global_load_lds_dwordx4 v132, s[74:75]
	s_mov_b32 m0, s15
	s_nop 0
	global_load_lds_dwordx4 v130, s[74:75]
	s_mov_b32 m0, s25
	s_nop 0
	global_load_lds_dwordx4 v133, s[56:57]
	s_mov_b32 m0, s27
	s_nop 0
	global_load_lds_dwordx4 v131, s[56:57]
	s_waitcnt vmcnt(8)
	s_waitcnt lgkmcnt(0)
	s_barrier
	s_setprio 1
	s_waitcnt lgkmcnt(0)
	v_mfma_f32_16x16x32_bf16 v[136:139], v[0:3], v[60:63], 0
	v_mfma_f32_16x16x32_bf16 v[144:147], v[0:3], v[104:107], 0
	v_mfma_f32_16x16x32_bf16 v[152:155], v[0:3], v[112:115], 0
	v_mfma_f32_16x16x32_bf16 v[0:3], v[0:3], v[120:123], 0
	v_mfma_f32_16x16x32_bf16 v[136:139], v[4:7], v[100:103], v[136:139]
	v_mfma_f32_16x16x32_bf16 v[144:147], v[4:7], v[108:111], v[144:147]
	v_mfma_f32_16x16x32_bf16 v[152:155], v[4:7], v[116:119], v[152:155]
	v_mfma_f32_16x16x32_bf16 v[0:3], v[4:7], v[124:127], v[0:3]
	v_mfma_f32_16x16x32_bf16 v[4:7], v[8:11], v[120:123], 0
	v_mfma_f32_16x16x32_bf16 v[140:143], v[8:11], v[60:63], 0
	v_mfma_f32_16x16x32_bf16 v[148:151], v[8:11], v[104:107], 0
	v_mfma_f32_16x16x32_bf16 v[156:159], v[8:11], v[112:115], 0
	v_mfma_f32_16x16x32_bf16 v[4:7], v[12:15], v[124:127], v[4:7]
	v_mfma_f32_16x16x32_bf16 v[140:143], v[12:15], v[100:103], v[140:143]
	v_mfma_f32_16x16x32_bf16 v[148:151], v[12:15], v[108:111], v[148:151]
	v_mfma_f32_16x16x32_bf16 v[156:159], v[12:15], v[116:119], v[156:159]
	s_setprio 0
	s_setprio 1
	v_mfma_f32_16x16x32_bf16 v[8:11], v[16:19], v[60:63], 0
	v_mfma_f32_16x16x32_bf16 v[12:15], v[24:27], v[60:63], 0
	v_mfma_f32_16x16x32_bf16 v[8:11], v[20:23], v[100:103], v[8:11]
	v_mfma_f32_16x16x32_bf16 v[12:15], v[28:31], v[100:103], v[12:15]
	v_mfma_f32_16x16x32_bf16 v[60:63], v[16:19], v[104:107], 0
	v_mfma_f32_16x16x32_bf16 v[100:103], v[24:27], v[104:107], 0
	v_mfma_f32_16x16x32_bf16 v[104:107], v[16:19], v[112:115], 0
	v_mfma_f32_16x16x32_bf16 v[16:19], v[16:19], v[120:123], 0
	v_mfma_f32_16x16x32_bf16 v[60:63], v[20:23], v[108:111], v[60:63]
	v_mfma_f32_16x16x32_bf16 v[100:103], v[28:31], v[108:111], v[100:103]
	v_mfma_f32_16x16x32_bf16 v[104:107], v[20:23], v[116:119], v[104:107]
	v_mfma_f32_16x16x32_bf16 v[108:111], v[24:27], v[112:115], 0
	v_mfma_f32_16x16x32_bf16 v[16:19], v[20:23], v[124:127], v[16:19]
	v_mfma_f32_16x16x32_bf16 v[20:23], v[24:27], v[120:123], 0
	v_mfma_f32_16x16x32_bf16 v[108:111], v[28:31], v[116:119], v[108:111]
	v_mfma_f32_16x16x32_bf16 v[20:23], v[28:31], v[124:127], v[20:23]
	s_setprio 0
	s_barrier
	s_add_i32 s71, 0, 0x18000
	s_add_i32 s69, 0, 0x1c000
	v_add_u32_e32 v196, s71, v134
	v_add_u32_e32 v198, s69, v134
	ds_read_b128 v[24:27], v196
	ds_read_b128 v[28:31], v196 offset:1024
	ds_read_b128 v[112:115], v196 offset:2048
	ds_read_b128 v[116:119], v196 offset:3072
	ds_read_b128 v[120:123], v198
	ds_read_b128 v[124:127], v198 offset:1024
	ds_read_b128 v[160:163], v198 offset:2048
	ds_read_b128 v[164:167], v198 offset:3072
	s_add_u32 s56, s30, 0x10100
	s_addc_u32 s57, s31, 0
	s_mov_b32 m0, s29
	ds_read_b128 v[168:171], v135 offset:32768
	ds_read_b128 v[172:175], v135 offset:33792
	ds_read_b128 v[176:179], v135 offset:34816
	ds_read_b128 v[180:183], v135 offset:35840
	ds_read_b128 v[184:187], v135 offset:36864
	ds_read_b128 v[188:191], v135 offset:37888
	ds_read_b128 v[192:195], v135 offset:38912
	ds_read_b128 v[200:203], v135 offset:39936
	s_nop 0
	global_load_lds_dwordx4 v133, s[56:57]
	s_mov_b32 m0, s47
	s_nop 0
	global_load_lds_dwordx4 v131, s[56:57]
	s_waitcnt vmcnt(8)
	s_waitcnt lgkmcnt(0)
	s_barrier
	s_setprio 1
	s_waitcnt lgkmcnt(0)
	v_mfma_f32_16x16x32_bf16 v[64:67], v[24:27], v[168:171], v[64:67]
	v_mfma_f32_16x16x32_bf16 v[64:67], v[28:31], v[172:175], v[64:67]
	v_mfma_f32_16x16x32_bf16 v[72:75], v[24:27], v[176:179], v[72:75]
	v_mfma_f32_16x16x32_bf16 v[72:75], v[28:31], v[180:183], v[72:75]
	v_mfma_f32_16x16x32_bf16 v[80:83], v[24:27], v[184:187], v[80:83]
	v_mfma_f32_16x16x32_bf16 v[80:83], v[28:31], v[188:191], v[80:83]
	v_mfma_f32_16x16x32_bf16 v[88:91], v[24:27], v[192:195], v[88:91]
	v_mfma_f32_16x16x32_bf16 v[88:91], v[28:31], v[200:203], v[88:91]
	v_mfma_f32_16x16x32_bf16 v[68:71], v[112:115], v[168:171], v[68:71]
	v_mfma_f32_16x16x32_bf16 v[68:71], v[116:119], v[172:175], v[68:71]
	v_mfma_f32_16x16x32_bf16 v[76:79], v[112:115], v[176:179], v[76:79]
	v_mfma_f32_16x16x32_bf16 v[76:79], v[116:119], v[180:183], v[76:79]
	v_mfma_f32_16x16x32_bf16 v[84:87], v[112:115], v[184:187], v[84:87]
	v_mfma_f32_16x16x32_bf16 v[84:87], v[116:119], v[188:191], v[84:87]
	v_mfma_f32_16x16x32_bf16 v[92:95], v[112:115], v[192:195], v[92:95]
	v_mfma_f32_16x16x32_bf16 v[92:95], v[116:119], v[200:203], v[92:95]
	s_setprio 0
	s_setprio 1
	v_mfma_f32_16x16x32_bf16 v[96:99], v[120:123], v[168:171], v[96:99]
	v_mfma_f32_16x16x32_bf16 v[96:99], v[124:127], v[172:175], v[96:99]
	v_mfma_f32_16x16x32_bf16 v[36:39], v[120:123], v[176:179], v[36:39]
	v_mfma_f32_16x16x32_bf16 v[36:39], v[124:127], v[180:183], v[36:39]
	v_mfma_f32_16x16x32_bf16 v[44:47], v[120:123], v[184:187], v[44:47]
	v_mfma_f32_16x16x32_bf16 v[44:47], v[124:127], v[188:191], v[44:47]
	v_mfma_f32_16x16x32_bf16 v[52:55], v[120:123], v[192:195], v[52:55]
	v_mfma_f32_16x16x32_bf16 v[52:55], v[124:127], v[200:203], v[52:55]
	v_mfma_f32_16x16x32_bf16 v[32:35], v[160:163], v[168:171], v[32:35]
	v_mfma_f32_16x16x32_bf16 v[32:35], v[164:167], v[172:175], v[32:35]
	v_mfma_f32_16x16x32_bf16 v[40:43], v[160:163], v[176:179], v[40:43]
	v_mfma_f32_16x16x32_bf16 v[40:43], v[164:167], v[180:183], v[40:43]
	v_mfma_f32_16x16x32_bf16 v[48:51], v[160:163], v[184:187], v[48:51]
	v_mfma_f32_16x16x32_bf16 v[48:51], v[164:167], v[188:191], v[48:51]
	v_mfma_f32_16x16x32_bf16 v[56:59], v[160:163], v[192:195], v[56:59]
	v_mfma_f32_16x16x32_bf16 v[56:59], v[164:167], v[200:203], v[56:59]
	s_setprio 0
	s_barrier
	s_add_u32 s74, s36, 0x180
	s_addc_u32 s75, s37, 0
	s_add_i32 s71, s71, s97
	s_add_i32 s56, s71, 0x2000
	s_mov_b32 m0, s71
	s_add_u32 s36, s36, 0x80180
	ds_read_b128 v[168:171], v135 offset:49152
	ds_read_b128 v[172:175], v135 offset:50176
	ds_read_b128 v[176:179], v135 offset:51200
	ds_read_b128 v[180:183], v135 offset:52224
	ds_read_b128 v[184:187], v135 offset:53248
	ds_read_b128 v[188:191], v135 offset:54272
	ds_read_b128 v[192:195], v135 offset:55296
	ds_read_b128 v[200:203], v135 offset:56320
	s_addc_u32 s37, s37, 0
	global_load_lds_dwordx4 v132, s[74:75]
	s_mov_b32 m0, s56
	s_add_i32 s57, s69, s97
	s_add_i32 s69, s57, 0x2000
	global_load_lds_dwordx4 v130, s[74:75]
	s_mov_b32 m0, s57
	s_nop 0
	global_load_lds_dwordx4 v132, s[36:37]
	s_mov_b32 m0, s69
	s_nop 0
	global_load_lds_dwordx4 v130, s[36:37]
	s_mov_b32 m0, s48
	s_nop 0
	global_load_lds_dwordx4 v133, s[80:81]
	s_mov_b32 m0, s49
	s_nop 0
	global_load_lds_dwordx4 v131, s[80:81]
	s_waitcnt vmcnt(8)
	s_waitcnt lgkmcnt(0)
	s_barrier
	s_setprio 1
	s_waitcnt lgkmcnt(0)
	v_mfma_f32_16x16x32_bf16 v[0:3], v[24:27], v[192:195], v[0:3]
	v_mfma_f32_16x16x32_bf16 v[0:3], v[28:31], v[200:203], v[0:3]
	v_mfma_f32_16x16x32_bf16 v[136:139], v[24:27], v[168:171], v[136:139]
	v_mfma_f32_16x16x32_bf16 v[136:139], v[28:31], v[172:175], v[136:139]
	v_mfma_f32_16x16x32_bf16 v[144:147], v[24:27], v[176:179], v[144:147]
	v_mfma_f32_16x16x32_bf16 v[144:147], v[28:31], v[180:183], v[144:147]
	v_mfma_f32_16x16x32_bf16 v[152:155], v[24:27], v[184:187], v[152:155]
	v_mfma_f32_16x16x32_bf16 v[152:155], v[28:31], v[188:191], v[152:155]
	v_mfma_f32_16x16x32_bf16 v[4:7], v[112:115], v[192:195], v[4:7]
	v_mfma_f32_16x16x32_bf16 v[4:7], v[116:119], v[200:203], v[4:7]
	v_mfma_f32_16x16x32_bf16 v[140:143], v[112:115], v[168:171], v[140:143]
	v_mfma_f32_16x16x32_bf16 v[140:143], v[116:119], v[172:175], v[140:143]
	v_mfma_f32_16x16x32_bf16 v[148:151], v[112:115], v[176:179], v[148:151]
	v_mfma_f32_16x16x32_bf16 v[148:151], v[116:119], v[180:183], v[148:151]
	v_mfma_f32_16x16x32_bf16 v[156:159], v[112:115], v[184:187], v[156:159]
	v_mfma_f32_16x16x32_bf16 v[156:159], v[116:119], v[188:191], v[156:159]
	s_setprio 0
	s_setprio 1
	v_mfma_f32_16x16x32_bf16 v[8:11], v[120:123], v[168:171], v[8:11]
	v_mfma_f32_16x16x32_bf16 v[12:15], v[160:163], v[168:171], v[12:15]
	v_mfma_f32_16x16x32_bf16 v[24:27], v[120:123], v[176:179], v[60:63]
	v_mfma_f32_16x16x32_bf16 v[28:31], v[160:163], v[176:179], v[100:103]
	v_mfma_f32_16x16x32_bf16 v[60:63], v[120:123], v[184:187], v[104:107]
	v_mfma_f32_16x16x32_bf16 v[100:103], v[160:163], v[184:187], v[108:111]
	v_mfma_f32_16x16x32_bf16 v[16:19], v[120:123], v[192:195], v[16:19]
	v_mfma_f32_16x16x32_bf16 v[20:23], v[160:163], v[192:195], v[20:23]
	v_mfma_f32_16x16x32_bf16 v[8:11], v[124:127], v[172:175], v[8:11]
	v_mfma_f32_16x16x32_bf16 v[12:15], v[164:167], v[172:175], v[12:15]
	v_mfma_f32_16x16x32_bf16 v[24:27], v[124:127], v[180:183], v[24:27]
	v_mfma_f32_16x16x32_bf16 v[28:31], v[164:167], v[180:183], v[28:31]
	v_mfma_f32_16x16x32_bf16 v[60:63], v[124:127], v[188:191], v[60:63]
	v_mfma_f32_16x16x32_bf16 v[100:103], v[164:167], v[188:191], v[100:103]
	v_mfma_f32_16x16x32_bf16 v[16:19], v[124:127], v[200:203], v[16:19]
	v_mfma_f32_16x16x32_bf16 v[20:23], v[164:167], v[200:203], v[20:23]
	s_setprio 0
	s_barrier
	ds_read_b128 v[104:107], v128
	ds_read_b128 v[108:111], v128 offset:1024
	ds_read_b128 v[112:115], v128 offset:2048
	ds_read_b128 v[116:119], v128 offset:3072
	ds_read_b128 v[120:123], v129
	ds_read_b128 v[124:127], v129 offset:1024
	ds_read_b128 v[160:163], v129 offset:2048
	ds_read_b128 v[164:167], v129 offset:3072
	s_add_u32 s36, s38, 0x80
	s_addc_u32 s37, s39, 0
	s_add_u32 s30, s30, 0x10180
	s_addc_u32 s31, s31, 0
	s_mov_b32 m0, s5
	ds_read_b128 v[168:171], v135
	ds_read_b128 v[172:175], v135 offset:1024
	ds_read_b128 v[176:179], v135 offset:2048
	ds_read_b128 v[180:183], v135 offset:3072
	ds_read_b128 v[184:187], v135 offset:4096
	ds_read_b128 v[188:191], v135 offset:5120
	ds_read_b128 v[192:195], v135 offset:6144
	ds_read_b128 v[200:203], v135 offset:7168
	s_nop 0
	global_load_lds_dwordx4 v133, s[30:31]
	s_mov_b32 m0, s11
	s_nop 0
	global_load_lds_dwordx4 v131, s[30:31]
	s_waitcnt vmcnt(8)
	s_waitcnt lgkmcnt(0)
	s_barrier
	s_setprio 1
	s_waitcnt lgkmcnt(0)
	v_mfma_f32_16x16x32_bf16 v[64:67], v[104:107], v[168:171], v[64:67]
	v_mfma_f32_16x16x32_bf16 v[64:67], v[108:111], v[172:175], v[64:67]
	v_mfma_f32_16x16x32_bf16 v[72:75], v[104:107], v[176:179], v[72:75]
	v_mfma_f32_16x16x32_bf16 v[72:75], v[108:111], v[180:183], v[72:75]
	v_mfma_f32_16x16x32_bf16 v[80:83], v[104:107], v[184:187], v[80:83]
	v_mfma_f32_16x16x32_bf16 v[80:83], v[108:111], v[188:191], v[80:83]
	v_mfma_f32_16x16x32_bf16 v[88:91], v[104:107], v[192:195], v[88:91]
	v_mfma_f32_16x16x32_bf16 v[88:91], v[108:111], v[200:203], v[88:91]
	v_mfma_f32_16x16x32_bf16 v[68:71], v[112:115], v[168:171], v[68:71]
	v_mfma_f32_16x16x32_bf16 v[68:71], v[116:119], v[172:175], v[68:71]
	v_mfma_f32_16x16x32_bf16 v[76:79], v[112:115], v[176:179], v[76:79]
	v_mfma_f32_16x16x32_bf16 v[76:79], v[116:119], v[180:183], v[76:79]
	v_mfma_f32_16x16x32_bf16 v[84:87], v[112:115], v[184:187], v[84:87]
	v_mfma_f32_16x16x32_bf16 v[84:87], v[116:119], v[188:191], v[84:87]
	v_mfma_f32_16x16x32_bf16 v[92:95], v[112:115], v[192:195], v[92:95]
	v_mfma_f32_16x16x32_bf16 v[92:95], v[116:119], v[200:203], v[92:95]
	s_setprio 0
	s_setprio 1
	v_mfma_f32_16x16x32_bf16 v[32:35], v[160:163], v[168:171], v[32:35]
	v_mfma_f32_16x16x32_bf16 v[96:99], v[120:123], v[168:171], v[96:99]
	v_mfma_f32_16x16x32_bf16 v[168:171], v[164:167], v[172:175], v[32:35]
	v_mfma_f32_16x16x32_bf16 v[32:35], v[120:123], v[176:179], v[36:39]
	v_mfma_f32_16x16x32_bf16 v[36:39], v[124:127], v[180:183], v[32:35]
	v_mfma_f32_16x16x32_bf16 v[32:35], v[160:163], v[176:179], v[40:43]
	v_mfma_f32_16x16x32_bf16 v[204:207], v[124:127], v[172:175], v[96:99]
	v_mfma_f32_16x16x32_bf16 v[172:175], v[164:167], v[180:183], v[32:35]
	v_mfma_f32_16x16x32_bf16 v[32:35], v[120:123], v[184:187], v[44:47]
	v_mfma_f32_16x16x32_bf16 v[44:47], v[124:127], v[188:191], v[32:35]
	v_mfma_f32_16x16x32_bf16 v[32:35], v[160:163], v[184:187], v[48:51]
	v_mfma_f32_16x16x32_bf16 v[48:51], v[164:167], v[188:191], v[32:35]
	v_mfma_f32_16x16x32_bf16 v[32:35], v[120:123], v[192:195], v[52:55]
	v_mfma_f32_16x16x32_bf16 v[52:55], v[124:127], v[200:203], v[32:35]
	v_mfma_f32_16x16x32_bf16 v[32:35], v[160:163], v[192:195], v[56:59]
	v_mfma_f32_16x16x32_bf16 v[56:59], v[164:167], v[200:203], v[32:35]
	s_setprio 0
	s_barrier
	s_mov_b32 m0, s70
	s_mov_b64 s[30:31], s[34:35]
	s_nop 2
	ds_read_b128 v[32:35], v135 offset:16384
	ds_read_b128 v[40:43], v135 offset:17408
	ds_read_b128 v[96:99], v135 offset:18432
	ds_read_b128 v[176:179], v135 offset:19456
	ds_read_b128 v[180:183], v135 offset:20480
	ds_read_b128 v[184:187], v135 offset:21504
	ds_read_b128 v[188:191], v135 offset:22528
	ds_read_b128 v[192:195], v135 offset:23552
	s_nop 0
	global_load_lds_dwordx4 v132, s[30:31]
	s_mov_b32 m0, s4
	s_add_u32 s4, s34, 0x80000
	s_addc_u32 s5, s35, 0
	global_load_lds_dwordx4 v130, s[30:31]
	s_mov_b32 m0, s13
	s_nop 0
	global_load_lds_dwordx4 v132, s[4:5]
	s_mov_b32 m0, s15
	s_nop 0
	global_load_lds_dwordx4 v130, s[4:5]
	s_mov_b64 s[4:5], s[38:39]
	s_mov_b32 m0, s25
	s_nop 0
	global_load_lds_dwordx4 v133, s[4:5]
	s_mov_b32 m0, s27
	s_nop 0
	global_load_lds_dwordx4 v131, s[4:5]
	s_waitcnt vmcnt(8)
	s_waitcnt lgkmcnt(0)
	s_barrier
	s_setprio 1
	s_waitcnt lgkmcnt(0)
	v_mfma_f32_16x16x32_bf16 v[0:3], v[104:107], v[188:191], v[0:3]
	v_mfma_f32_16x16x32_bf16 v[0:3], v[108:111], v[192:195], v[0:3]
	v_mfma_f32_16x16x32_bf16 v[136:139], v[104:107], v[32:35], v[136:139]
	v_mfma_f32_16x16x32_bf16 v[136:139], v[108:111], v[40:43], v[136:139]
	v_mfma_f32_16x16x32_bf16 v[144:147], v[104:107], v[96:99], v[144:147]
	v_mfma_f32_16x16x32_bf16 v[144:147], v[108:111], v[176:179], v[144:147]
	v_mfma_f32_16x16x32_bf16 v[152:155], v[104:107], v[180:183], v[152:155]
	v_mfma_f32_16x16x32_bf16 v[152:155], v[108:111], v[184:187], v[152:155]
	v_mfma_f32_16x16x32_bf16 v[4:7], v[112:115], v[188:191], v[4:7]
	v_mfma_f32_16x16x32_bf16 v[4:7], v[116:119], v[192:195], v[4:7]
	v_mfma_f32_16x16x32_bf16 v[140:143], v[112:115], v[32:35], v[140:143]
	v_mfma_f32_16x16x32_bf16 v[140:143], v[116:119], v[40:43], v[140:143]
	v_mfma_f32_16x16x32_bf16 v[148:151], v[112:115], v[96:99], v[148:151]
	v_mfma_f32_16x16x32_bf16 v[148:151], v[116:119], v[176:179], v[148:151]
	v_mfma_f32_16x16x32_bf16 v[156:159], v[112:115], v[180:183], v[156:159]
	v_mfma_f32_16x16x32_bf16 v[156:159], v[116:119], v[184:187], v[156:159]
	s_setprio 0
	s_setprio 1
	v_mfma_f32_16x16x32_bf16 v[12:15], v[160:163], v[32:35], v[12:15]
	v_mfma_f32_16x16x32_bf16 v[200:203], v[164:167], v[40:43], v[12:15]
	v_mfma_f32_16x16x32_bf16 v[12:15], v[120:123], v[96:99], v[24:27]
	v_mfma_f32_16x16x32_bf16 v[24:27], v[124:127], v[176:179], v[12:15]
	v_mfma_f32_16x16x32_bf16 v[12:15], v[160:163], v[96:99], v[28:31]
	v_mfma_f32_16x16x32_bf16 v[176:179], v[164:167], v[176:179], v[12:15]
	v_mfma_f32_16x16x32_bf16 v[12:15], v[120:123], v[180:183], v[60:63]
	v_mfma_f32_16x16x32_bf16 v[208:211], v[124:127], v[184:187], v[12:15]
	v_mfma_f32_16x16x32_bf16 v[12:15], v[160:163], v[180:183], v[100:103]
	v_mfma_f32_16x16x32_bf16 v[8:11], v[120:123], v[32:35], v[8:11]
	v_mfma_f32_16x16x32_bf16 v[180:183], v[164:167], v[184:187], v[12:15]
	v_mfma_f32_16x16x32_bf16 v[12:15], v[120:123], v[188:191], v[16:19]
	v_mfma_f32_16x16x32_bf16 v[8:11], v[124:127], v[40:43], v[8:11]
	v_mfma_f32_16x16x32_bf16 v[184:187], v[124:127], v[192:195], v[12:15]
	v_mfma_f32_16x16x32_bf16 v[12:15], v[160:163], v[188:191], v[20:23]
	v_mfma_f32_16x16x32_bf16 v[160:163], v[164:167], v[192:195], v[12:15]
	s_setprio 0
	s_barrier
	s_nop 4
	ds_read_b128 v[12:15], v196
	ds_read_b128 v[16:19], v196 offset:1024
	ds_read_b128 v[164:167], v196 offset:2048
	ds_read_b128 v[188:191], v196 offset:3072
	ds_read_b128 v[192:195], v198
	ds_read_b128 v[220:223], v198 offset:1024
	ds_read_b128 v[224:227], v198 offset:2048
	ds_read_b128 v[228:231], v198 offset:3072
	s_add_u32 s4, s38, 0x10000
	s_addc_u32 s5, s39, 0
	s_mov_b32 m0, s29
	ds_read_b128 v[20:23], v135 offset:32768
	ds_read_b128 v[28:31], v135 offset:33792
	ds_read_b128 v[60:63], v135 offset:34816
	ds_read_b128 v[100:103], v135 offset:35840
	ds_read_b128 v[232:235], v135 offset:36864
	ds_read_b128 v[236:239], v135 offset:37888
	ds_read_b128 v[240:243], v135 offset:38912
	ds_read_b128 v[244:247], v135 offset:39936
	s_nop 0
	global_load_lds_dwordx4 v133, s[4:5]
	s_mov_b32 m0, s47
	s_nop 0
	global_load_lds_dwordx4 v131, s[4:5]
	s_waitcnt vmcnt(8)
	s_waitcnt lgkmcnt(0)
	s_barrier
	s_setprio 1
	s_waitcnt lgkmcnt(0)
	v_mfma_f32_16x16x32_bf16 v[32:35], v[12:15], v[20:23], v[64:67]
	v_mfma_f32_16x16x32_bf16 v[120:123], v[16:19], v[28:31], v[32:35]
	v_mfma_f32_16x16x32_bf16 v[32:35], v[164:167], v[20:23], v[68:71]
	v_mfma_f32_16x16x32_bf16 v[112:115], v[188:191], v[28:31], v[32:35]
	v_mfma_f32_16x16x32_bf16 v[32:35], v[12:15], v[60:63], v[72:75]
	v_mfma_f32_16x16x32_bf16 v[104:107], v[16:19], v[100:103], v[32:35]
	v_mfma_f32_16x16x32_bf16 v[32:35], v[164:167], v[60:63], v[76:79]
	v_mfma_f32_16x16x32_bf16 v[96:99], v[188:191], v[100:103], v[32:35]
	v_mfma_f32_16x16x32_bf16 v[32:35], v[12:15], v[232:235], v[80:83]
	v_mfma_f32_16x16x32_bf16 v[72:75], v[16:19], v[236:239], v[32:35]
	v_mfma_f32_16x16x32_bf16 v[32:35], v[164:167], v[232:235], v[84:87]
	v_mfma_f32_16x16x32_bf16 v[64:67], v[188:191], v[236:239], v[32:35]
	v_mfma_f32_16x16x32_bf16 v[32:35], v[12:15], v[240:243], v[88:91]
	v_mfma_f32_16x16x32_bf16 v[40:43], v[16:19], v[244:247], v[32:35]
	v_mfma_f32_16x16x32_bf16 v[32:35], v[164:167], v[240:243], v[92:95]
	v_mfma_f32_16x16x32_bf16 v[32:35], v[188:191], v[244:247], v[32:35]
	s_setprio 0
	s_setprio 1
	v_mfma_f32_16x16x32_bf16 v[68:71], v[192:195], v[20:23], v[204:207]
	v_mfma_f32_16x16x32_bf16 v[20:23], v[224:227], v[20:23], v[168:171]
	v_mfma_f32_16x16x32_bf16 v[116:119], v[228:231], v[28:31], v[20:23]
	v_mfma_f32_16x16x32_bf16 v[20:23], v[192:195], v[60:63], v[36:39]
	v_mfma_f32_16x16x32_bf16 v[108:111], v[220:223], v[100:103], v[20:23]
	v_mfma_f32_16x16x32_bf16 v[20:23], v[224:227], v[60:63], v[172:175]
	v_mfma_f32_16x16x32_bf16 v[100:103], v[228:231], v[100:103], v[20:23]
	v_mfma_f32_16x16x32_bf16 v[20:23], v[192:195], v[232:235], v[44:47]
	v_mfma_f32_16x16x32_bf16 v[76:79], v[220:223], v[236:239], v[20:23]
	v_mfma_f32_16x16x32_bf16 v[20:23], v[224:227], v[232:235], v[48:51]
	v_mfma_f32_16x16x32_bf16 v[124:127], v[220:223], v[28:31], v[68:71]
	v_mfma_f32_16x16x32_bf16 v[68:71], v[228:231], v[236:239], v[20:23]
	v_mfma_f32_16x16x32_bf16 v[20:23], v[192:195], v[240:243], v[52:55]
	v_mfma_f32_16x16x32_bf16 v[44:47], v[220:223], v[244:247], v[20:23]
	v_mfma_f32_16x16x32_bf16 v[20:23], v[224:227], v[240:243], v[56:59]
	v_mfma_f32_16x16x32_bf16 v[36:39], v[228:231], v[244:247], v[20:23]
	s_setprio 0
	s_barrier
	s_add_u32 s4, s34, 0x80
	s_mov_b32 m0, s71
	s_addc_u32 s5, s35, 0
	ds_read_b128 v[48:51], v135 offset:49152
	ds_read_b128 v[56:59], v135 offset:50176
	ds_read_b128 v[168:171], v135 offset:51200
	ds_read_b128 v[172:175], v135 offset:52224
	ds_read_b128 v[204:207], v135 offset:53248
	ds_read_b128 v[232:235], v135 offset:54272
	ds_read_b128 v[236:239], v135 offset:55296
	ds_read_b128 v[240:243], v135 offset:56320
	s_nop 0
	global_load_lds_dwordx4 v132, s[4:5]
	s_mov_b32 m0, s56
	s_nop 0
	global_load_lds_dwordx4 v130, s[4:5]
	s_add_u32 s4, s34, 0x80080
	s_addc_u32 s5, s35, 0
	s_mov_b32 m0, s57
	s_nop 0
	global_load_lds_dwordx4 v132, s[4:5]
	s_mov_b32 m0, s69
	s_nop 0
	global_load_lds_dwordx4 v130, s[4:5]
	s_mov_b32 m0, s48
	s_nop 0
	global_load_lds_dwordx4 v133, s[36:37]
	s_mov_b32 m0, s49
	s_nop 0
	global_load_lds_dwordx4 v131, s[36:37]
	s_waitcnt vmcnt(8)
	s_waitcnt lgkmcnt(0)
	s_barrier
	s_setprio 1
	s_waitcnt lgkmcnt(0)
	v_mfma_f32_16x16x32_bf16 v[20:23], v[12:15], v[48:51], v[136:139]
	v_mfma_f32_16x16x32_bf16 v[92:95], v[16:19], v[56:59], v[20:23]
	v_mfma_f32_16x16x32_bf16 v[20:23], v[164:167], v[48:51], v[140:143]
	v_mfma_f32_16x16x32_bf16 v[84:87], v[188:191], v[56:59], v[20:23]
	v_mfma_f32_16x16x32_bf16 v[20:23], v[12:15], v[168:171], v[144:147]
	v_mfma_f32_16x16x32_bf16 v[60:63], v[16:19], v[172:175], v[20:23]
	v_mfma_f32_16x16x32_bf16 v[20:23], v[164:167], v[168:171], v[148:151]
	v_mfma_f32_16x16x32_bf16 v[52:55], v[188:191], v[172:175], v[20:23]
	v_mfma_f32_16x16x32_bf16 v[20:23], v[12:15], v[204:207], v[152:155]
	v_mfma_f32_16x16x32_bf16 v[0:3], v[12:15], v[236:239], v[0:3]
	v_mfma_f32_16x16x32_bf16 v[28:31], v[16:19], v[232:235], v[20:23]
	v_mfma_f32_16x16x32_bf16 v[20:23], v[164:167], v[204:207], v[156:159]
	v_mfma_f32_16x16x32_bf16 v[12:15], v[16:19], v[240:243], v[0:3]
	v_mfma_f32_16x16x32_bf16 v[0:3], v[164:167], v[236:239], v[4:7]
	v_mfma_f32_16x16x32_bf16 v[20:23], v[188:191], v[232:235], v[20:23]
	v_mfma_f32_16x16x32_bf16 v[4:7], v[188:191], v[240:243], v[0:3]
	s_setprio 0
	s_setprio 1
	v_mfma_f32_16x16x32_bf16 v[0:3], v[192:195], v[48:51], v[8:11]
	v_mfma_f32_16x16x32_bf16 v[88:91], v[220:223], v[56:59], v[0:3]
	v_mfma_f32_16x16x32_bf16 v[0:3], v[224:227], v[48:51], v[200:203]
	v_mfma_f32_16x16x32_bf16 v[80:83], v[228:231], v[56:59], v[0:3]
	v_mfma_f32_16x16x32_bf16 v[0:3], v[192:195], v[168:171], v[24:27]
	v_mfma_f32_16x16x32_bf16 v[56:59], v[220:223], v[172:175], v[0:3]
	v_mfma_f32_16x16x32_bf16 v[0:3], v[224:227], v[168:171], v[176:179]
	v_mfma_f32_16x16x32_bf16 v[48:51], v[228:231], v[172:175], v[0:3]
	v_mfma_f32_16x16x32_bf16 v[0:3], v[192:195], v[204:207], v[208:211]
	v_mfma_f32_16x16x32_bf16 v[24:27], v[220:223], v[232:235], v[0:3]
	v_mfma_f32_16x16x32_bf16 v[0:3], v[224:227], v[204:207], v[180:183]
	v_mfma_f32_16x16x32_bf16 v[16:19], v[228:231], v[232:235], v[0:3]
	v_mfma_f32_16x16x32_bf16 v[0:3], v[192:195], v[236:239], v[184:187]
	v_mfma_f32_16x16x32_bf16 v[8:11], v[220:223], v[240:243], v[0:3]
	v_mfma_f32_16x16x32_bf16 v[0:3], v[224:227], v[236:239], v[160:163]
	v_mfma_f32_16x16x32_bf16 v[0:3], v[228:231], v[240:243], v[0:3]
	s_setprio 0
	s_barrier
	s_andn2_b64 vcc, exec, s[60:61]
	s_cbranch_vccnz .LBB0_315
	s_barrier

.LBB0_380:
	s_cmp_eq_u32 s15, 28
	s_cselect_b32 s36, s20, s4
	s_cselect_b32 s37, s21, s5
	s_cselect_b32 s34, s26, s11
	s_cselect_b32 s35, s27, s13
	s_add_u32 s30, s36, 0x80
	s_addc_u32 s31, s37, 0
	s_add_i32 s17, 0, 0x10000
	v_add_u32_e32 v128, s17, v134
	s_add_i32 s69, 0, 0x14000
	ds_read_b128 v[136:139], v128
	ds_read_b128 v[140:143], v128 offset:1024
	ds_read_b128 v[144:147], v128 offset:2048
	ds_read_b128 v[148:151], v128 offset:3072
	v_add_u32_e32 v128, s69, v134
	ds_read_b128 v[152:155], v128
	ds_read_b128 v[156:159], v128 offset:1024
	ds_read_b128 v[160:163], v128 offset:2048
	ds_read_b128 v[164:167], v128 offset:3072
	s_mov_b64 s[70:71], s[28:29]
	s_add_i32 m0, s23, 0xc000
	ds_read_b128 v[168:171], v135
	ds_read_b128 v[172:175], v135 offset:1024
	ds_read_b128 v[176:179], v135 offset:2048
	ds_read_b128 v[180:183], v135 offset:3072
	ds_read_b128 v[184:187], v135 offset:4096
	ds_read_b128 v[188:191], v135 offset:5120
	ds_read_b128 v[192:195], v135 offset:6144
	ds_read_b128 v[200:203], v135 offset:7168
	s_nop 0
	global_load_lds_dwordx4 v133, s[70:71]
	s_add_i32 m0, s23, 0xe000
	s_nop 0
	global_load_lds_dwordx4 v131, s[70:71]
	s_waitcnt vmcnt(8)
	s_waitcnt lgkmcnt(0)
	s_barrier
	s_setprio 1
	s_waitcnt lgkmcnt(0)
	v_mfma_f32_16x16x32_bf16 v[124:127], v[136:139], v[168:171], v[124:127]
	v_mfma_f32_16x16x32_bf16 v[124:127], v[140:143], v[172:175], v[124:127]
	v_mfma_f32_16x16x32_bf16 v[116:119], v[136:139], v[176:179], v[116:119]
	v_mfma_f32_16x16x32_bf16 v[116:119], v[140:143], v[180:183], v[116:119]
	v_mfma_f32_16x16x32_bf16 v[100:103], v[136:139], v[184:187], v[100:103]
	v_mfma_f32_16x16x32_bf16 v[100:103], v[140:143], v[188:191], v[100:103]
	v_mfma_f32_16x16x32_bf16 v[84:87], v[136:139], v[192:195], v[84:87]
	v_mfma_f32_16x16x32_bf16 v[84:87], v[140:143], v[200:203], v[84:87]
	v_mfma_f32_16x16x32_bf16 v[120:123], v[144:147], v[168:171], v[120:123]
	v_mfma_f32_16x16x32_bf16 v[120:123], v[148:151], v[172:175], v[120:123]
	v_mfma_f32_16x16x32_bf16 v[108:111], v[144:147], v[176:179], v[108:111]
	v_mfma_f32_16x16x32_bf16 v[108:111], v[148:151], v[180:183], v[108:111]
	v_mfma_f32_16x16x32_bf16 v[92:95], v[144:147], v[184:187], v[92:95]
	v_mfma_f32_16x16x32_bf16 v[92:95], v[148:151], v[188:191], v[92:95]
	v_mfma_f32_16x16x32_bf16 v[76:79], v[144:147], v[192:195], v[76:79]
	v_mfma_f32_16x16x32_bf16 v[76:79], v[148:151], v[200:203], v[76:79]
	s_setprio 0
	s_setprio 1
	v_mfma_f32_16x16x32_bf16 v[112:115], v[152:155], v[168:171], v[112:115]
	v_mfma_f32_16x16x32_bf16 v[112:115], v[156:159], v[172:175], v[112:115]
	v_mfma_f32_16x16x32_bf16 v[96:99], v[152:155], v[176:179], v[96:99]
	v_mfma_f32_16x16x32_bf16 v[96:99], v[156:159], v[180:183], v[96:99]
	v_mfma_f32_16x16x32_bf16 v[80:83], v[152:155], v[184:187], v[80:83]
	v_mfma_f32_16x16x32_bf16 v[80:83], v[156:159], v[188:191], v[80:83]
	v_mfma_f32_16x16x32_bf16 v[68:71], v[152:155], v[192:195], v[68:71]
	v_mfma_f32_16x16x32_bf16 v[68:71], v[156:159], v[200:203], v[68:71]
	v_mfma_f32_16x16x32_bf16 v[104:107], v[160:163], v[168:171], v[104:107]
	v_mfma_f32_16x16x32_bf16 v[104:107], v[164:167], v[172:175], v[104:107]
	v_mfma_f32_16x16x32_bf16 v[88:91], v[160:163], v[176:179], v[88:91]
	v_mfma_f32_16x16x32_bf16 v[88:91], v[164:167], v[180:183], v[88:91]
	v_mfma_f32_16x16x32_bf16 v[72:75], v[160:163], v[184:187], v[72:75]
	v_mfma_f32_16x16x32_bf16 v[72:75], v[164:167], v[188:191], v[72:75]
	v_mfma_f32_16x16x32_bf16 v[64:67], v[160:163], v[192:195], v[64:67]
	v_mfma_f32_16x16x32_bf16 v[64:67], v[164:167], v[200:203], v[64:67]
	s_setprio 0
	s_barrier
	s_add_i32 s17, s17, s97
	s_mov_b64 s[70:71], s[34:35]
	s_mov_b32 m0, s17
	ds_read_b128 v[168:171], v135 offset:16384
	ds_read_b128 v[172:175], v135 offset:17408
	ds_read_b128 v[176:179], v135 offset:18432
	ds_read_b128 v[180:183], v135 offset:19456
	ds_read_b128 v[184:187], v135 offset:20480
	ds_read_b128 v[188:191], v135 offset:21504
	ds_read_b128 v[192:195], v135 offset:22528
	ds_read_b128 v[200:203], v135 offset:23552
	s_nop 0
	global_load_lds_dwordx4 v132, s[70:71]
	s_add_i32 m0, s17, 0x2000
	s_nop 0
	global_load_lds_dwordx4 v130, s[70:71]
	s_add_u32 s70, s34, 0x200000
	s_addc_u32 s71, s35, 0
	s_add_i32 s17, s69, s97
	s_mov_b32 m0, s17
	s_nop 0
	global_load_lds_dwordx4 v132, s[70:71]
	s_add_i32 m0, s17, 0x2000
	s_nop 0
	global_load_lds_dwordx4 v130, s[70:71]
	s_mov_b64 s[70:71], s[36:37]
	s_mov_b32 m0, s23
	s_nop 0
	global_load_lds_dwordx4 v133, s[70:71]
	s_mov_b32 m0, s25
	s_nop 0
	global_load_lds_dwordx4 v131, s[70:71]
	s_waitcnt vmcnt(8)
	s_waitcnt lgkmcnt(0)
	s_barrier
	s_setprio 1
	s_waitcnt lgkmcnt(0)
	v_mfma_f32_16x16x32_bf16 v[60:63], v[136:139], v[168:171], v[60:63]
	v_mfma_f32_16x16x32_bf16 v[60:63], v[140:143], v[172:175], v[60:63]
	v_mfma_f32_16x16x32_bf16 v[52:55], v[136:139], v[176:179], v[52:55]
	v_mfma_f32_16x16x32_bf16 v[52:55], v[140:143], v[180:183], v[52:55]
	v_mfma_f32_16x16x32_bf16 v[36:39], v[136:139], v[184:187], v[36:39]
	v_mfma_f32_16x16x32_bf16 v[36:39], v[140:143], v[188:191], v[36:39]
	v_mfma_f32_16x16x32_bf16 v[20:23], v[136:139], v[192:195], v[20:23]
	v_mfma_f32_16x16x32_bf16 v[20:23], v[140:143], v[200:203], v[20:23]
	v_mfma_f32_16x16x32_bf16 v[56:59], v[144:147], v[168:171], v[56:59]
	v_mfma_f32_16x16x32_bf16 v[56:59], v[148:151], v[172:175], v[56:59]
	v_mfma_f32_16x16x32_bf16 v[44:47], v[144:147], v[176:179], v[44:47]
	v_mfma_f32_16x16x32_bf16 v[44:47], v[148:151], v[180:183], v[44:47]
	v_mfma_f32_16x16x32_bf16 v[28:31], v[144:147], v[184:187], v[28:31]
	v_mfma_f32_16x16x32_bf16 v[28:31], v[148:151], v[188:191], v[28:31]
	v_mfma_f32_16x16x32_bf16 v[12:15], v[144:147], v[192:195], v[12:15]
	v_mfma_f32_16x16x32_bf16 v[12:15], v[148:151], v[200:203], v[12:15]
	s_setprio 0
	s_setprio 1
	v_mfma_f32_16x16x32_bf16 v[48:51], v[152:155], v[168:171], v[48:51]
	v_mfma_f32_16x16x32_bf16 v[48:51], v[156:159], v[172:175], v[48:51]
	v_mfma_f32_16x16x32_bf16 v[32:35], v[152:155], v[176:179], v[32:35]
	v_mfma_f32_16x16x32_bf16 v[32:35], v[156:159], v[180:183], v[32:35]
	v_mfma_f32_16x16x32_bf16 v[16:19], v[152:155], v[184:187], v[16:19]
	v_mfma_f32_16x16x32_bf16 v[16:19], v[156:159], v[188:191], v[16:19]
	v_mfma_f32_16x16x32_bf16 v[4:7], v[152:155], v[192:195], v[4:7]
	v_mfma_f32_16x16x32_bf16 v[4:7], v[156:159], v[200:203], v[4:7]
	v_mfma_f32_16x16x32_bf16 v[40:43], v[160:163], v[168:171], v[40:43]
	v_mfma_f32_16x16x32_bf16 v[40:43], v[164:167], v[172:175], v[40:43]
	v_mfma_f32_16x16x32_bf16 v[24:27], v[160:163], v[176:179], v[24:27]
	v_mfma_f32_16x16x32_bf16 v[24:27], v[164:167], v[180:183], v[24:27]
	v_mfma_f32_16x16x32_bf16 v[8:11], v[160:163], v[184:187], v[8:11]
	v_mfma_f32_16x16x32_bf16 v[8:11], v[164:167], v[188:191], v[8:11]
	v_mfma_f32_16x16x32_bf16 v[0:3], v[160:163], v[192:195], v[0:3]
	v_mfma_f32_16x16x32_bf16 v[0:3], v[164:167], v[200:203], v[0:3]
	s_setprio 0
	s_barrier
	s_add_i32 s17, 0, 0x18000
	v_add_u32_e32 v128, s17, v134
	s_add_i32 s69, 0, 0x1c000
	ds_read_b128 v[136:139], v128
	ds_read_b128 v[140:143], v128 offset:1024
	ds_read_b128 v[144:147], v128 offset:2048
	ds_read_b128 v[148:151], v128 offset:3072
	v_add_u32_e32 v128, s69, v134
	ds_read_b128 v[152:155], v128
	ds_read_b128 v[156:159], v128 offset:1024
	ds_read_b128 v[160:163], v128 offset:2048
	ds_read_b128 v[164:167], v128 offset:3072
	s_add_u32 s36, s36, 0x80000
	s_addc_u32 s37, s37, 0
	s_mov_b32 m0, s46
	ds_read_b128 v[168:171], v135 offset:32768
	ds_read_b128 v[172:175], v135 offset:33792
	ds_read_b128 v[176:179], v135 offset:34816
	ds_read_b128 v[180:183], v135 offset:35840
	ds_read_b128 v[184:187], v135 offset:36864
	ds_read_b128 v[188:191], v135 offset:37888
	ds_read_b128 v[192:195], v135 offset:38912
	ds_read_b128 v[200:203], v135 offset:39936
	s_nop 0
	global_load_lds_dwordx4 v133, s[36:37]
	s_mov_b32 m0, s47
	s_nop 0
	global_load_lds_dwordx4 v131, s[36:37]
	s_waitcnt vmcnt(8)
	s_waitcnt lgkmcnt(0)
	s_barrier
	s_setprio 1
	s_waitcnt lgkmcnt(0)
	v_mfma_f32_16x16x32_bf16 v[124:127], v[136:139], v[168:171], v[124:127]
	v_mfma_f32_16x16x32_bf16 v[124:127], v[140:143], v[172:175], v[124:127]
	v_mfma_f32_16x16x32_bf16 v[116:119], v[136:139], v[176:179], v[116:119]
	v_mfma_f32_16x16x32_bf16 v[116:119], v[140:143], v[180:183], v[116:119]
	v_mfma_f32_16x16x32_bf16 v[100:103], v[136:139], v[184:187], v[100:103]
	v_mfma_f32_16x16x32_bf16 v[100:103], v[140:143], v[188:191], v[100:103]
	v_mfma_f32_16x16x32_bf16 v[84:87], v[136:139], v[192:195], v[84:87]
	v_mfma_f32_16x16x32_bf16 v[84:87], v[140:143], v[200:203], v[84:87]
	v_mfma_f32_16x16x32_bf16 v[120:123], v[144:147], v[168:171], v[120:123]
	v_mfma_f32_16x16x32_bf16 v[120:123], v[148:151], v[172:175], v[120:123]
	v_mfma_f32_16x16x32_bf16 v[108:111], v[144:147], v[176:179], v[108:111]
	v_mfma_f32_16x16x32_bf16 v[108:111], v[148:151], v[180:183], v[108:111]
	v_mfma_f32_16x16x32_bf16 v[92:95], v[144:147], v[184:187], v[92:95]
	v_mfma_f32_16x16x32_bf16 v[92:95], v[148:151], v[188:191], v[92:95]
	v_mfma_f32_16x16x32_bf16 v[76:79], v[144:147], v[192:195], v[76:79]
	v_mfma_f32_16x16x32_bf16 v[76:79], v[148:151], v[200:203], v[76:79]
	s_setprio 0
	s_setprio 1
	v_mfma_f32_16x16x32_bf16 v[112:115], v[152:155], v[168:171], v[112:115]
	v_mfma_f32_16x16x32_bf16 v[112:115], v[156:159], v[172:175], v[112:115]
	v_mfma_f32_16x16x32_bf16 v[96:99], v[152:155], v[176:179], v[96:99]
	v_mfma_f32_16x16x32_bf16 v[96:99], v[156:159], v[180:183], v[96:99]
	v_mfma_f32_16x16x32_bf16 v[80:83], v[152:155], v[184:187], v[80:83]
	v_mfma_f32_16x16x32_bf16 v[80:83], v[156:159], v[188:191], v[80:83]
	v_mfma_f32_16x16x32_bf16 v[68:71], v[152:155], v[192:195], v[68:71]
	v_mfma_f32_16x16x32_bf16 v[68:71], v[156:159], v[200:203], v[68:71]
	v_mfma_f32_16x16x32_bf16 v[104:107], v[160:163], v[168:171], v[104:107]
	v_mfma_f32_16x16x32_bf16 v[104:107], v[164:167], v[172:175], v[104:107]
	v_mfma_f32_16x16x32_bf16 v[88:91], v[160:163], v[176:179], v[88:91]
	v_mfma_f32_16x16x32_bf16 v[88:91], v[164:167], v[180:183], v[88:91]
	v_mfma_f32_16x16x32_bf16 v[72:75], v[160:163], v[184:187], v[72:75]
	v_mfma_f32_16x16x32_bf16 v[72:75], v[164:167], v[188:191], v[72:75]
	v_mfma_f32_16x16x32_bf16 v[64:67], v[160:163], v[192:195], v[64:67]
	v_mfma_f32_16x16x32_bf16 v[64:67], v[164:167], v[200:203], v[64:67]
	s_setprio 0
	s_barrier
	s_add_u32 s36, s34, 0x80
	s_addc_u32 s37, s35, 0
	s_add_i32 s17, s17, s97
	s_mov_b32 m0, s17
	ds_read_b128 v[168:171], v135 offset:49152
	ds_read_b128 v[172:175], v135 offset:50176
	ds_read_b128 v[176:179], v135 offset:51200
	ds_read_b128 v[180:183], v135 offset:52224
	ds_read_b128 v[184:187], v135 offset:53248
	ds_read_b128 v[188:191], v135 offset:54272
	ds_read_b128 v[192:195], v135 offset:55296
	ds_read_b128 v[200:203], v135 offset:56320
	s_nop 0
	global_load_lds_dwordx4 v132, s[36:37]
	s_add_i32 m0, s17, 0x2000
	s_add_u32 s34, s34, 0x200080
	s_addc_u32 s35, s35, 0
	s_add_i32 s17, s69, s97
	s_nop 0
	global_load_lds_dwordx4 v130, s[36:37]
	s_mov_b32 m0, s17
	s_nop 0
	global_load_lds_dwordx4 v132, s[34:35]
	s_add_i32 m0, s17, 0x2000
	s_nop 0
	global_load_lds_dwordx4 v130, s[34:35]
	s_mov_b32 m0, s56
	s_nop 0
	global_load_lds_dwordx4 v133, s[30:31]
	s_mov_b32 m0, s57
	s_nop 0
	global_load_lds_dwordx4 v131, s[30:31]
	s_waitcnt vmcnt(8)
	s_waitcnt lgkmcnt(0)
	s_barrier
	s_setprio 1
	s_waitcnt lgkmcnt(0)
	v_mfma_f32_16x16x32_bf16 v[60:63], v[136:139], v[168:171], v[60:63]
	v_mfma_f32_16x16x32_bf16 v[60:63], v[140:143], v[172:175], v[60:63]
	v_mfma_f32_16x16x32_bf16 v[52:55], v[136:139], v[176:179], v[52:55]
	v_mfma_f32_16x16x32_bf16 v[52:55], v[140:143], v[180:183], v[52:55]
	v_mfma_f32_16x16x32_bf16 v[36:39], v[136:139], v[184:187], v[36:39]
	v_mfma_f32_16x16x32_bf16 v[36:39], v[140:143], v[188:191], v[36:39]
	v_mfma_f32_16x16x32_bf16 v[20:23], v[136:139], v[192:195], v[20:23]
	v_mfma_f32_16x16x32_bf16 v[20:23], v[140:143], v[200:203], v[20:23]
	v_mfma_f32_16x16x32_bf16 v[56:59], v[144:147], v[168:171], v[56:59]
	v_mfma_f32_16x16x32_bf16 v[56:59], v[148:151], v[172:175], v[56:59]
	v_mfma_f32_16x16x32_bf16 v[44:47], v[144:147], v[176:179], v[44:47]
	v_mfma_f32_16x16x32_bf16 v[44:47], v[148:151], v[180:183], v[44:47]
	v_mfma_f32_16x16x32_bf16 v[28:31], v[144:147], v[184:187], v[28:31]
	v_mfma_f32_16x16x32_bf16 v[28:31], v[148:151], v[188:191], v[28:31]
	v_mfma_f32_16x16x32_bf16 v[12:15], v[144:147], v[192:195], v[12:15]
	v_mfma_f32_16x16x32_bf16 v[12:15], v[148:151], v[200:203], v[12:15]
	s_setprio 0
	s_setprio 1
	v_mfma_f32_16x16x32_bf16 v[48:51], v[152:155], v[168:171], v[48:51]
	v_mfma_f32_16x16x32_bf16 v[48:51], v[156:159], v[172:175], v[48:51]
	v_mfma_f32_16x16x32_bf16 v[32:35], v[152:155], v[176:179], v[32:35]
	v_mfma_f32_16x16x32_bf16 v[32:35], v[156:159], v[180:183], v[32:35]
	v_mfma_f32_16x16x32_bf16 v[16:19], v[152:155], v[184:187], v[16:19]
	v_mfma_f32_16x16x32_bf16 v[16:19], v[156:159], v[188:191], v[16:19]
	v_mfma_f32_16x16x32_bf16 v[4:7], v[152:155], v[192:195], v[4:7]
	v_mfma_f32_16x16x32_bf16 v[4:7], v[156:159], v[200:203], v[4:7]
	v_mfma_f32_16x16x32_bf16 v[40:43], v[160:163], v[168:171], v[40:43]
	v_mfma_f32_16x16x32_bf16 v[40:43], v[164:167], v[172:175], v[40:43]
	v_mfma_f32_16x16x32_bf16 v[24:27], v[160:163], v[176:179], v[24:27]
	v_mfma_f32_16x16x32_bf16 v[24:27], v[164:167], v[180:183], v[24:27]
	v_mfma_f32_16x16x32_bf16 v[8:11], v[160:163], v[184:187], v[8:11]
	v_mfma_f32_16x16x32_bf16 v[8:11], v[164:167], v[188:191], v[8:11]
	v_mfma_f32_16x16x32_bf16 v[0:3], v[160:163], v[192:195], v[0:3]
	v_mfma_f32_16x16x32_bf16 v[0:3], v[164:167], v[200:203], v[0:3]
	s_setprio 0
	s_barrier
	s_add_i32 s15, s15, 2
	s_add_u32 s4, s4, 0x100
	s_addc_u32 s5, s5, 0
	s_add_u32 s11, s11, 0x100
	s_addc_u32 s13, s13, 0
	s_add_u32 s28, s28, 0x100
	s_addc_u32 s29, s29, 0
	s_cmp_gt_u32 s15, 29
	s_cbranch_scc0 .LBB0_380
	s_and_b64 vcc, exec, s[60:61]
	s_cbranch_vccz .LBB0_383
	s_barrier

.LBB0_397:
	s_cmp_eq_u32 s69, 4
	s_cselect_b32 s34, s15, s49
	s_cselect_b32 s35, s5, s56
	s_cselect_b32 s30, s48, s57
	s_cselect_b32 s31, s13, s65
	s_add_u32 s28, s34, 0x80
	s_addc_u32 s29, s35, 0
	s_add_i32 s72, 0, 0x10000
	v_add_u32_e32 v128, s72, v134
	s_add_i32 s74, 0, 0x14000
	ds_read_b128 v[136:139], v128
	ds_read_b128 v[140:143], v128 offset:1024
	ds_read_b128 v[144:147], v128 offset:2048
	ds_read_b128 v[148:151], v128 offset:3072
	v_add_u32_e32 v128, s74, v134
	ds_read_b128 v[152:155], v128
	ds_read_b128 v[156:159], v128 offset:1024
	ds_read_b128 v[160:163], v128 offset:2048
	ds_read_b128 v[164:167], v128 offset:3072
	s_mov_b64 s[70:71], s[26:27]
	s_add_i32 m0, s25, 0xc000
	ds_read_b128 v[168:171], v135
	ds_read_b128 v[172:175], v135 offset:1024
	ds_read_b128 v[176:179], v135 offset:2048
	ds_read_b128 v[180:183], v135 offset:3072
	ds_read_b128 v[184:187], v135 offset:4096
	ds_read_b128 v[188:191], v135 offset:5120
	ds_read_b128 v[192:195], v135 offset:6144
	ds_read_b128 v[200:203], v135 offset:7168
	s_nop 0
	global_load_lds_dwordx4 v133, s[70:71]
	s_add_i32 m0, s25, 0xe000
	s_nop 0
	global_load_lds_dwordx4 v131, s[70:71]
	s_waitcnt vmcnt(8)
	s_waitcnt lgkmcnt(0)
	s_barrier
	s_setprio 1
	s_waitcnt lgkmcnt(0)
	v_mfma_f32_16x16x32_bf16 v[124:127], v[136:139], v[168:171], v[124:127]
	v_mfma_f32_16x16x32_bf16 v[124:127], v[140:143], v[172:175], v[124:127]
	v_mfma_f32_16x16x32_bf16 v[116:119], v[136:139], v[176:179], v[116:119]
	v_mfma_f32_16x16x32_bf16 v[116:119], v[140:143], v[180:183], v[116:119]
	v_mfma_f32_16x16x32_bf16 v[100:103], v[136:139], v[184:187], v[100:103]
	v_mfma_f32_16x16x32_bf16 v[100:103], v[140:143], v[188:191], v[100:103]
	v_mfma_f32_16x16x32_bf16 v[84:87], v[136:139], v[192:195], v[84:87]
	v_mfma_f32_16x16x32_bf16 v[84:87], v[140:143], v[200:203], v[84:87]
	v_mfma_f32_16x16x32_bf16 v[120:123], v[144:147], v[168:171], v[120:123]
	v_mfma_f32_16x16x32_bf16 v[120:123], v[148:151], v[172:175], v[120:123]
	v_mfma_f32_16x16x32_bf16 v[108:111], v[144:147], v[176:179], v[108:111]
	v_mfma_f32_16x16x32_bf16 v[108:111], v[148:151], v[180:183], v[108:111]
	v_mfma_f32_16x16x32_bf16 v[92:95], v[144:147], v[184:187], v[92:95]
	v_mfma_f32_16x16x32_bf16 v[92:95], v[148:151], v[188:191], v[92:95]
	v_mfma_f32_16x16x32_bf16 v[76:79], v[144:147], v[192:195], v[76:79]
	v_mfma_f32_16x16x32_bf16 v[76:79], v[148:151], v[200:203], v[76:79]
	s_setprio 0
	s_setprio 1
	v_mfma_f32_16x16x32_bf16 v[112:115], v[152:155], v[168:171], v[112:115]
	v_mfma_f32_16x16x32_bf16 v[112:115], v[156:159], v[172:175], v[112:115]
	v_mfma_f32_16x16x32_bf16 v[96:99], v[152:155], v[176:179], v[96:99]
	v_mfma_f32_16x16x32_bf16 v[96:99], v[156:159], v[180:183], v[96:99]
	v_mfma_f32_16x16x32_bf16 v[80:83], v[152:155], v[184:187], v[80:83]
	v_mfma_f32_16x16x32_bf16 v[80:83], v[156:159], v[188:191], v[80:83]
	v_mfma_f32_16x16x32_bf16 v[68:71], v[152:155], v[192:195], v[68:71]
	v_mfma_f32_16x16x32_bf16 v[68:71], v[156:159], v[200:203], v[68:71]
	v_mfma_f32_16x16x32_bf16 v[104:107], v[160:163], v[168:171], v[104:107]
	v_mfma_f32_16x16x32_bf16 v[104:107], v[164:167], v[172:175], v[104:107]
	v_mfma_f32_16x16x32_bf16 v[88:91], v[160:163], v[176:179], v[88:91]
	v_mfma_f32_16x16x32_bf16 v[88:91], v[164:167], v[180:183], v[88:91]
	v_mfma_f32_16x16x32_bf16 v[72:75], v[160:163], v[184:187], v[72:75]
	v_mfma_f32_16x16x32_bf16 v[72:75], v[164:167], v[188:191], v[72:75]
	v_mfma_f32_16x16x32_bf16 v[64:67], v[160:163], v[192:195], v[64:67]
	v_mfma_f32_16x16x32_bf16 v[64:67], v[164:167], v[200:203], v[64:67]
	s_setprio 0
	s_barrier
	s_add_i32 s72, s72, s97
	s_mov_b64 s[70:71], s[30:31]
	s_mov_b32 m0, s72
	ds_read_b128 v[168:171], v135 offset:16384
	ds_read_b128 v[172:175], v135 offset:17408
	ds_read_b128 v[176:179], v135 offset:18432
	ds_read_b128 v[180:183], v135 offset:19456
	ds_read_b128 v[184:187], v135 offset:20480
	ds_read_b128 v[188:191], v135 offset:21504
	ds_read_b128 v[192:195], v135 offset:22528
	ds_read_b128 v[200:203], v135 offset:23552
	s_nop 0
	global_load_lds_dwordx4 v132, s[70:71]
	s_add_i32 m0, s72, 0x2000
	s_nop 0
	global_load_lds_dwordx4 v130, s[70:71]
	s_add_u32 s70, s30, 0x20000
	s_addc_u32 s71, s31, 0
	s_add_i32 s72, s74, s97
	s_mov_b32 m0, s72
	s_nop 0
	global_load_lds_dwordx4 v132, s[70:71]
	s_add_i32 m0, s72, 0x2000
	s_nop 0
	global_load_lds_dwordx4 v130, s[70:71]
	s_mov_b64 s[70:71], s[34:35]
	s_mov_b32 m0, s25
	s_nop 0
	global_load_lds_dwordx4 v133, s[70:71]
	s_mov_b32 m0, s37
	s_nop 0
	global_load_lds_dwordx4 v131, s[70:71]
	s_waitcnt vmcnt(8)
	s_waitcnt lgkmcnt(0)
	s_barrier
	s_setprio 1
	s_waitcnt lgkmcnt(0)
	v_mfma_f32_16x16x32_bf16 v[60:63], v[136:139], v[168:171], v[60:63]
	v_mfma_f32_16x16x32_bf16 v[60:63], v[140:143], v[172:175], v[60:63]
	v_mfma_f32_16x16x32_bf16 v[52:55], v[136:139], v[176:179], v[52:55]
	v_mfma_f32_16x16x32_bf16 v[52:55], v[140:143], v[180:183], v[52:55]
	v_mfma_f32_16x16x32_bf16 v[36:39], v[136:139], v[184:187], v[36:39]
	v_mfma_f32_16x16x32_bf16 v[36:39], v[140:143], v[188:191], v[36:39]
	v_mfma_f32_16x16x32_bf16 v[20:23], v[136:139], v[192:195], v[20:23]
	v_mfma_f32_16x16x32_bf16 v[20:23], v[140:143], v[200:203], v[20:23]
	v_mfma_f32_16x16x32_bf16 v[56:59], v[144:147], v[168:171], v[56:59]
	v_mfma_f32_16x16x32_bf16 v[56:59], v[148:151], v[172:175], v[56:59]
	v_mfma_f32_16x16x32_bf16 v[44:47], v[144:147], v[176:179], v[44:47]
	v_mfma_f32_16x16x32_bf16 v[44:47], v[148:151], v[180:183], v[44:47]
	v_mfma_f32_16x16x32_bf16 v[28:31], v[144:147], v[184:187], v[28:31]
	v_mfma_f32_16x16x32_bf16 v[28:31], v[148:151], v[188:191], v[28:31]
	v_mfma_f32_16x16x32_bf16 v[12:15], v[144:147], v[192:195], v[12:15]
	v_mfma_f32_16x16x32_bf16 v[12:15], v[148:151], v[200:203], v[12:15]
	s_setprio 0
	s_setprio 1
	v_mfma_f32_16x16x32_bf16 v[48:51], v[152:155], v[168:171], v[48:51]
	v_mfma_f32_16x16x32_bf16 v[48:51], v[156:159], v[172:175], v[48:51]
	v_mfma_f32_16x16x32_bf16 v[32:35], v[152:155], v[176:179], v[32:35]
	v_mfma_f32_16x16x32_bf16 v[32:35], v[156:159], v[180:183], v[32:35]
	v_mfma_f32_16x16x32_bf16 v[16:19], v[152:155], v[184:187], v[16:19]
	v_mfma_f32_16x16x32_bf16 v[16:19], v[156:159], v[188:191], v[16:19]
	v_mfma_f32_16x16x32_bf16 v[4:7], v[152:155], v[192:195], v[4:7]
	v_mfma_f32_16x16x32_bf16 v[4:7], v[156:159], v[200:203], v[4:7]
	v_mfma_f32_16x16x32_bf16 v[40:43], v[160:163], v[168:171], v[40:43]
	v_mfma_f32_16x16x32_bf16 v[40:43], v[164:167], v[172:175], v[40:43]
	v_mfma_f32_16x16x32_bf16 v[24:27], v[160:163], v[176:179], v[24:27]
	v_mfma_f32_16x16x32_bf16 v[24:27], v[164:167], v[180:183], v[24:27]
	v_mfma_f32_16x16x32_bf16 v[8:11], v[160:163], v[184:187], v[8:11]
	v_mfma_f32_16x16x32_bf16 v[8:11], v[164:167], v[188:191], v[8:11]
	v_mfma_f32_16x16x32_bf16 v[0:3], v[160:163], v[192:195], v[0:3]
	v_mfma_f32_16x16x32_bf16 v[0:3], v[164:167], v[200:203], v[0:3]
	s_setprio 0
	s_barrier
	s_add_i32 s70, 0, 0x18000
	v_add_u32_e32 v128, s70, v134
	s_add_i32 s71, 0, 0x1c000
	ds_read_b128 v[136:139], v128
	ds_read_b128 v[140:143], v128 offset:1024
	ds_read_b128 v[144:147], v128 offset:2048
	ds_read_b128 v[148:151], v128 offset:3072
	v_add_u32_e32 v128, s71, v134
	ds_read_b128 v[152:155], v128
	ds_read_b128 v[156:159], v128 offset:1024
	ds_read_b128 v[160:163], v128 offset:2048
	ds_read_b128 v[164:167], v128 offset:3072
	s_add_u32 s34, s34, 0x20000
	s_addc_u32 s35, s35, 0
	s_mov_b32 m0, s38
	ds_read_b128 v[168:171], v135 offset:32768
	ds_read_b128 v[172:175], v135 offset:33792
	ds_read_b128 v[176:179], v135 offset:34816
	ds_read_b128 v[180:183], v135 offset:35840
	ds_read_b128 v[184:187], v135 offset:36864
	ds_read_b128 v[188:191], v135 offset:37888
	ds_read_b128 v[192:195], v135 offset:38912
	ds_read_b128 v[200:203], v135 offset:39936
	s_nop 0
	global_load_lds_dwordx4 v133, s[34:35]
	s_mov_b32 m0, s39
	s_nop 0
	global_load_lds_dwordx4 v131, s[34:35]
	s_waitcnt vmcnt(8)
	s_waitcnt lgkmcnt(0)
	s_barrier
	s_setprio 1
	s_waitcnt lgkmcnt(0)
	v_mfma_f32_16x16x32_bf16 v[124:127], v[136:139], v[168:171], v[124:127]
	v_mfma_f32_16x16x32_bf16 v[124:127], v[140:143], v[172:175], v[124:127]
	v_mfma_f32_16x16x32_bf16 v[116:119], v[136:139], v[176:179], v[116:119]
	v_mfma_f32_16x16x32_bf16 v[116:119], v[140:143], v[180:183], v[116:119]
	v_mfma_f32_16x16x32_bf16 v[100:103], v[136:139], v[184:187], v[100:103]
	v_mfma_f32_16x16x32_bf16 v[100:103], v[140:143], v[188:191], v[100:103]
	v_mfma_f32_16x16x32_bf16 v[84:87], v[136:139], v[192:195], v[84:87]
	v_mfma_f32_16x16x32_bf16 v[84:87], v[140:143], v[200:203], v[84:87]
	v_mfma_f32_16x16x32_bf16 v[120:123], v[144:147], v[168:171], v[120:123]
	v_mfma_f32_16x16x32_bf16 v[120:123], v[148:151], v[172:175], v[120:123]
	v_mfma_f32_16x16x32_bf16 v[108:111], v[144:147], v[176:179], v[108:111]
	v_mfma_f32_16x16x32_bf16 v[108:111], v[148:151], v[180:183], v[108:111]
	v_mfma_f32_16x16x32_bf16 v[92:95], v[144:147], v[184:187], v[92:95]
	v_mfma_f32_16x16x32_bf16 v[92:95], v[148:151], v[188:191], v[92:95]
	v_mfma_f32_16x16x32_bf16 v[76:79], v[144:147], v[192:195], v[76:79]
	v_mfma_f32_16x16x32_bf16 v[76:79], v[148:151], v[200:203], v[76:79]
	s_setprio 0
	s_setprio 1
	v_mfma_f32_16x16x32_bf16 v[112:115], v[152:155], v[168:171], v[112:115]
	v_mfma_f32_16x16x32_bf16 v[112:115], v[156:159], v[172:175], v[112:115]
	v_mfma_f32_16x16x32_bf16 v[96:99], v[152:155], v[176:179], v[96:99]
	v_mfma_f32_16x16x32_bf16 v[96:99], v[156:159], v[180:183], v[96:99]
	v_mfma_f32_16x16x32_bf16 v[80:83], v[152:155], v[184:187], v[80:83]
	v_mfma_f32_16x16x32_bf16 v[80:83], v[156:159], v[188:191], v[80:83]
	v_mfma_f32_16x16x32_bf16 v[68:71], v[152:155], v[192:195], v[68:71]
	v_mfma_f32_16x16x32_bf16 v[68:71], v[156:159], v[200:203], v[68:71]
	v_mfma_f32_16x16x32_bf16 v[104:107], v[160:163], v[168:171], v[104:107]
	v_mfma_f32_16x16x32_bf16 v[104:107], v[164:167], v[172:175], v[104:107]
	v_mfma_f32_16x16x32_bf16 v[88:91], v[160:163], v[176:179], v[88:91]
	v_mfma_f32_16x16x32_bf16 v[88:91], v[164:167], v[180:183], v[88:91]
	v_mfma_f32_16x16x32_bf16 v[72:75], v[160:163], v[184:187], v[72:75]
	v_mfma_f32_16x16x32_bf16 v[72:75], v[164:167], v[188:191], v[72:75]
	v_mfma_f32_16x16x32_bf16 v[64:67], v[160:163], v[192:195], v[64:67]
	v_mfma_f32_16x16x32_bf16 v[64:67], v[164:167], v[200:203], v[64:67]
	s_setprio 0
	s_barrier
	s_add_u32 s34, s30, 0x80
	s_addc_u32 s35, s31, 0
	s_add_i32 s70, s70, s97
	s_mov_b32 m0, s70
	ds_read_b128 v[168:171], v135 offset:49152
	ds_read_b128 v[172:175], v135 offset:50176
	ds_read_b128 v[176:179], v135 offset:51200
	ds_read_b128 v[180:183], v135 offset:52224
	ds_read_b128 v[184:187], v135 offset:53248
	ds_read_b128 v[188:191], v135 offset:54272
	ds_read_b128 v[192:195], v135 offset:55296
	ds_read_b128 v[200:203], v135 offset:56320
	s_nop 0
	global_load_lds_dwordx4 v132, s[34:35]
	s_add_i32 m0, s70, 0x2000
	s_add_u32 s30, s30, 0x20080
	s_addc_u32 s31, s31, 0
	global_load_lds_dwordx4 v130, s[34:35]
	s_add_i32 s34, s71, s97
	s_mov_b32 m0, s34
	s_nop 0
	global_load_lds_dwordx4 v132, s[30:31]
	s_add_i32 m0, s34, 0x2000
	s_nop 0
	global_load_lds_dwordx4 v130, s[30:31]
	s_mov_b32 m0, s44
	s_nop 0
	global_load_lds_dwordx4 v133, s[28:29]
	s_mov_b32 m0, s46
	s_nop 0
	global_load_lds_dwordx4 v131, s[28:29]
	s_waitcnt vmcnt(8)
	s_waitcnt lgkmcnt(0)
	s_barrier
	s_setprio 1
	s_waitcnt lgkmcnt(0)
	v_mfma_f32_16x16x32_bf16 v[60:63], v[136:139], v[168:171], v[60:63]
	v_mfma_f32_16x16x32_bf16 v[60:63], v[140:143], v[172:175], v[60:63]
	v_mfma_f32_16x16x32_bf16 v[52:55], v[136:139], v[176:179], v[52:55]
	v_mfma_f32_16x16x32_bf16 v[52:55], v[140:143], v[180:183], v[52:55]
	v_mfma_f32_16x16x32_bf16 v[36:39], v[136:139], v[184:187], v[36:39]
	v_mfma_f32_16x16x32_bf16 v[36:39], v[140:143], v[188:191], v[36:39]
	v_mfma_f32_16x16x32_bf16 v[20:23], v[136:139], v[192:195], v[20:23]
	v_mfma_f32_16x16x32_bf16 v[20:23], v[140:143], v[200:203], v[20:23]
	v_mfma_f32_16x16x32_bf16 v[56:59], v[144:147], v[168:171], v[56:59]
	v_mfma_f32_16x16x32_bf16 v[56:59], v[148:151], v[172:175], v[56:59]
	v_mfma_f32_16x16x32_bf16 v[44:47], v[144:147], v[176:179], v[44:47]
	v_mfma_f32_16x16x32_bf16 v[44:47], v[148:151], v[180:183], v[44:47]
	v_mfma_f32_16x16x32_bf16 v[28:31], v[144:147], v[184:187], v[28:31]
	v_mfma_f32_16x16x32_bf16 v[28:31], v[148:151], v[188:191], v[28:31]
	v_mfma_f32_16x16x32_bf16 v[12:15], v[144:147], v[192:195], v[12:15]
	v_mfma_f32_16x16x32_bf16 v[12:15], v[148:151], v[200:203], v[12:15]
	s_setprio 0
	s_setprio 1
	v_mfma_f32_16x16x32_bf16 v[48:51], v[152:155], v[168:171], v[48:51]
	v_mfma_f32_16x16x32_bf16 v[48:51], v[156:159], v[172:175], v[48:51]
	v_mfma_f32_16x16x32_bf16 v[32:35], v[152:155], v[176:179], v[32:35]
	v_mfma_f32_16x16x32_bf16 v[32:35], v[156:159], v[180:183], v[32:35]
	v_mfma_f32_16x16x32_bf16 v[16:19], v[152:155], v[184:187], v[16:19]
	v_mfma_f32_16x16x32_bf16 v[16:19], v[156:159], v[188:191], v[16:19]
	v_mfma_f32_16x16x32_bf16 v[4:7], v[152:155], v[192:195], v[4:7]
	v_mfma_f32_16x16x32_bf16 v[4:7], v[156:159], v[200:203], v[4:7]
	v_mfma_f32_16x16x32_bf16 v[40:43], v[160:163], v[168:171], v[40:43]
	v_mfma_f32_16x16x32_bf16 v[40:43], v[164:167], v[172:175], v[40:43]
	v_mfma_f32_16x16x32_bf16 v[24:27], v[160:163], v[176:179], v[24:27]
	v_mfma_f32_16x16x32_bf16 v[24:27], v[164:167], v[180:183], v[24:27]
	v_mfma_f32_16x16x32_bf16 v[8:11], v[160:163], v[184:187], v[8:11]
	v_mfma_f32_16x16x32_bf16 v[8:11], v[164:167], v[188:191], v[8:11]
	v_mfma_f32_16x16x32_bf16 v[0:3], v[160:163], v[192:195], v[0:3]
	v_mfma_f32_16x16x32_bf16 v[0:3], v[164:167], v[200:203], v[0:3]
	s_setprio 0
	s_barrier
	s_add_i32 s69, s69, 2
	s_add_u32 s49, s49, 0x100
	s_addc_u32 s56, s56, 0
	s_add_u32 s57, s57, 0x100
	s_addc_u32 s65, s65, 0
	s_add_u32 s26, s26, 0x100
	s_addc_u32 s27, s27, 0
	s_cmp_gt_u32 s69, 5
	s_cbranch_scc0 .LBB0_397
	s_and_b64 vcc, exec, s[60:61]
	s_cbranch_vccz .LBB0_400
	s_barrier

.LBB0_527:
	s_cmp_eq_u32 s85, 28
	s_cselect_b32 s56, s5, s39
	s_cselect_b32 s57, s4, s69
	s_cselect_b32 s86, s37, s72
	s_cselect_b32 s87, s11, s74
	s_add_u32 s12, s56, 0x80
	s_addc_u32 s13, s57, 0
	s_add_i32 vcc_lo, 0, 0x10000
	s_add_i32 vcc_hi, 0, 0x14000
	v_add_u32_e32 v136, vcc_lo, v184
	v_add_u32_e32 v156, vcc_hi, v184
	ds_read_b128 v[104:107], v136
	ds_read_b128 v[108:111], v136 offset:1024
	ds_read_b128 v[132:135], v136 offset:2048
	ds_read_b128 v[136:139], v136 offset:3072
	ds_read_b128 v[144:147], v156
	ds_read_b128 v[148:151], v156 offset:1024
	ds_read_b128 v[152:155], v156 offset:2048
	ds_read_b128 v[156:159], v156 offset:3072
	s_mov_b64 s[8:9], s[16:17]
	s_add_i32 m0, s89, 0xc000
	ds_read_b128 v[160:163], v185
	ds_read_b128 v[164:167], v185 offset:1024
	ds_read_b128 v[168:171], v185 offset:2048
	ds_read_b128 v[172:175], v185 offset:3072
	ds_read_b128 v[186:189], v185 offset:4096
	ds_read_b128 v[190:193], v185 offset:5120
	ds_read_b128 v[200:203], v185 offset:6144
	ds_read_b128 v[204:207], v185 offset:7168
	s_nop 0
	global_load_lds_dwordx4 v179, s[8:9]
	s_add_i32 m0, s89, 0xe000
	s_nop 0
	global_load_lds_dwordx4 v182, s[8:9]
	s_waitcnt vmcnt(8)
	s_waitcnt lgkmcnt(0)
	s_barrier
	s_setprio 1
	s_waitcnt lgkmcnt(0)
	v_mfma_f32_16x16x32_bf16 v[140:143], v[104:107], v[160:163], v[140:143]
	v_mfma_f32_16x16x32_bf16 v[140:143], v[108:111], v[164:167], v[140:143]
	v_mfma_f32_16x16x32_bf16 v[124:127], v[104:107], v[168:171], v[124:127]
	v_mfma_f32_16x16x32_bf16 v[124:127], v[108:111], v[172:175], v[124:127]
	v_mfma_f32_16x16x32_bf16 v[96:99], v[104:107], v[186:189], v[96:99]
	v_mfma_f32_16x16x32_bf16 v[96:99], v[108:111], v[190:193], v[96:99]
	v_mfma_f32_16x16x32_bf16 v[84:87], v[104:107], v[200:203], v[84:87]
	v_mfma_f32_16x16x32_bf16 v[84:87], v[108:111], v[204:207], v[84:87]
	v_mfma_f32_16x16x32_bf16 v[128:131], v[132:135], v[160:163], v[128:131]
	v_mfma_f32_16x16x32_bf16 v[128:131], v[136:139], v[164:167], v[128:131]
	v_mfma_f32_16x16x32_bf16 v[112:115], v[132:135], v[168:171], v[112:115]
	v_mfma_f32_16x16x32_bf16 v[112:115], v[136:139], v[172:175], v[112:115]
	v_mfma_f32_16x16x32_bf16 v[88:91], v[132:135], v[186:189], v[88:91]
	v_mfma_f32_16x16x32_bf16 v[88:91], v[136:139], v[190:193], v[88:91]
	v_mfma_f32_16x16x32_bf16 v[72:75], v[132:135], v[200:203], v[72:75]
	v_mfma_f32_16x16x32_bf16 v[72:75], v[136:139], v[204:207], v[72:75]
	s_setprio 0
	s_setprio 1
	v_mfma_f32_16x16x32_bf16 v[120:123], v[144:147], v[160:163], v[120:123]
	v_mfma_f32_16x16x32_bf16 v[120:123], v[148:151], v[164:167], v[120:123]
	v_mfma_f32_16x16x32_bf16 v[100:103], v[144:147], v[168:171], v[100:103]
	v_mfma_f32_16x16x32_bf16 v[100:103], v[148:151], v[172:175], v[100:103]
	v_mfma_f32_16x16x32_bf16 v[80:83], v[144:147], v[186:189], v[80:83]
	v_mfma_f32_16x16x32_bf16 v[80:83], v[148:151], v[190:193], v[80:83]
	v_mfma_f32_16x16x32_bf16 v[68:71], v[144:147], v[200:203], v[68:71]
	v_mfma_f32_16x16x32_bf16 v[68:71], v[148:151], v[204:207], v[68:71]
	v_mfma_f32_16x16x32_bf16 v[116:119], v[152:155], v[160:163], v[116:119]
	v_mfma_f32_16x16x32_bf16 v[116:119], v[156:159], v[164:167], v[116:119]
	v_mfma_f32_16x16x32_bf16 v[92:95], v[152:155], v[168:171], v[92:95]
	v_mfma_f32_16x16x32_bf16 v[92:95], v[156:159], v[172:175], v[92:95]
	v_mfma_f32_16x16x32_bf16 v[76:79], v[152:155], v[186:189], v[76:79]
	v_mfma_f32_16x16x32_bf16 v[76:79], v[156:159], v[190:193], v[76:79]
	v_mfma_f32_16x16x32_bf16 v[64:67], v[152:155], v[200:203], v[64:67]
	v_mfma_f32_16x16x32_bf16 v[64:67], v[156:159], v[204:207], v[64:67]
	s_setprio 0
	s_barrier
	s_add_i32 vcc_lo, vcc_lo, s97
	s_mov_b64 s[8:9], s[86:87]
	s_mov_b32 m0, vcc_lo
	ds_read_b128 v[160:163], v185 offset:16384
	ds_read_b128 v[164:167], v185 offset:17408
	ds_read_b128 v[168:171], v185 offset:18432
	ds_read_b128 v[172:175], v185 offset:19456
	ds_read_b128 v[186:189], v185 offset:20480
	ds_read_b128 v[190:193], v185 offset:21504
	ds_read_b128 v[200:203], v185 offset:22528
	ds_read_b128 v[204:207], v185 offset:23552
	s_nop 0
	global_load_lds_dwordx4 v181, s[8:9]
	s_add_i32 m0, vcc_lo, 0x2000
	s_nop 0
	global_load_lds_dwordx4 v183, s[8:9]
	s_add_u32 s8, s86, 0x80000
	s_addc_u32 s9, s87, 0
	s_add_i32 vcc_lo, vcc_hi, s97
	s_mov_b32 m0, vcc_lo
	s_nop 0
	global_load_lds_dwordx4 v181, s[8:9]
	s_add_i32 m0, vcc_lo, 0x2000
	s_nop 0
	global_load_lds_dwordx4 v183, s[8:9]
	s_mov_b64 s[8:9], s[56:57]
	s_mov_b32 m0, s89
	s_nop 0
	global_load_lds_dwordx4 v179, s[8:9]
	s_mov_b32 m0, s92
	s_nop 0
	global_load_lds_dwordx4 v182, s[8:9]
	s_waitcnt vmcnt(8)
	s_waitcnt lgkmcnt(0)
	s_barrier
	s_setprio 1
	s_waitcnt lgkmcnt(0)
	v_mfma_f32_16x16x32_bf16 v[60:63], v[104:107], v[160:163], v[60:63]
	v_mfma_f32_16x16x32_bf16 v[60:63], v[108:111], v[164:167], v[60:63]
	v_mfma_f32_16x16x32_bf16 v[48:51], v[104:107], v[168:171], v[48:51]
	v_mfma_f32_16x16x32_bf16 v[48:51], v[108:111], v[172:175], v[48:51]
	v_mfma_f32_16x16x32_bf16 v[32:35], v[104:107], v[186:189], v[32:35]
	v_mfma_f32_16x16x32_bf16 v[32:35], v[108:111], v[190:193], v[32:35]
	v_mfma_f32_16x16x32_bf16 v[16:19], v[104:107], v[200:203], v[16:19]
	v_mfma_f32_16x16x32_bf16 v[16:19], v[108:111], v[204:207], v[16:19]
	v_mfma_f32_16x16x32_bf16 v[56:59], v[132:135], v[160:163], v[56:59]
	v_mfma_f32_16x16x32_bf16 v[56:59], v[136:139], v[164:167], v[56:59]
	v_mfma_f32_16x16x32_bf16 v[40:43], v[132:135], v[168:171], v[40:43]
	v_mfma_f32_16x16x32_bf16 v[40:43], v[136:139], v[172:175], v[40:43]
	v_mfma_f32_16x16x32_bf16 v[24:27], v[132:135], v[186:189], v[24:27]
	v_mfma_f32_16x16x32_bf16 v[24:27], v[136:139], v[190:193], v[24:27]
	v_mfma_f32_16x16x32_bf16 v[8:11], v[132:135], v[200:203], v[8:11]
	v_mfma_f32_16x16x32_bf16 v[8:11], v[136:139], v[204:207], v[8:11]
	s_setprio 0
	s_setprio 1
	v_mfma_f32_16x16x32_bf16 v[52:55], v[144:147], v[160:163], v[52:55]
	v_mfma_f32_16x16x32_bf16 v[52:55], v[148:151], v[164:167], v[52:55]
	v_mfma_f32_16x16x32_bf16 v[36:39], v[144:147], v[168:171], v[36:39]
	v_mfma_f32_16x16x32_bf16 v[36:39], v[148:151], v[172:175], v[36:39]
	v_mfma_f32_16x16x32_bf16 v[20:23], v[144:147], v[186:189], v[20:23]
	v_mfma_f32_16x16x32_bf16 v[20:23], v[148:151], v[190:193], v[20:23]
	v_mfma_f32_16x16x32_bf16 v[4:7], v[144:147], v[200:203], v[4:7]
	v_mfma_f32_16x16x32_bf16 v[4:7], v[148:151], v[204:207], v[4:7]
	v_mfma_f32_16x16x32_bf16 v[44:47], v[152:155], v[160:163], v[44:47]
	v_mfma_f32_16x16x32_bf16 v[44:47], v[156:159], v[164:167], v[44:47]
	v_mfma_f32_16x16x32_bf16 v[28:31], v[152:155], v[168:171], v[28:31]
	v_mfma_f32_16x16x32_bf16 v[28:31], v[156:159], v[172:175], v[28:31]
	v_mfma_f32_16x16x32_bf16 v[12:15], v[152:155], v[186:189], v[12:15]
	v_mfma_f32_16x16x32_bf16 v[12:15], v[156:159], v[190:193], v[12:15]
	v_mfma_f32_16x16x32_bf16 v[0:3], v[152:155], v[200:203], v[0:3]
	v_mfma_f32_16x16x32_bf16 v[0:3], v[156:159], v[204:207], v[0:3]
	s_setprio 0
	s_barrier
	s_add_i32 vcc_lo, 0, 0x18000
	s_add_i32 vcc_hi, 0, 0x1c000
	v_add_u32_e32 v136, vcc_lo, v184
	v_add_u32_e32 v156, vcc_hi, v184
	ds_read_b128 v[104:107], v136
	ds_read_b128 v[108:111], v136 offset:1024
	ds_read_b128 v[132:135], v136 offset:2048
	ds_read_b128 v[136:139], v136 offset:3072
	ds_read_b128 v[144:147], v156
	ds_read_b128 v[148:151], v156 offset:1024
	ds_read_b128 v[152:155], v156 offset:2048
	ds_read_b128 v[156:159], v156 offset:3072
	s_add_u32 s8, s56, 0x80000
	s_addc_u32 s9, s57, 0
	s_mov_b32 m0, s93
	ds_read_b128 v[160:163], v185 offset:32768
	ds_read_b128 v[164:167], v185 offset:33792
	ds_read_b128 v[168:171], v185 offset:34816
	ds_read_b128 v[172:175], v185 offset:35840
	ds_read_b128 v[186:189], v185 offset:36864
	ds_read_b128 v[190:193], v185 offset:37888
	ds_read_b128 v[200:203], v185 offset:38912
	ds_read_b128 v[204:207], v185 offset:39936
	s_nop 0
	global_load_lds_dwordx4 v179, s[8:9]
	s_mov_b32 m0, s48
	s_nop 0
	global_load_lds_dwordx4 v182, s[8:9]
	s_waitcnt vmcnt(8)
	s_waitcnt lgkmcnt(0)
	s_barrier
	s_setprio 1
	s_waitcnt lgkmcnt(0)
	v_mfma_f32_16x16x32_bf16 v[140:143], v[104:107], v[160:163], v[140:143]
	v_mfma_f32_16x16x32_bf16 v[140:143], v[108:111], v[164:167], v[140:143]
	v_mfma_f32_16x16x32_bf16 v[124:127], v[104:107], v[168:171], v[124:127]
	v_mfma_f32_16x16x32_bf16 v[124:127], v[108:111], v[172:175], v[124:127]
	v_mfma_f32_16x16x32_bf16 v[96:99], v[104:107], v[186:189], v[96:99]
	v_mfma_f32_16x16x32_bf16 v[96:99], v[108:111], v[190:193], v[96:99]
	v_mfma_f32_16x16x32_bf16 v[84:87], v[104:107], v[200:203], v[84:87]
	v_mfma_f32_16x16x32_bf16 v[84:87], v[108:111], v[204:207], v[84:87]
	v_mfma_f32_16x16x32_bf16 v[128:131], v[132:135], v[160:163], v[128:131]
	v_mfma_f32_16x16x32_bf16 v[128:131], v[136:139], v[164:167], v[128:131]
	v_mfma_f32_16x16x32_bf16 v[112:115], v[132:135], v[168:171], v[112:115]
	v_mfma_f32_16x16x32_bf16 v[112:115], v[136:139], v[172:175], v[112:115]
	v_mfma_f32_16x16x32_bf16 v[88:91], v[132:135], v[186:189], v[88:91]
	v_mfma_f32_16x16x32_bf16 v[88:91], v[136:139], v[190:193], v[88:91]
	v_mfma_f32_16x16x32_bf16 v[72:75], v[132:135], v[200:203], v[72:75]
	v_mfma_f32_16x16x32_bf16 v[72:75], v[136:139], v[204:207], v[72:75]
	s_setprio 0
	s_setprio 1
	v_mfma_f32_16x16x32_bf16 v[120:123], v[144:147], v[160:163], v[120:123]
	v_mfma_f32_16x16x32_bf16 v[120:123], v[148:151], v[164:167], v[120:123]
	v_mfma_f32_16x16x32_bf16 v[100:103], v[144:147], v[168:171], v[100:103]
	v_mfma_f32_16x16x32_bf16 v[100:103], v[148:151], v[172:175], v[100:103]
	v_mfma_f32_16x16x32_bf16 v[80:83], v[144:147], v[186:189], v[80:83]
	v_mfma_f32_16x16x32_bf16 v[80:83], v[148:151], v[190:193], v[80:83]
	v_mfma_f32_16x16x32_bf16 v[68:71], v[144:147], v[200:203], v[68:71]
	v_mfma_f32_16x16x32_bf16 v[68:71], v[148:151], v[204:207], v[68:71]
	v_mfma_f32_16x16x32_bf16 v[116:119], v[152:155], v[160:163], v[116:119]
	v_mfma_f32_16x16x32_bf16 v[116:119], v[156:159], v[164:167], v[116:119]
	v_mfma_f32_16x16x32_bf16 v[92:95], v[152:155], v[168:171], v[92:95]
	v_mfma_f32_16x16x32_bf16 v[92:95], v[156:159], v[172:175], v[92:95]
	v_mfma_f32_16x16x32_bf16 v[76:79], v[152:155], v[186:189], v[76:79]
	v_mfma_f32_16x16x32_bf16 v[76:79], v[156:159], v[190:193], v[76:79]
	v_mfma_f32_16x16x32_bf16 v[64:67], v[152:155], v[200:203], v[64:67]
	v_mfma_f32_16x16x32_bf16 v[64:67], v[156:159], v[204:207], v[64:67]
	s_setprio 0
	s_barrier
	s_add_u32 s8, s86, 0x80
	s_addc_u32 s9, s87, 0
	s_add_i32 s56, vcc_lo, s97
	s_mov_b32 m0, s56
	ds_read_b128 v[160:163], v185 offset:49152
	ds_read_b128 v[164:167], v185 offset:50176
	ds_read_b128 v[168:171], v185 offset:51200
	ds_read_b128 v[172:175], v185 offset:52224
	ds_read_b128 v[186:189], v185 offset:53248
	ds_read_b128 v[190:193], v185 offset:54272
	ds_read_b128 v[200:203], v185 offset:55296
	ds_read_b128 v[204:207], v185 offset:56320
	s_nop 0
	global_load_lds_dwordx4 v181, s[8:9]
	s_add_i32 m0, s56, 0x2000
	s_nop 0
	global_load_lds_dwordx4 v183, s[8:9]
	s_add_u32 s8, s86, 0x80080
	s_addc_u32 s9, s87, 0
	s_add_i32 s56, vcc_hi, s97
	s_mov_b32 m0, s56
	s_nop 0
	global_load_lds_dwordx4 v181, s[8:9]
	s_add_i32 m0, s56, 0x2000
	s_nop 0
	global_load_lds_dwordx4 v183, s[8:9]
	s_mov_b32 m0, s46
	s_nop 0
	global_load_lds_dwordx4 v179, s[12:13]
	s_mov_b32 m0, s70
	s_nop 0
	global_load_lds_dwordx4 v182, s[12:13]
	s_waitcnt vmcnt(8)
	s_waitcnt lgkmcnt(0)
	s_barrier
	s_setprio 1
	s_waitcnt lgkmcnt(0)
	v_mfma_f32_16x16x32_bf16 v[60:63], v[104:107], v[160:163], v[60:63]
	v_mfma_f32_16x16x32_bf16 v[60:63], v[108:111], v[164:167], v[60:63]
	v_mfma_f32_16x16x32_bf16 v[48:51], v[104:107], v[168:171], v[48:51]
	v_mfma_f32_16x16x32_bf16 v[48:51], v[108:111], v[172:175], v[48:51]
	v_mfma_f32_16x16x32_bf16 v[32:35], v[104:107], v[186:189], v[32:35]
	v_mfma_f32_16x16x32_bf16 v[32:35], v[108:111], v[190:193], v[32:35]
	v_mfma_f32_16x16x32_bf16 v[16:19], v[104:107], v[200:203], v[16:19]
	v_mfma_f32_16x16x32_bf16 v[16:19], v[108:111], v[204:207], v[16:19]
	v_mfma_f32_16x16x32_bf16 v[56:59], v[132:135], v[160:163], v[56:59]
	v_mfma_f32_16x16x32_bf16 v[56:59], v[136:139], v[164:167], v[56:59]
	v_mfma_f32_16x16x32_bf16 v[40:43], v[132:135], v[168:171], v[40:43]
	v_mfma_f32_16x16x32_bf16 v[40:43], v[136:139], v[172:175], v[40:43]
	v_mfma_f32_16x16x32_bf16 v[24:27], v[132:135], v[186:189], v[24:27]
	v_mfma_f32_16x16x32_bf16 v[24:27], v[136:139], v[190:193], v[24:27]
	v_mfma_f32_16x16x32_bf16 v[8:11], v[132:135], v[200:203], v[8:11]
	v_mfma_f32_16x16x32_bf16 v[8:11], v[136:139], v[204:207], v[8:11]
	s_setprio 0
	s_setprio 1
	v_mfma_f32_16x16x32_bf16 v[52:55], v[144:147], v[160:163], v[52:55]
	v_mfma_f32_16x16x32_bf16 v[52:55], v[148:151], v[164:167], v[52:55]
	v_mfma_f32_16x16x32_bf16 v[36:39], v[144:147], v[168:171], v[36:39]
	v_mfma_f32_16x16x32_bf16 v[36:39], v[148:151], v[172:175], v[36:39]
	v_mfma_f32_16x16x32_bf16 v[20:23], v[144:147], v[186:189], v[20:23]
	v_mfma_f32_16x16x32_bf16 v[20:23], v[148:151], v[190:193], v[20:23]
	v_mfma_f32_16x16x32_bf16 v[4:7], v[144:147], v[200:203], v[4:7]
	v_mfma_f32_16x16x32_bf16 v[4:7], v[148:151], v[204:207], v[4:7]
	v_mfma_f32_16x16x32_bf16 v[44:47], v[152:155], v[160:163], v[44:47]
	v_mfma_f32_16x16x32_bf16 v[44:47], v[156:159], v[164:167], v[44:47]
	v_mfma_f32_16x16x32_bf16 v[28:31], v[152:155], v[168:171], v[28:31]
	v_mfma_f32_16x16x32_bf16 v[28:31], v[156:159], v[172:175], v[28:31]
	v_mfma_f32_16x16x32_bf16 v[12:15], v[152:155], v[186:189], v[12:15]
	v_mfma_f32_16x16x32_bf16 v[12:15], v[156:159], v[190:193], v[12:15]
	v_mfma_f32_16x16x32_bf16 v[0:3], v[152:155], v[200:203], v[0:3]
	v_mfma_f32_16x16x32_bf16 v[0:3], v[156:159], v[204:207], v[0:3]
	s_setprio 0
	s_barrier
	s_add_i32 s85, s85, 2
	s_add_u32 s39, s39, 0x100
	s_addc_u32 s69, s69, 0
	s_add_u32 s72, s72, 0x100
	s_addc_u32 s74, s74, 0
	s_add_u32 s16, s16, 0x100
	s_addc_u32 s17, s17, 0
	s_cmp_gt_u32 s85, 29
	s_cbranch_scc0 .LBB0_527
	s_and_b64 vcc, exec, s[60:61]
	s_cbranch_vccz .LBB0_530
	s_barrier

.LBB0_604:
	s_cmp_eq_u32 s21, 4
	s_cselect_b32 s38, s22, s4
	s_cselect_b32 s39, s23, s5
	s_cselect_b32 s36, s24, s15
	s_cselect_b32 s37, s25, s17
	s_add_u32 s34, s38, 0x80
	s_addc_u32 s35, s39, 0
	s_add_i32 s65, 0, 0x10000
	s_add_i32 s69, 0, 0x14000
	v_add_u32_e32 v132, s65, v154
	v_add_u32_e32 v148, s69, v154
	ds_read_b128 v[112:115], v132
	ds_read_b128 v[120:123], v132 offset:1024
	ds_read_b128 v[128:131], v132 offset:2048
	ds_read_b128 v[132:135], v132 offset:3072
	ds_read_b128 v[144:147], v148
	ds_read_b128 v[156:159], v148 offset:1024
	ds_read_b128 v[160:163], v148 offset:2048
	ds_read_b128 v[164:167], v148 offset:3072
	s_add_u32 s70, s4, 0x7ff80
	s_addc_u32 s71, s5, 0
	s_add_i32 m0, s27, 0xc000
	ds_read_b128 v[168:171], v155
	ds_read_b128 v[172:175], v155 offset:1024
	ds_read_b128 v[176:179], v155 offset:2048
	ds_read_b128 v[180:183], v155 offset:3072
	ds_read_b128 v[184:187], v155 offset:4096
	ds_read_b128 v[188:191], v155 offset:5120
	ds_read_b128 v[192:195], v155 offset:6144
	ds_read_b128 v[200:203], v155 offset:7168
	s_nop 0
	global_load_lds_dwordx4 v151, s[70:71]
	s_add_i32 m0, s27, 0xe000
	s_nop 0
	global_load_lds_dwordx4 v150, s[70:71]
	s_waitcnt vmcnt(8)
	s_waitcnt lgkmcnt(0)
	s_barrier
	s_setprio 1
	s_waitcnt lgkmcnt(0)
	v_mfma_f32_16x16x32_bf16 v[140:143], v[112:115], v[168:171], v[140:143]
	v_mfma_f32_16x16x32_bf16 v[140:143], v[120:123], v[172:175], v[140:143]
	v_mfma_f32_16x16x32_bf16 v[108:111], v[112:115], v[176:179], v[108:111]
	v_mfma_f32_16x16x32_bf16 v[108:111], v[120:123], v[180:183], v[108:111]
	v_mfma_f32_16x16x32_bf16 v[92:95], v[112:115], v[184:187], v[92:95]
	v_mfma_f32_16x16x32_bf16 v[92:95], v[120:123], v[188:191], v[92:95]
	v_mfma_f32_16x16x32_bf16 v[76:79], v[112:115], v[192:195], v[76:79]
	v_mfma_f32_16x16x32_bf16 v[76:79], v[120:123], v[200:203], v[76:79]
	v_mfma_f32_16x16x32_bf16 v[136:139], v[128:131], v[168:171], v[136:139]
	v_mfma_f32_16x16x32_bf16 v[136:139], v[132:135], v[172:175], v[136:139]
	v_mfma_f32_16x16x32_bf16 v[104:107], v[128:131], v[176:179], v[104:107]
	v_mfma_f32_16x16x32_bf16 v[104:107], v[132:135], v[180:183], v[104:107]
	v_mfma_f32_16x16x32_bf16 v[88:91], v[128:131], v[184:187], v[88:91]
	v_mfma_f32_16x16x32_bf16 v[88:91], v[132:135], v[188:191], v[88:91]
	v_mfma_f32_16x16x32_bf16 v[72:75], v[128:131], v[192:195], v[72:75]
	v_mfma_f32_16x16x32_bf16 v[72:75], v[132:135], v[200:203], v[72:75]
	s_setprio 0
	s_setprio 1
	v_mfma_f32_16x16x32_bf16 v[124:127], v[144:147], v[168:171], v[124:127]
	v_mfma_f32_16x16x32_bf16 v[124:127], v[156:159], v[172:175], v[124:127]
	v_mfma_f32_16x16x32_bf16 v[100:103], v[144:147], v[176:179], v[100:103]
	v_mfma_f32_16x16x32_bf16 v[100:103], v[156:159], v[180:183], v[100:103]
	v_mfma_f32_16x16x32_bf16 v[84:87], v[144:147], v[184:187], v[84:87]
	v_mfma_f32_16x16x32_bf16 v[84:87], v[156:159], v[188:191], v[84:87]
	v_mfma_f32_16x16x32_bf16 v[68:71], v[144:147], v[192:195], v[68:71]
	v_mfma_f32_16x16x32_bf16 v[68:71], v[156:159], v[200:203], v[68:71]
	v_mfma_f32_16x16x32_bf16 v[116:119], v[160:163], v[168:171], v[116:119]
	v_mfma_f32_16x16x32_bf16 v[116:119], v[164:167], v[172:175], v[116:119]
	v_mfma_f32_16x16x32_bf16 v[96:99], v[160:163], v[176:179], v[96:99]
	v_mfma_f32_16x16x32_bf16 v[96:99], v[164:167], v[180:183], v[96:99]
	v_mfma_f32_16x16x32_bf16 v[80:83], v[160:163], v[184:187], v[80:83]
	v_mfma_f32_16x16x32_bf16 v[80:83], v[164:167], v[188:191], v[80:83]
	v_mfma_f32_16x16x32_bf16 v[64:67], v[160:163], v[192:195], v[64:67]
	v_mfma_f32_16x16x32_bf16 v[64:67], v[164:167], v[200:203], v[64:67]
	s_setprio 0
	s_barrier
	s_add_i32 s65, s65, s97
	s_mov_b64 s[70:71], s[36:37]
	s_mov_b32 m0, s65
	ds_read_b128 v[168:171], v155 offset:16384
	ds_read_b128 v[172:175], v155 offset:17408
	ds_read_b128 v[176:179], v155 offset:18432
	ds_read_b128 v[180:183], v155 offset:19456
	ds_read_b128 v[184:187], v155 offset:20480
	ds_read_b128 v[188:191], v155 offset:21504
	ds_read_b128 v[192:195], v155 offset:22528
	ds_read_b128 v[200:203], v155 offset:23552
	s_nop 0
	global_load_lds_dwordx4 v152, s[70:71]
	s_add_i32 m0, s65, 0x2000
	s_nop 0
	global_load_lds_dwordx4 v153, s[70:71]
	s_add_u32 s70, s36, 0x80000
	s_addc_u32 s71, s37, 0
	s_add_i32 s65, s69, s97
	s_mov_b32 m0, s65
	s_nop 0
	global_load_lds_dwordx4 v152, s[70:71]
	s_add_i32 m0, s65, 0x2000
	s_nop 0
	global_load_lds_dwordx4 v153, s[70:71]
	s_mov_b64 s[70:71], s[38:39]
	s_mov_b32 m0, s27
	s_nop 0
	global_load_lds_dwordx4 v151, s[70:71]
	s_mov_b32 m0, s29
	s_nop 0
	global_load_lds_dwordx4 v150, s[70:71]
	s_waitcnt vmcnt(8)
	s_waitcnt lgkmcnt(0)
	s_barrier
	s_setprio 1
	s_waitcnt lgkmcnt(0)
	v_mfma_f32_16x16x32_bf16 v[60:63], v[112:115], v[168:171], v[60:63]
	v_mfma_f32_16x16x32_bf16 v[60:63], v[120:123], v[172:175], v[60:63]
	v_mfma_f32_16x16x32_bf16 v[52:55], v[112:115], v[176:179], v[52:55]
	v_mfma_f32_16x16x32_bf16 v[52:55], v[120:123], v[180:183], v[52:55]
	v_mfma_f32_16x16x32_bf16 v[36:39], v[112:115], v[184:187], v[36:39]
	v_mfma_f32_16x16x32_bf16 v[36:39], v[120:123], v[188:191], v[36:39]
	v_mfma_f32_16x16x32_bf16 v[20:23], v[112:115], v[192:195], v[20:23]
	v_mfma_f32_16x16x32_bf16 v[20:23], v[120:123], v[200:203], v[20:23]
	v_mfma_f32_16x16x32_bf16 v[56:59], v[128:131], v[168:171], v[56:59]
	v_mfma_f32_16x16x32_bf16 v[56:59], v[132:135], v[172:175], v[56:59]
	v_mfma_f32_16x16x32_bf16 v[44:47], v[128:131], v[176:179], v[44:47]
	v_mfma_f32_16x16x32_bf16 v[44:47], v[132:135], v[180:183], v[44:47]
	v_mfma_f32_16x16x32_bf16 v[28:31], v[128:131], v[184:187], v[28:31]
	v_mfma_f32_16x16x32_bf16 v[28:31], v[132:135], v[188:191], v[28:31]
	v_mfma_f32_16x16x32_bf16 v[8:11], v[128:131], v[192:195], v[8:11]
	v_mfma_f32_16x16x32_bf16 v[8:11], v[132:135], v[200:203], v[8:11]
	s_setprio 0
	s_setprio 1
	v_mfma_f32_16x16x32_bf16 v[48:51], v[144:147], v[168:171], v[48:51]
	v_mfma_f32_16x16x32_bf16 v[48:51], v[156:159], v[172:175], v[48:51]
	v_mfma_f32_16x16x32_bf16 v[32:35], v[144:147], v[176:179], v[32:35]
	v_mfma_f32_16x16x32_bf16 v[32:35], v[156:159], v[180:183], v[32:35]
	v_mfma_f32_16x16x32_bf16 v[16:19], v[144:147], v[184:187], v[16:19]
	v_mfma_f32_16x16x32_bf16 v[16:19], v[156:159], v[188:191], v[16:19]
	v_mfma_f32_16x16x32_bf16 v[4:7], v[144:147], v[192:195], v[4:7]
	v_mfma_f32_16x16x32_bf16 v[4:7], v[156:159], v[200:203], v[4:7]
	v_mfma_f32_16x16x32_bf16 v[40:43], v[160:163], v[168:171], v[40:43]
	v_mfma_f32_16x16x32_bf16 v[40:43], v[164:167], v[172:175], v[40:43]
	v_mfma_f32_16x16x32_bf16 v[24:27], v[160:163], v[176:179], v[24:27]
	v_mfma_f32_16x16x32_bf16 v[24:27], v[164:167], v[180:183], v[24:27]
	v_mfma_f32_16x16x32_bf16 v[12:15], v[160:163], v[184:187], v[12:15]
	v_mfma_f32_16x16x32_bf16 v[12:15], v[164:167], v[188:191], v[12:15]
	v_mfma_f32_16x16x32_bf16 v[0:3], v[160:163], v[192:195], v[0:3]
	v_mfma_f32_16x16x32_bf16 v[0:3], v[164:167], v[200:203], v[0:3]
	s_setprio 0
	s_barrier
	s_add_i32 s65, 0, 0x18000
	s_add_i32 s69, 0, 0x1c000
	v_add_u32_e32 v132, s65, v154
	v_add_u32_e32 v148, s69, v154
	ds_read_b128 v[112:115], v132
	ds_read_b128 v[120:123], v132 offset:1024
	ds_read_b128 v[128:131], v132 offset:2048
	ds_read_b128 v[132:135], v132 offset:3072
	ds_read_b128 v[144:147], v148
	ds_read_b128 v[156:159], v148 offset:1024
	ds_read_b128 v[160:163], v148 offset:2048
	ds_read_b128 v[164:167], v148 offset:3072
	s_add_u32 s38, s38, 0x80000
	s_addc_u32 s39, s39, 0
	s_mov_b32 m0, s31
	ds_read_b128 v[168:171], v155 offset:32768
	ds_read_b128 v[172:175], v155 offset:33792
	ds_read_b128 v[176:179], v155 offset:34816
	ds_read_b128 v[180:183], v155 offset:35840
	ds_read_b128 v[184:187], v155 offset:36864
	ds_read_b128 v[188:191], v155 offset:37888
	ds_read_b128 v[192:195], v155 offset:38912
	ds_read_b128 v[200:203], v155 offset:39936
	s_nop 0
	global_load_lds_dwordx4 v151, s[38:39]
	s_mov_b32 m0, s48
	s_nop 0
	global_load_lds_dwordx4 v150, s[38:39]
	s_waitcnt vmcnt(8)
	s_waitcnt lgkmcnt(0)
	s_barrier
	s_setprio 1
	s_waitcnt lgkmcnt(0)
	v_mfma_f32_16x16x32_bf16 v[140:143], v[112:115], v[168:171], v[140:143]
	v_mfma_f32_16x16x32_bf16 v[140:143], v[120:123], v[172:175], v[140:143]
	v_mfma_f32_16x16x32_bf16 v[108:111], v[112:115], v[176:179], v[108:111]
	v_mfma_f32_16x16x32_bf16 v[108:111], v[120:123], v[180:183], v[108:111]
	v_mfma_f32_16x16x32_bf16 v[92:95], v[112:115], v[184:187], v[92:95]
	v_mfma_f32_16x16x32_bf16 v[92:95], v[120:123], v[188:191], v[92:95]
	v_mfma_f32_16x16x32_bf16 v[76:79], v[112:115], v[192:195], v[76:79]
	v_mfma_f32_16x16x32_bf16 v[76:79], v[120:123], v[200:203], v[76:79]
	v_mfma_f32_16x16x32_bf16 v[136:139], v[128:131], v[168:171], v[136:139]
	v_mfma_f32_16x16x32_bf16 v[136:139], v[132:135], v[172:175], v[136:139]
	v_mfma_f32_16x16x32_bf16 v[104:107], v[128:131], v[176:179], v[104:107]
	v_mfma_f32_16x16x32_bf16 v[104:107], v[132:135], v[180:183], v[104:107]
	v_mfma_f32_16x16x32_bf16 v[88:91], v[128:131], v[184:187], v[88:91]
	v_mfma_f32_16x16x32_bf16 v[88:91], v[132:135], v[188:191], v[88:91]
	v_mfma_f32_16x16x32_bf16 v[72:75], v[128:131], v[192:195], v[72:75]
	v_mfma_f32_16x16x32_bf16 v[72:75], v[132:135], v[200:203], v[72:75]
	s_setprio 0
	s_setprio 1
	v_mfma_f32_16x16x32_bf16 v[124:127], v[144:147], v[168:171], v[124:127]
	v_mfma_f32_16x16x32_bf16 v[124:127], v[156:159], v[172:175], v[124:127]
	v_mfma_f32_16x16x32_bf16 v[100:103], v[144:147], v[176:179], v[100:103]
	v_mfma_f32_16x16x32_bf16 v[100:103], v[156:159], v[180:183], v[100:103]
	v_mfma_f32_16x16x32_bf16 v[84:87], v[144:147], v[184:187], v[84:87]
	v_mfma_f32_16x16x32_bf16 v[84:87], v[156:159], v[188:191], v[84:87]
	v_mfma_f32_16x16x32_bf16 v[68:71], v[144:147], v[192:195], v[68:71]
	v_mfma_f32_16x16x32_bf16 v[68:71], v[156:159], v[200:203], v[68:71]
	v_mfma_f32_16x16x32_bf16 v[116:119], v[160:163], v[168:171], v[116:119]
	v_mfma_f32_16x16x32_bf16 v[116:119], v[164:167], v[172:175], v[116:119]
	v_mfma_f32_16x16x32_bf16 v[96:99], v[160:163], v[176:179], v[96:99]
	v_mfma_f32_16x16x32_bf16 v[96:99], v[164:167], v[180:183], v[96:99]
	v_mfma_f32_16x16x32_bf16 v[80:83], v[160:163], v[184:187], v[80:83]
	v_mfma_f32_16x16x32_bf16 v[80:83], v[164:167], v[188:191], v[80:83]
	v_mfma_f32_16x16x32_bf16 v[64:67], v[160:163], v[192:195], v[64:67]
	v_mfma_f32_16x16x32_bf16 v[64:67], v[164:167], v[200:203], v[64:67]
	s_setprio 0
	s_barrier
	s_add_u32 s38, s36, 0x80
	s_addc_u32 s39, s37, 0
	s_add_i32 s65, s65, s97
	s_mov_b32 m0, s65
	ds_read_b128 v[168:171], v155 offset:49152
	ds_read_b128 v[172:175], v155 offset:50176
	ds_read_b128 v[176:179], v155 offset:51200
	ds_read_b128 v[180:183], v155 offset:52224
	ds_read_b128 v[184:187], v155 offset:53248
	ds_read_b128 v[188:191], v155 offset:54272
	ds_read_b128 v[192:195], v155 offset:55296
	ds_read_b128 v[200:203], v155 offset:56320
	s_nop 0
	global_load_lds_dwordx4 v152, s[38:39]
	s_add_i32 m0, s65, 0x2000
	s_add_u32 s36, s36, 0x80080
	s_addc_u32 s37, s37, 0
	global_load_lds_dwordx4 v153, s[38:39]
	s_add_i32 s38, s69, s97
	s_mov_b32 m0, s38
	s_nop 0
	global_load_lds_dwordx4 v152, s[36:37]
	s_add_i32 m0, s38, 0x2000
	s_nop 0
	global_load_lds_dwordx4 v153, s[36:37]
	s_mov_b32 m0, s49
	s_nop 0
	global_load_lds_dwordx4 v151, s[34:35]
	s_mov_b32 m0, s56
	s_nop 0
	global_load_lds_dwordx4 v150, s[34:35]
	s_waitcnt vmcnt(8)
	s_waitcnt lgkmcnt(0)
	s_barrier
	s_setprio 1
	s_waitcnt lgkmcnt(0)
	v_mfma_f32_16x16x32_bf16 v[60:63], v[112:115], v[168:171], v[60:63]
	v_mfma_f32_16x16x32_bf16 v[60:63], v[120:123], v[172:175], v[60:63]
	v_mfma_f32_16x16x32_bf16 v[52:55], v[112:115], v[176:179], v[52:55]
	v_mfma_f32_16x16x32_bf16 v[52:55], v[120:123], v[180:183], v[52:55]
	v_mfma_f32_16x16x32_bf16 v[36:39], v[112:115], v[184:187], v[36:39]
	v_mfma_f32_16x16x32_bf16 v[36:39], v[120:123], v[188:191], v[36:39]
	v_mfma_f32_16x16x32_bf16 v[20:23], v[112:115], v[192:195], v[20:23]
	v_mfma_f32_16x16x32_bf16 v[20:23], v[120:123], v[200:203], v[20:23]
	v_mfma_f32_16x16x32_bf16 v[56:59], v[128:131], v[168:171], v[56:59]
	v_mfma_f32_16x16x32_bf16 v[56:59], v[132:135], v[172:175], v[56:59]
	v_mfma_f32_16x16x32_bf16 v[44:47], v[128:131], v[176:179], v[44:47]
	v_mfma_f32_16x16x32_bf16 v[44:47], v[132:135], v[180:183], v[44:47]
	v_mfma_f32_16x16x32_bf16 v[28:31], v[128:131], v[184:187], v[28:31]
	v_mfma_f32_16x16x32_bf16 v[28:31], v[132:135], v[188:191], v[28:31]
	v_mfma_f32_16x16x32_bf16 v[8:11], v[128:131], v[192:195], v[8:11]
	v_mfma_f32_16x16x32_bf16 v[8:11], v[132:135], v[200:203], v[8:11]
	s_setprio 0
	s_setprio 1
	v_mfma_f32_16x16x32_bf16 v[48:51], v[144:147], v[168:171], v[48:51]
	v_mfma_f32_16x16x32_bf16 v[48:51], v[156:159], v[172:175], v[48:51]
	v_mfma_f32_16x16x32_bf16 v[32:35], v[144:147], v[176:179], v[32:35]
	v_mfma_f32_16x16x32_bf16 v[32:35], v[156:159], v[180:183], v[32:35]
	v_mfma_f32_16x16x32_bf16 v[16:19], v[144:147], v[184:187], v[16:19]
	v_mfma_f32_16x16x32_bf16 v[16:19], v[156:159], v[188:191], v[16:19]
	v_mfma_f32_16x16x32_bf16 v[4:7], v[144:147], v[192:195], v[4:7]
	v_mfma_f32_16x16x32_bf16 v[4:7], v[156:159], v[200:203], v[4:7]
	v_mfma_f32_16x16x32_bf16 v[40:43], v[160:163], v[168:171], v[40:43]
	v_mfma_f32_16x16x32_bf16 v[40:43], v[164:167], v[172:175], v[40:43]
	v_mfma_f32_16x16x32_bf16 v[24:27], v[160:163], v[176:179], v[24:27]
	v_mfma_f32_16x16x32_bf16 v[24:27], v[164:167], v[180:183], v[24:27]
	v_mfma_f32_16x16x32_bf16 v[12:15], v[160:163], v[184:187], v[12:15]
	v_mfma_f32_16x16x32_bf16 v[12:15], v[164:167], v[188:191], v[12:15]
	v_mfma_f32_16x16x32_bf16 v[0:3], v[160:163], v[192:195], v[0:3]
	v_mfma_f32_16x16x32_bf16 v[0:3], v[164:167], v[200:203], v[0:3]
	s_setprio 0
	s_barrier
	s_add_i32 s21, s21, 2
	s_add_u32 s4, s4, 0x100
	s_addc_u32 s5, s5, 0
	s_add_u32 s15, s15, 0x100
	s_addc_u32 s17, s17, 0
	s_cmp_gt_u32 s21, 5
	s_cbranch_scc0 .LBB0_604
	s_and_b64 vcc, exec, s[60:61]
	s_cbranch_vccz .LBB0_607
	s_barrier

.LBB0_676:
	s_add_u32 s30, s28, 0x100
	s_addc_u32 s31, s29, 0
	s_cmp_eq_u32 s69, 28
	s_cselect_b32 s38, s5, s30
	s_cselect_b32 s39, s4, s31
	s_cselect_b32 s36, s17, s21
	s_cselect_b32 s37, s13, s27
	s_add_u32 s34, s38, 0x80
	s_addc_u32 s35, s39, 0
	s_add_i32 s74, 0, 0x10000
	s_add_i32 s84, 0, 0x14000
	v_add_u32_e32 v140, s74, v150
	v_add_u32_e32 v144, s84, v150
	ds_read_b128 v[128:131], v140
	ds_read_b128 v[132:135], v140 offset:1024
	ds_read_b128 v[136:139], v140 offset:2048
	ds_read_b128 v[140:143], v140 offset:3072
	ds_read_b128 v[152:155], v144
	ds_read_b128 v[156:159], v144 offset:1024
	ds_read_b128 v[160:163], v144 offset:2048
	ds_read_b128 v[164:167], v144 offset:3072
	s_add_u32 s28, s28, 0x80080
	s_addc_u32 s29, s29, 0
	s_add_i32 m0, s48, 0xc000
	ds_read_b128 v[168:171], v151
	ds_read_b128 v[172:175], v151 offset:1024
	ds_read_b128 v[176:179], v151 offset:2048
	ds_read_b128 v[180:183], v151 offset:3072
	ds_read_b128 v[184:187], v151 offset:4096
	ds_read_b128 v[188:191], v151 offset:5120
	ds_read_b128 v[192:195], v151 offset:6144
	ds_read_b128 v[200:203], v151 offset:7168
	s_nop 0
	global_load_lds_dwordx4 v146, s[28:29]
	s_add_i32 m0, s48, 0xe000
	s_nop 0
	global_load_lds_dwordx4 v148, s[28:29]
	s_waitcnt vmcnt(8)
	s_waitcnt lgkmcnt(0)
	s_barrier
	s_setprio 1
	s_waitcnt lgkmcnt(0)
	v_mfma_f32_16x16x32_bf16 v[124:127], v[128:131], v[168:171], v[124:127]
	v_mfma_f32_16x16x32_bf16 v[124:127], v[132:135], v[172:175], v[124:127]
	v_mfma_f32_16x16x32_bf16 v[108:111], v[128:131], v[176:179], v[108:111]
	v_mfma_f32_16x16x32_bf16 v[108:111], v[132:135], v[180:183], v[108:111]
	v_mfma_f32_16x16x32_bf16 v[96:99], v[128:131], v[184:187], v[96:99]
	v_mfma_f32_16x16x32_bf16 v[96:99], v[132:135], v[188:191], v[96:99]
	v_mfma_f32_16x16x32_bf16 v[80:83], v[128:131], v[192:195], v[80:83]
	v_mfma_f32_16x16x32_bf16 v[80:83], v[132:135], v[200:203], v[80:83]
	v_mfma_f32_16x16x32_bf16 v[120:123], v[136:139], v[168:171], v[120:123]
	v_mfma_f32_16x16x32_bf16 v[120:123], v[140:143], v[172:175], v[120:123]
	v_mfma_f32_16x16x32_bf16 v[104:107], v[136:139], v[176:179], v[104:107]
	v_mfma_f32_16x16x32_bf16 v[104:107], v[140:143], v[180:183], v[104:107]
	v_mfma_f32_16x16x32_bf16 v[88:91], v[136:139], v[184:187], v[88:91]
	v_mfma_f32_16x16x32_bf16 v[88:91], v[140:143], v[188:191], v[88:91]
	v_mfma_f32_16x16x32_bf16 v[72:75], v[136:139], v[192:195], v[72:75]
	v_mfma_f32_16x16x32_bf16 v[72:75], v[140:143], v[200:203], v[72:75]
	s_setprio 0
	s_setprio 1
	v_mfma_f32_16x16x32_bf16 v[116:119], v[152:155], v[168:171], v[116:119]
	v_mfma_f32_16x16x32_bf16 v[116:119], v[156:159], v[172:175], v[116:119]
	v_mfma_f32_16x16x32_bf16 v[100:103], v[152:155], v[176:179], v[100:103]
	v_mfma_f32_16x16x32_bf16 v[100:103], v[156:159], v[180:183], v[100:103]
	v_mfma_f32_16x16x32_bf16 v[84:87], v[152:155], v[184:187], v[84:87]
	v_mfma_f32_16x16x32_bf16 v[84:87], v[156:159], v[188:191], v[84:87]
	v_mfma_f32_16x16x32_bf16 v[68:71], v[152:155], v[192:195], v[68:71]
	v_mfma_f32_16x16x32_bf16 v[68:71], v[156:159], v[200:203], v[68:71]
	v_mfma_f32_16x16x32_bf16 v[112:115], v[160:163], v[168:171], v[112:115]
	v_mfma_f32_16x16x32_bf16 v[112:115], v[164:167], v[172:175], v[112:115]
	v_mfma_f32_16x16x32_bf16 v[92:95], v[160:163], v[176:179], v[92:95]
	v_mfma_f32_16x16x32_bf16 v[92:95], v[164:167], v[180:183], v[92:95]
	v_mfma_f32_16x16x32_bf16 v[76:79], v[160:163], v[184:187], v[76:79]
	v_mfma_f32_16x16x32_bf16 v[76:79], v[164:167], v[188:191], v[76:79]
	v_mfma_f32_16x16x32_bf16 v[64:67], v[160:163], v[192:195], v[64:67]
	v_mfma_f32_16x16x32_bf16 v[64:67], v[164:167], v[200:203], v[64:67]
	s_setprio 0
	s_barrier
	s_add_i32 s74, s74, s97
	s_mov_b64 s[28:29], s[36:37]
	s_mov_b32 m0, s74
	ds_read_b128 v[168:171], v151 offset:16384
	ds_read_b128 v[172:175], v151 offset:17408
	ds_read_b128 v[176:179], v151 offset:18432
	ds_read_b128 v[180:183], v151 offset:19456
	ds_read_b128 v[184:187], v151 offset:20480
	ds_read_b128 v[188:191], v151 offset:21504
	ds_read_b128 v[192:195], v151 offset:22528
	ds_read_b128 v[200:203], v151 offset:23552
	s_nop 0
	global_load_lds_dwordx4 v147, s[28:29]
	s_add_i32 m0, s74, 0x2000
	s_nop 0
	global_load_lds_dwordx4 v149, s[28:29]
	s_add_u32 s28, s36, 0x80000
	s_addc_u32 s29, s37, 0
	s_add_i32 s74, s84, s97
	s_mov_b32 m0, s74
	s_nop 0
	global_load_lds_dwordx4 v147, s[28:29]
	s_add_i32 m0, s74, 0x2000
	s_nop 0
	global_load_lds_dwordx4 v149, s[28:29]
	s_mov_b64 s[28:29], s[38:39]
	s_mov_b32 m0, s48
	s_nop 0
	global_load_lds_dwordx4 v146, s[28:29]
	s_mov_b32 m0, s49
	s_nop 0
	global_load_lds_dwordx4 v148, s[28:29]
	s_waitcnt vmcnt(8)
	s_waitcnt lgkmcnt(0)
	s_barrier
	s_setprio 1
	s_waitcnt lgkmcnt(0)
	v_mfma_f32_16x16x32_bf16 v[60:63], v[128:131], v[168:171], v[60:63]
	v_mfma_f32_16x16x32_bf16 v[60:63], v[132:135], v[172:175], v[60:63]
	v_mfma_f32_16x16x32_bf16 v[48:51], v[128:131], v[176:179], v[48:51]
	v_mfma_f32_16x16x32_bf16 v[48:51], v[132:135], v[180:183], v[48:51]
	v_mfma_f32_16x16x32_bf16 v[32:35], v[128:131], v[184:187], v[32:35]
	v_mfma_f32_16x16x32_bf16 v[32:35], v[132:135], v[188:191], v[32:35]
	v_mfma_f32_16x16x32_bf16 v[16:19], v[128:131], v[192:195], v[16:19]
	v_mfma_f32_16x16x32_bf16 v[16:19], v[132:135], v[200:203], v[16:19]
	v_mfma_f32_16x16x32_bf16 v[56:59], v[136:139], v[168:171], v[56:59]
	v_mfma_f32_16x16x32_bf16 v[56:59], v[140:143], v[172:175], v[56:59]
	v_mfma_f32_16x16x32_bf16 v[40:43], v[136:139], v[176:179], v[40:43]
	v_mfma_f32_16x16x32_bf16 v[40:43], v[140:143], v[180:183], v[40:43]
	v_mfma_f32_16x16x32_bf16 v[24:27], v[136:139], v[184:187], v[24:27]
	v_mfma_f32_16x16x32_bf16 v[24:27], v[140:143], v[188:191], v[24:27]
	v_mfma_f32_16x16x32_bf16 v[8:11], v[136:139], v[192:195], v[8:11]
	v_mfma_f32_16x16x32_bf16 v[8:11], v[140:143], v[200:203], v[8:11]
	s_setprio 0
	s_setprio 1
	v_mfma_f32_16x16x32_bf16 v[52:55], v[152:155], v[168:171], v[52:55]
	v_mfma_f32_16x16x32_bf16 v[52:55], v[156:159], v[172:175], v[52:55]
	v_mfma_f32_16x16x32_bf16 v[36:39], v[152:155], v[176:179], v[36:39]
	v_mfma_f32_16x16x32_bf16 v[36:39], v[156:159], v[180:183], v[36:39]
	v_mfma_f32_16x16x32_bf16 v[20:23], v[152:155], v[184:187], v[20:23]
	v_mfma_f32_16x16x32_bf16 v[20:23], v[156:159], v[188:191], v[20:23]
	v_mfma_f32_16x16x32_bf16 v[4:7], v[152:155], v[192:195], v[4:7]
	v_mfma_f32_16x16x32_bf16 v[4:7], v[156:159], v[200:203], v[4:7]
	v_mfma_f32_16x16x32_bf16 v[44:47], v[160:163], v[168:171], v[44:47]
	v_mfma_f32_16x16x32_bf16 v[44:47], v[164:167], v[172:175], v[44:47]
	v_mfma_f32_16x16x32_bf16 v[28:31], v[160:163], v[176:179], v[28:31]
	v_mfma_f32_16x16x32_bf16 v[28:31], v[164:167], v[180:183], v[28:31]
	v_mfma_f32_16x16x32_bf16 v[12:15], v[160:163], v[184:187], v[12:15]
	v_mfma_f32_16x16x32_bf16 v[12:15], v[164:167], v[188:191], v[12:15]
	v_mfma_f32_16x16x32_bf16 v[0:3], v[160:163], v[192:195], v[0:3]
	v_mfma_f32_16x16x32_bf16 v[0:3], v[164:167], v[200:203], v[0:3]
	s_setprio 0
	s_barrier
	s_add_i32 s74, 0, 0x18000
	s_add_i32 s84, 0, 0x1c000
	v_add_u32_e32 v140, s74, v150
	v_add_u32_e32 v144, s84, v150
	ds_read_b128 v[128:131], v140
	ds_read_b128 v[132:135], v140 offset:1024
	ds_read_b128 v[136:139], v140 offset:2048
	ds_read_b128 v[140:143], v140 offset:3072
	ds_read_b128 v[152:155], v144
	ds_read_b128 v[156:159], v144 offset:1024
	ds_read_b128 v[160:163], v144 offset:2048
	ds_read_b128 v[164:167], v144 offset:3072
	s_add_u32 s28, s38, 0x80000
	s_addc_u32 s29, s39, 0
	s_mov_b32 m0, s56
	ds_read_b128 v[168:171], v151 offset:32768
	ds_read_b128 v[172:175], v151 offset:33792
	ds_read_b128 v[176:179], v151 offset:34816
	ds_read_b128 v[180:183], v151 offset:35840
	ds_read_b128 v[184:187], v151 offset:36864
	ds_read_b128 v[188:191], v151 offset:37888
	ds_read_b128 v[192:195], v151 offset:38912
	ds_read_b128 v[200:203], v151 offset:39936
	s_nop 0
	global_load_lds_dwordx4 v146, s[28:29]
	s_mov_b32 m0, s57
	s_nop 0
	global_load_lds_dwordx4 v148, s[28:29]
	s_waitcnt vmcnt(8)
	s_waitcnt lgkmcnt(0)
	s_barrier
	s_setprio 1
	s_waitcnt lgkmcnt(0)
	v_mfma_f32_16x16x32_bf16 v[124:127], v[128:131], v[168:171], v[124:127]
	v_mfma_f32_16x16x32_bf16 v[124:127], v[132:135], v[172:175], v[124:127]
	v_mfma_f32_16x16x32_bf16 v[108:111], v[128:131], v[176:179], v[108:111]
	v_mfma_f32_16x16x32_bf16 v[108:111], v[132:135], v[180:183], v[108:111]
	v_mfma_f32_16x16x32_bf16 v[96:99], v[128:131], v[184:187], v[96:99]
	v_mfma_f32_16x16x32_bf16 v[96:99], v[132:135], v[188:191], v[96:99]
	v_mfma_f32_16x16x32_bf16 v[80:83], v[128:131], v[192:195], v[80:83]
	v_mfma_f32_16x16x32_bf16 v[80:83], v[132:135], v[200:203], v[80:83]
	v_mfma_f32_16x16x32_bf16 v[120:123], v[136:139], v[168:171], v[120:123]
	v_mfma_f32_16x16x32_bf16 v[120:123], v[140:143], v[172:175], v[120:123]
	v_mfma_f32_16x16x32_bf16 v[104:107], v[136:139], v[176:179], v[104:107]
	v_mfma_f32_16x16x32_bf16 v[104:107], v[140:143], v[180:183], v[104:107]
	v_mfma_f32_16x16x32_bf16 v[88:91], v[136:139], v[184:187], v[88:91]
	v_mfma_f32_16x16x32_bf16 v[88:91], v[140:143], v[188:191], v[88:91]
	v_mfma_f32_16x16x32_bf16 v[72:75], v[136:139], v[192:195], v[72:75]
	v_mfma_f32_16x16x32_bf16 v[72:75], v[140:143], v[200:203], v[72:75]
	s_setprio 0
	s_setprio 1
	v_mfma_f32_16x16x32_bf16 v[116:119], v[152:155], v[168:171], v[116:119]
	v_mfma_f32_16x16x32_bf16 v[116:119], v[156:159], v[172:175], v[116:119]
	v_mfma_f32_16x16x32_bf16 v[100:103], v[152:155], v[176:179], v[100:103]
	v_mfma_f32_16x16x32_bf16 v[100:103], v[156:159], v[180:183], v[100:103]
	v_mfma_f32_16x16x32_bf16 v[84:87], v[152:155], v[184:187], v[84:87]
	v_mfma_f32_16x16x32_bf16 v[84:87], v[156:159], v[188:191], v[84:87]
	v_mfma_f32_16x16x32_bf16 v[68:71], v[152:155], v[192:195], v[68:71]
	v_mfma_f32_16x16x32_bf16 v[68:71], v[156:159], v[200:203], v[68:71]
	v_mfma_f32_16x16x32_bf16 v[112:115], v[160:163], v[168:171], v[112:115]
	v_mfma_f32_16x16x32_bf16 v[112:115], v[164:167], v[172:175], v[112:115]
	v_mfma_f32_16x16x32_bf16 v[92:95], v[160:163], v[176:179], v[92:95]
	v_mfma_f32_16x16x32_bf16 v[92:95], v[164:167], v[180:183], v[92:95]
	v_mfma_f32_16x16x32_bf16 v[76:79], v[160:163], v[184:187], v[76:79]
	v_mfma_f32_16x16x32_bf16 v[76:79], v[164:167], v[188:191], v[76:79]
	v_mfma_f32_16x16x32_bf16 v[64:67], v[160:163], v[192:195], v[64:67]
	v_mfma_f32_16x16x32_bf16 v[64:67], v[164:167], v[200:203], v[64:67]
	s_setprio 0
	s_barrier
	s_add_u32 s28, s36, 0x80
	s_addc_u32 s29, s37, 0
	s_add_i32 s38, s74, s97
	s_mov_b32 m0, s38
	ds_read_b128 v[168:171], v151 offset:49152
	ds_read_b128 v[172:175], v151 offset:50176
	ds_read_b128 v[176:179], v151 offset:51200
	ds_read_b128 v[180:183], v151 offset:52224
	ds_read_b128 v[184:187], v151 offset:53248
	ds_read_b128 v[188:191], v151 offset:54272
	ds_read_b128 v[192:195], v151 offset:55296
	ds_read_b128 v[200:203], v151 offset:56320
	s_nop 0
	global_load_lds_dwordx4 v147, s[28:29]
	s_add_i32 m0, s38, 0x2000
	s_nop 0
	global_load_lds_dwordx4 v149, s[28:29]
	s_add_u32 s28, s36, 0x80080
	s_addc_u32 s29, s37, 0
	s_add_i32 s36, s84, s97
	s_mov_b32 m0, s36
	s_nop 0
	global_load_lds_dwordx4 v147, s[28:29]
	s_add_i32 m0, s36, 0x2000
	s_nop 0
	global_load_lds_dwordx4 v149, s[28:29]
	s_mov_b32 m0, s82
	s_nop 0
	global_load_lds_dwordx4 v146, s[34:35]
	s_mov_b32 m0, s83
	s_nop 0
	global_load_lds_dwordx4 v148, s[34:35]
	s_waitcnt vmcnt(8)
	s_waitcnt lgkmcnt(0)
	s_barrier
	s_setprio 1
	s_waitcnt lgkmcnt(0)
	v_mfma_f32_16x16x32_bf16 v[60:63], v[128:131], v[168:171], v[60:63]
	v_mfma_f32_16x16x32_bf16 v[60:63], v[132:135], v[172:175], v[60:63]
	v_mfma_f32_16x16x32_bf16 v[48:51], v[128:131], v[176:179], v[48:51]
	v_mfma_f32_16x16x32_bf16 v[48:51], v[132:135], v[180:183], v[48:51]
	v_mfma_f32_16x16x32_bf16 v[32:35], v[128:131], v[184:187], v[32:35]
	v_mfma_f32_16x16x32_bf16 v[32:35], v[132:135], v[188:191], v[32:35]
	v_mfma_f32_16x16x32_bf16 v[16:19], v[128:131], v[192:195], v[16:19]
	v_mfma_f32_16x16x32_bf16 v[16:19], v[132:135], v[200:203], v[16:19]
	v_mfma_f32_16x16x32_bf16 v[56:59], v[136:139], v[168:171], v[56:59]
	v_mfma_f32_16x16x32_bf16 v[56:59], v[140:143], v[172:175], v[56:59]
	v_mfma_f32_16x16x32_bf16 v[40:43], v[136:139], v[176:179], v[40:43]
	v_mfma_f32_16x16x32_bf16 v[40:43], v[140:143], v[180:183], v[40:43]
	v_mfma_f32_16x16x32_bf16 v[24:27], v[136:139], v[184:187], v[24:27]
	v_mfma_f32_16x16x32_bf16 v[24:27], v[140:143], v[188:191], v[24:27]
	v_mfma_f32_16x16x32_bf16 v[8:11], v[136:139], v[192:195], v[8:11]
	v_mfma_f32_16x16x32_bf16 v[8:11], v[140:143], v[200:203], v[8:11]
	s_setprio 0
	s_setprio 1
	v_mfma_f32_16x16x32_bf16 v[52:55], v[152:155], v[168:171], v[52:55]
	v_mfma_f32_16x16x32_bf16 v[52:55], v[156:159], v[172:175], v[52:55]
	v_mfma_f32_16x16x32_bf16 v[36:39], v[152:155], v[176:179], v[36:39]
	v_mfma_f32_16x16x32_bf16 v[36:39], v[156:159], v[180:183], v[36:39]
	v_mfma_f32_16x16x32_bf16 v[20:23], v[152:155], v[184:187], v[20:23]
	v_mfma_f32_16x16x32_bf16 v[20:23], v[156:159], v[188:191], v[20:23]
	v_mfma_f32_16x16x32_bf16 v[4:7], v[152:155], v[192:195], v[4:7]
	v_mfma_f32_16x16x32_bf16 v[4:7], v[156:159], v[200:203], v[4:7]
	v_mfma_f32_16x16x32_bf16 v[44:47], v[160:163], v[168:171], v[44:47]
	v_mfma_f32_16x16x32_bf16 v[44:47], v[164:167], v[172:175], v[44:47]
	v_mfma_f32_16x16x32_bf16 v[28:31], v[160:163], v[176:179], v[28:31]
	v_mfma_f32_16x16x32_bf16 v[28:31], v[164:167], v[180:183], v[28:31]
	v_mfma_f32_16x16x32_bf16 v[12:15], v[160:163], v[184:187], v[12:15]
	v_mfma_f32_16x16x32_bf16 v[12:15], v[164:167], v[188:191], v[12:15]
	v_mfma_f32_16x16x32_bf16 v[0:3], v[160:163], v[192:195], v[0:3]
	v_mfma_f32_16x16x32_bf16 v[0:3], v[164:167], v[200:203], v[0:3]
	s_setprio 0
	s_barrier
	s_add_i32 s69, s69, 2
	s_add_u32 s21, s21, 0x100
	s_addc_u32 s27, s27, 0
	s_cmp_gt_u32 s69, 29
	s_mov_b64 s[28:29], s[30:31]
	s_cbranch_scc0 .LBB0_676
	s_and_b64 vcc, exec, s[60:61]
	s_cbranch_vccz .LBB0_679
	s_barrier

.LBB0_788:
	s_add_u32 s30, s28, 0x100
	s_addc_u32 s31, s29, 0
	s_cmp_eq_u32 s17, 4
	s_cselect_b32 s38, s20, s30
	s_cselect_b32 s39, s21, s31
	s_cselect_b32 s36, s22, s5
	s_cselect_b32 s37, s23, s15
	s_add_u32 s34, s38, 0x80
	s_addc_u32 s35, s39, 0
	s_add_i32 s83, 0, 0x10000
	s_add_i32 s84, 0, 0x14000
	v_add_u32_e32 v146, s83, v136
	v_add_u32_e32 v162, s84, v136
	ds_read_b128 v[128:131], v146
	ds_read_b128 v[138:141], v146 offset:1024
	ds_read_b128 v[142:145], v146 offset:2048
	ds_read_b128 v[146:149], v146 offset:3072
	ds_read_b128 v[150:153], v162
	ds_read_b128 v[154:157], v162 offset:1024
	ds_read_b128 v[158:161], v162 offset:2048
	ds_read_b128 v[162:165], v162 offset:3072
	s_add_u32 s28, s28, 0x20080
	s_addc_u32 s29, s29, 0
	s_add_i32 m0, s27, 0xc000
	ds_read_b128 v[166:169], v137
	ds_read_b128 v[170:173], v137 offset:1024
	ds_read_b128 v[174:177], v137 offset:2048
	ds_read_b128 v[178:181], v137 offset:3072
	ds_read_b128 v[182:185], v137 offset:4096
	ds_read_b128 v[186:189], v137 offset:5120
	ds_read_b128 v[190:193], v137 offset:6144
	ds_read_b128 v[200:203], v137 offset:7168
	s_nop 0
	global_load_lds_dwordx4 v132, s[28:29]
	s_add_i32 m0, s27, 0xe000
	s_nop 0
	global_load_lds_dwordx4 v134, s[28:29]
	s_waitcnt vmcnt(8)
	s_waitcnt lgkmcnt(0)
	s_barrier
	s_setprio 1
	s_waitcnt lgkmcnt(0)
	v_mfma_f32_16x16x32_bf16 v[124:127], v[128:131], v[166:169], v[124:127]
	v_mfma_f32_16x16x32_bf16 v[124:127], v[138:141], v[170:173], v[124:127]
	v_mfma_f32_16x16x32_bf16 v[108:111], v[128:131], v[174:177], v[108:111]
	v_mfma_f32_16x16x32_bf16 v[108:111], v[138:141], v[178:181], v[108:111]
	v_mfma_f32_16x16x32_bf16 v[92:95], v[128:131], v[182:185], v[92:95]
	v_mfma_f32_16x16x32_bf16 v[92:95], v[138:141], v[186:189], v[92:95]
	v_mfma_f32_16x16x32_bf16 v[76:79], v[128:131], v[190:193], v[76:79]
	v_mfma_f32_16x16x32_bf16 v[76:79], v[138:141], v[200:203], v[76:79]
	v_mfma_f32_16x16x32_bf16 v[120:123], v[142:145], v[166:169], v[120:123]
	v_mfma_f32_16x16x32_bf16 v[120:123], v[146:149], v[170:173], v[120:123]
	v_mfma_f32_16x16x32_bf16 v[104:107], v[142:145], v[174:177], v[104:107]
	v_mfma_f32_16x16x32_bf16 v[104:107], v[146:149], v[178:181], v[104:107]
	v_mfma_f32_16x16x32_bf16 v[88:91], v[142:145], v[182:185], v[88:91]
	v_mfma_f32_16x16x32_bf16 v[88:91], v[146:149], v[186:189], v[88:91]
	v_mfma_f32_16x16x32_bf16 v[72:75], v[142:145], v[190:193], v[72:75]
	v_mfma_f32_16x16x32_bf16 v[72:75], v[146:149], v[200:203], v[72:75]
	s_setprio 0
	s_setprio 1
	v_mfma_f32_16x16x32_bf16 v[116:119], v[150:153], v[166:169], v[116:119]
	v_mfma_f32_16x16x32_bf16 v[116:119], v[154:157], v[170:173], v[116:119]
	v_mfma_f32_16x16x32_bf16 v[100:103], v[150:153], v[174:177], v[100:103]
	v_mfma_f32_16x16x32_bf16 v[100:103], v[154:157], v[178:181], v[100:103]
	v_mfma_f32_16x16x32_bf16 v[84:87], v[150:153], v[182:185], v[84:87]
	v_mfma_f32_16x16x32_bf16 v[84:87], v[154:157], v[186:189], v[84:87]
	v_mfma_f32_16x16x32_bf16 v[68:71], v[150:153], v[190:193], v[68:71]
	v_mfma_f32_16x16x32_bf16 v[68:71], v[154:157], v[200:203], v[68:71]
	v_mfma_f32_16x16x32_bf16 v[112:115], v[158:161], v[166:169], v[112:115]
	v_mfma_f32_16x16x32_bf16 v[112:115], v[162:165], v[170:173], v[112:115]
	v_mfma_f32_16x16x32_bf16 v[96:99], v[158:161], v[174:177], v[96:99]
	v_mfma_f32_16x16x32_bf16 v[96:99], v[162:165], v[178:181], v[96:99]
	v_mfma_f32_16x16x32_bf16 v[80:83], v[158:161], v[182:185], v[80:83]
	v_mfma_f32_16x16x32_bf16 v[80:83], v[162:165], v[186:189], v[80:83]
	v_mfma_f32_16x16x32_bf16 v[64:67], v[158:161], v[190:193], v[64:67]
	v_mfma_f32_16x16x32_bf16 v[64:67], v[162:165], v[200:203], v[64:67]
	s_setprio 0
	s_barrier
	s_add_i32 s83, s83, s97
	s_mov_b64 s[28:29], s[36:37]
	s_mov_b32 m0, s83
	ds_read_b128 v[166:169], v137 offset:16384
	ds_read_b128 v[170:173], v137 offset:17408
	ds_read_b128 v[174:177], v137 offset:18432
	ds_read_b128 v[178:181], v137 offset:19456
	ds_read_b128 v[182:185], v137 offset:20480
	ds_read_b128 v[186:189], v137 offset:21504
	ds_read_b128 v[190:193], v137 offset:22528
	ds_read_b128 v[200:203], v137 offset:23552
	s_nop 0
	global_load_lds_dwordx4 v133, s[28:29]
	s_add_i32 m0, s83, 0x2000
	s_nop 0
	global_load_lds_dwordx4 v135, s[28:29]
	s_add_u32 s28, s36, 0x20000
	s_addc_u32 s29, s37, 0
	s_add_i32 s83, s84, s97
	s_mov_b32 m0, s83
	s_nop 0
	global_load_lds_dwordx4 v133, s[28:29]
	s_add_i32 m0, s83, 0x2000
	s_nop 0
	global_load_lds_dwordx4 v135, s[28:29]
	s_mov_b64 s[28:29], s[38:39]
	s_mov_b32 m0, s27
	s_nop 0
	global_load_lds_dwordx4 v132, s[28:29]
	s_mov_b32 m0, s69
	s_nop 0
	global_load_lds_dwordx4 v134, s[28:29]
	s_waitcnt vmcnt(8)
	s_waitcnt lgkmcnt(0)
	s_barrier
	s_setprio 1
	s_waitcnt lgkmcnt(0)
	v_mfma_f32_16x16x32_bf16 v[60:63], v[128:131], v[166:169], v[60:63]
	v_mfma_f32_16x16x32_bf16 v[60:63], v[138:141], v[170:173], v[60:63]
	v_mfma_f32_16x16x32_bf16 v[44:47], v[128:131], v[174:177], v[44:47]
	v_mfma_f32_16x16x32_bf16 v[44:47], v[138:141], v[178:181], v[44:47]
	v_mfma_f32_16x16x32_bf16 v[28:31], v[128:131], v[182:185], v[28:31]
	v_mfma_f32_16x16x32_bf16 v[28:31], v[138:141], v[186:189], v[28:31]
	v_mfma_f32_16x16x32_bf16 v[12:15], v[128:131], v[190:193], v[12:15]
	v_mfma_f32_16x16x32_bf16 v[12:15], v[138:141], v[200:203], v[12:15]
	v_mfma_f32_16x16x32_bf16 v[56:59], v[142:145], v[166:169], v[56:59]
	v_mfma_f32_16x16x32_bf16 v[56:59], v[146:149], v[170:173], v[56:59]
	v_mfma_f32_16x16x32_bf16 v[40:43], v[142:145], v[174:177], v[40:43]
	v_mfma_f32_16x16x32_bf16 v[40:43], v[146:149], v[178:181], v[40:43]
	v_mfma_f32_16x16x32_bf16 v[24:27], v[142:145], v[182:185], v[24:27]
	v_mfma_f32_16x16x32_bf16 v[24:27], v[146:149], v[186:189], v[24:27]
	v_mfma_f32_16x16x32_bf16 v[8:11], v[142:145], v[190:193], v[8:11]
	v_mfma_f32_16x16x32_bf16 v[8:11], v[146:149], v[200:203], v[8:11]
	s_setprio 0
	s_setprio 1
	v_mfma_f32_16x16x32_bf16 v[52:55], v[150:153], v[166:169], v[52:55]
	v_mfma_f32_16x16x32_bf16 v[52:55], v[154:157], v[170:173], v[52:55]
	v_mfma_f32_16x16x32_bf16 v[36:39], v[150:153], v[174:177], v[36:39]
	v_mfma_f32_16x16x32_bf16 v[36:39], v[154:157], v[178:181], v[36:39]
	v_mfma_f32_16x16x32_bf16 v[20:23], v[150:153], v[182:185], v[20:23]
	v_mfma_f32_16x16x32_bf16 v[20:23], v[154:157], v[186:189], v[20:23]
	v_mfma_f32_16x16x32_bf16 v[4:7], v[150:153], v[190:193], v[4:7]
	v_mfma_f32_16x16x32_bf16 v[4:7], v[154:157], v[200:203], v[4:7]
	v_mfma_f32_16x16x32_bf16 v[48:51], v[158:161], v[166:169], v[48:51]
	v_mfma_f32_16x16x32_bf16 v[48:51], v[162:165], v[170:173], v[48:51]
	v_mfma_f32_16x16x32_bf16 v[32:35], v[158:161], v[174:177], v[32:35]
	v_mfma_f32_16x16x32_bf16 v[32:35], v[162:165], v[178:181], v[32:35]
	v_mfma_f32_16x16x32_bf16 v[16:19], v[158:161], v[182:185], v[16:19]
	v_mfma_f32_16x16x32_bf16 v[16:19], v[162:165], v[186:189], v[16:19]
	v_mfma_f32_16x16x32_bf16 v[0:3], v[158:161], v[190:193], v[0:3]
	v_mfma_f32_16x16x32_bf16 v[0:3], v[162:165], v[200:203], v[0:3]
	s_setprio 0
	s_barrier
	s_add_i32 s83, 0, 0x18000
	s_add_i32 s84, 0, 0x1c000
	v_add_u32_e32 v146, s83, v136
	v_add_u32_e32 v162, s84, v136
	ds_read_b128 v[128:131], v146
	ds_read_b128 v[138:141], v146 offset:1024
	ds_read_b128 v[142:145], v146 offset:2048
	ds_read_b128 v[146:149], v146 offset:3072
	ds_read_b128 v[150:153], v162
	ds_read_b128 v[154:157], v162 offset:1024
	ds_read_b128 v[158:161], v162 offset:2048
	ds_read_b128 v[162:165], v162 offset:3072
	s_add_u32 s28, s38, 0x20000
	s_addc_u32 s29, s39, 0
	s_mov_b32 m0, s71
	ds_read_b128 v[166:169], v137 offset:32768
	ds_read_b128 v[170:173], v137 offset:33792
	ds_read_b128 v[174:177], v137 offset:34816
	ds_read_b128 v[178:181], v137 offset:35840
	ds_read_b128 v[182:185], v137 offset:36864
	ds_read_b128 v[186:189], v137 offset:37888
	ds_read_b128 v[190:193], v137 offset:38912
	ds_read_b128 v[200:203], v137 offset:39936
	s_nop 0
	global_load_lds_dwordx4 v132, s[28:29]
	s_mov_b32 m0, s72
	s_nop 0
	global_load_lds_dwordx4 v134, s[28:29]
	s_waitcnt vmcnt(8)
	s_waitcnt lgkmcnt(0)
	s_barrier
	s_setprio 1
	s_waitcnt lgkmcnt(0)
	v_mfma_f32_16x16x32_bf16 v[124:127], v[128:131], v[166:169], v[124:127]
	v_mfma_f32_16x16x32_bf16 v[124:127], v[138:141], v[170:173], v[124:127]
	v_mfma_f32_16x16x32_bf16 v[108:111], v[128:131], v[174:177], v[108:111]
	v_mfma_f32_16x16x32_bf16 v[108:111], v[138:141], v[178:181], v[108:111]
	v_mfma_f32_16x16x32_bf16 v[92:95], v[128:131], v[182:185], v[92:95]
	v_mfma_f32_16x16x32_bf16 v[92:95], v[138:141], v[186:189], v[92:95]
	v_mfma_f32_16x16x32_bf16 v[76:79], v[128:131], v[190:193], v[76:79]
	v_mfma_f32_16x16x32_bf16 v[76:79], v[138:141], v[200:203], v[76:79]
	v_mfma_f32_16x16x32_bf16 v[120:123], v[142:145], v[166:169], v[120:123]
	v_mfma_f32_16x16x32_bf16 v[120:123], v[146:149], v[170:173], v[120:123]
	v_mfma_f32_16x16x32_bf16 v[104:107], v[142:145], v[174:177], v[104:107]
	v_mfma_f32_16x16x32_bf16 v[104:107], v[146:149], v[178:181], v[104:107]
	v_mfma_f32_16x16x32_bf16 v[88:91], v[142:145], v[182:185], v[88:91]
	v_mfma_f32_16x16x32_bf16 v[88:91], v[146:149], v[186:189], v[88:91]
	v_mfma_f32_16x16x32_bf16 v[72:75], v[142:145], v[190:193], v[72:75]
	v_mfma_f32_16x16x32_bf16 v[72:75], v[146:149], v[200:203], v[72:75]
	s_setprio 0
	s_setprio 1
	v_mfma_f32_16x16x32_bf16 v[116:119], v[150:153], v[166:169], v[116:119]
	v_mfma_f32_16x16x32_bf16 v[116:119], v[154:157], v[170:173], v[116:119]
	v_mfma_f32_16x16x32_bf16 v[100:103], v[150:153], v[174:177], v[100:103]
	v_mfma_f32_16x16x32_bf16 v[100:103], v[154:157], v[178:181], v[100:103]
	v_mfma_f32_16x16x32_bf16 v[84:87], v[150:153], v[182:185], v[84:87]
	v_mfma_f32_16x16x32_bf16 v[84:87], v[154:157], v[186:189], v[84:87]
	v_mfma_f32_16x16x32_bf16 v[68:71], v[150:153], v[190:193], v[68:71]
	v_mfma_f32_16x16x32_bf16 v[68:71], v[154:157], v[200:203], v[68:71]
	v_mfma_f32_16x16x32_bf16 v[112:115], v[158:161], v[166:169], v[112:115]
	v_mfma_f32_16x16x32_bf16 v[112:115], v[162:165], v[170:173], v[112:115]
	v_mfma_f32_16x16x32_bf16 v[96:99], v[158:161], v[174:177], v[96:99]
	v_mfma_f32_16x16x32_bf16 v[96:99], v[162:165], v[178:181], v[96:99]
	v_mfma_f32_16x16x32_bf16 v[80:83], v[158:161], v[182:185], v[80:83]
	v_mfma_f32_16x16x32_bf16 v[80:83], v[162:165], v[186:189], v[80:83]
	v_mfma_f32_16x16x32_bf16 v[64:67], v[158:161], v[190:193], v[64:67]
	v_mfma_f32_16x16x32_bf16 v[64:67], v[162:165], v[200:203], v[64:67]
	s_setprio 0
	s_barrier
	s_add_u32 s28, s36, 0x80
	s_addc_u32 s29, s37, 0
	s_add_i32 s38, s83, s97
	s_mov_b32 m0, s38
	ds_read_b128 v[166:169], v137 offset:49152
	ds_read_b128 v[170:173], v137 offset:50176
	ds_read_b128 v[174:177], v137 offset:51200
	ds_read_b128 v[178:181], v137 offset:52224
	ds_read_b128 v[182:185], v137 offset:53248
	ds_read_b128 v[186:189], v137 offset:54272
	ds_read_b128 v[190:193], v137 offset:55296
	ds_read_b128 v[200:203], v137 offset:56320
	s_nop 0
	global_load_lds_dwordx4 v133, s[28:29]
	s_add_i32 m0, s38, 0x2000
	s_nop 0
	global_load_lds_dwordx4 v135, s[28:29]
	s_add_u32 s28, s36, 0x20080
	s_addc_u32 s29, s37, 0
	s_add_i32 s36, s84, s97
	s_mov_b32 m0, s36
	s_nop 0
	global_load_lds_dwordx4 v133, s[28:29]
	s_add_i32 m0, s36, 0x2000
	s_nop 0
	global_load_lds_dwordx4 v135, s[28:29]
	s_mov_b32 m0, s80
	s_nop 0
	global_load_lds_dwordx4 v132, s[34:35]
	s_mov_b32 m0, s81
	s_nop 0
	global_load_lds_dwordx4 v134, s[34:35]
	s_waitcnt vmcnt(8)
	s_waitcnt lgkmcnt(0)
	s_barrier
	s_setprio 1
	s_waitcnt lgkmcnt(0)
	v_mfma_f32_16x16x32_bf16 v[60:63], v[128:131], v[166:169], v[60:63]
	v_mfma_f32_16x16x32_bf16 v[60:63], v[138:141], v[170:173], v[60:63]
	v_mfma_f32_16x16x32_bf16 v[44:47], v[128:131], v[174:177], v[44:47]
	v_mfma_f32_16x16x32_bf16 v[44:47], v[138:141], v[178:181], v[44:47]
	v_mfma_f32_16x16x32_bf16 v[28:31], v[128:131], v[182:185], v[28:31]
	v_mfma_f32_16x16x32_bf16 v[28:31], v[138:141], v[186:189], v[28:31]
	v_mfma_f32_16x16x32_bf16 v[12:15], v[128:131], v[190:193], v[12:15]
	v_mfma_f32_16x16x32_bf16 v[12:15], v[138:141], v[200:203], v[12:15]
	v_mfma_f32_16x16x32_bf16 v[56:59], v[142:145], v[166:169], v[56:59]
	v_mfma_f32_16x16x32_bf16 v[56:59], v[146:149], v[170:173], v[56:59]
	v_mfma_f32_16x16x32_bf16 v[40:43], v[142:145], v[174:177], v[40:43]
	v_mfma_f32_16x16x32_bf16 v[40:43], v[146:149], v[178:181], v[40:43]
	v_mfma_f32_16x16x32_bf16 v[24:27], v[142:145], v[182:185], v[24:27]
	v_mfma_f32_16x16x32_bf16 v[24:27], v[146:149], v[186:189], v[24:27]
	v_mfma_f32_16x16x32_bf16 v[8:11], v[142:145], v[190:193], v[8:11]
	v_mfma_f32_16x16x32_bf16 v[8:11], v[146:149], v[200:203], v[8:11]
	s_setprio 0
	s_setprio 1
	v_mfma_f32_16x16x32_bf16 v[52:55], v[150:153], v[166:169], v[52:55]
	v_mfma_f32_16x16x32_bf16 v[52:55], v[154:157], v[170:173], v[52:55]
	v_mfma_f32_16x16x32_bf16 v[36:39], v[150:153], v[174:177], v[36:39]
	v_mfma_f32_16x16x32_bf16 v[36:39], v[154:157], v[178:181], v[36:39]
	v_mfma_f32_16x16x32_bf16 v[20:23], v[150:153], v[182:185], v[20:23]
	v_mfma_f32_16x16x32_bf16 v[20:23], v[154:157], v[186:189], v[20:23]
	v_mfma_f32_16x16x32_bf16 v[4:7], v[150:153], v[190:193], v[4:7]
	v_mfma_f32_16x16x32_bf16 v[4:7], v[154:157], v[200:203], v[4:7]
	v_mfma_f32_16x16x32_bf16 v[48:51], v[158:161], v[166:169], v[48:51]
	v_mfma_f32_16x16x32_bf16 v[48:51], v[162:165], v[170:173], v[48:51]
	v_mfma_f32_16x16x32_bf16 v[32:35], v[158:161], v[174:177], v[32:35]
	v_mfma_f32_16x16x32_bf16 v[32:35], v[162:165], v[178:181], v[32:35]
	v_mfma_f32_16x16x32_bf16 v[16:19], v[158:161], v[182:185], v[16:19]
	v_mfma_f32_16x16x32_bf16 v[16:19], v[162:165], v[186:189], v[16:19]
	v_mfma_f32_16x16x32_bf16 v[0:3], v[158:161], v[190:193], v[0:3]
	v_mfma_f32_16x16x32_bf16 v[0:3], v[162:165], v[200:203], v[0:3]
	s_setprio 0
	s_barrier
	s_add_i32 s17, s17, 2
	s_add_u32 s5, s5, 0x100
	s_addc_u32 s15, s15, 0
	s_cmp_gt_u32 s17, 5
	s_mov_b64 s[28:29], s[30:31]
	s_cbranch_scc0 .LBB0_788
	s_and_b64 vcc, exec, s[60:61]
	s_cbranch_vccz .LBB0_791
	s_barrier

.LBB0_1050:
	s_cmp_eq_u32 s83, 28
	s_cselect_b32 s56, s5, s39
	s_cselect_b32 s57, s4, s69
	s_cselect_b32 s84, s37, s72
	s_cselect_b32 s85, s11, s74
	s_add_u32 s12, s56, 0x80
	s_addc_u32 s13, s57, 0
	s_add_i32 vcc_lo, 0, 0x10000
	s_add_i32 vcc_hi, 0, 0x14000
	v_add_u32_e32 v136, vcc_lo, v184
	v_add_u32_e32 v156, vcc_hi, v184
	ds_read_b128 v[104:107], v136
	ds_read_b128 v[108:111], v136 offset:1024
	ds_read_b128 v[132:135], v136 offset:2048
	ds_read_b128 v[136:139], v136 offset:3072
	ds_read_b128 v[144:147], v156
	ds_read_b128 v[148:151], v156 offset:1024
	ds_read_b128 v[152:155], v156 offset:2048
	ds_read_b128 v[156:159], v156 offset:3072
	s_mov_b64 s[86:87], s[8:9]
	s_add_i32 m0, s92, 0xc000
	ds_read_b128 v[160:163], v185
	ds_read_b128 v[164:167], v185 offset:1024
	ds_read_b128 v[168:171], v185 offset:2048
	ds_read_b128 v[172:175], v185 offset:3072
	ds_read_b128 v[186:189], v185 offset:4096
	ds_read_b128 v[190:193], v185 offset:5120
	ds_read_b128 v[200:203], v185 offset:6144
	ds_read_b128 v[204:207], v185 offset:7168
	s_nop 0
	global_load_lds_dwordx4 v179, s[86:87]
	s_add_i32 m0, s92, 0xe000
	s_nop 0
	global_load_lds_dwordx4 v182, s[86:87]
	s_waitcnt vmcnt(8)
	s_waitcnt lgkmcnt(0)
	s_barrier
	s_setprio 1
	s_waitcnt lgkmcnt(0)
	v_mfma_f32_16x16x32_bf16 v[140:143], v[104:107], v[160:163], v[140:143]
	v_mfma_f32_16x16x32_bf16 v[140:143], v[108:111], v[164:167], v[140:143]
	v_mfma_f32_16x16x32_bf16 v[124:127], v[104:107], v[168:171], v[124:127]
	v_mfma_f32_16x16x32_bf16 v[124:127], v[108:111], v[172:175], v[124:127]
	v_mfma_f32_16x16x32_bf16 v[96:99], v[104:107], v[186:189], v[96:99]
	v_mfma_f32_16x16x32_bf16 v[96:99], v[108:111], v[190:193], v[96:99]
	v_mfma_f32_16x16x32_bf16 v[84:87], v[104:107], v[200:203], v[84:87]
	v_mfma_f32_16x16x32_bf16 v[84:87], v[108:111], v[204:207], v[84:87]
	v_mfma_f32_16x16x32_bf16 v[128:131], v[132:135], v[160:163], v[128:131]
	v_mfma_f32_16x16x32_bf16 v[128:131], v[136:139], v[164:167], v[128:131]
	v_mfma_f32_16x16x32_bf16 v[112:115], v[132:135], v[168:171], v[112:115]
	v_mfma_f32_16x16x32_bf16 v[112:115], v[136:139], v[172:175], v[112:115]
	v_mfma_f32_16x16x32_bf16 v[88:91], v[132:135], v[186:189], v[88:91]
	v_mfma_f32_16x16x32_bf16 v[88:91], v[136:139], v[190:193], v[88:91]
	v_mfma_f32_16x16x32_bf16 v[72:75], v[132:135], v[200:203], v[72:75]
	v_mfma_f32_16x16x32_bf16 v[72:75], v[136:139], v[204:207], v[72:75]
	s_setprio 0
	s_setprio 1
	v_mfma_f32_16x16x32_bf16 v[120:123], v[144:147], v[160:163], v[120:123]
	v_mfma_f32_16x16x32_bf16 v[120:123], v[148:151], v[164:167], v[120:123]
	v_mfma_f32_16x16x32_bf16 v[100:103], v[144:147], v[168:171], v[100:103]
	v_mfma_f32_16x16x32_bf16 v[100:103], v[148:151], v[172:175], v[100:103]
	v_mfma_f32_16x16x32_bf16 v[80:83], v[144:147], v[186:189], v[80:83]
	v_mfma_f32_16x16x32_bf16 v[80:83], v[148:151], v[190:193], v[80:83]
	v_mfma_f32_16x16x32_bf16 v[68:71], v[144:147], v[200:203], v[68:71]
	v_mfma_f32_16x16x32_bf16 v[68:71], v[148:151], v[204:207], v[68:71]
	v_mfma_f32_16x16x32_bf16 v[116:119], v[152:155], v[160:163], v[116:119]
	v_mfma_f32_16x16x32_bf16 v[116:119], v[156:159], v[164:167], v[116:119]
	v_mfma_f32_16x16x32_bf16 v[92:95], v[152:155], v[168:171], v[92:95]
	v_mfma_f32_16x16x32_bf16 v[92:95], v[156:159], v[172:175], v[92:95]
	v_mfma_f32_16x16x32_bf16 v[76:79], v[152:155], v[186:189], v[76:79]
	v_mfma_f32_16x16x32_bf16 v[76:79], v[156:159], v[190:193], v[76:79]
	v_mfma_f32_16x16x32_bf16 v[64:67], v[152:155], v[200:203], v[64:67]
	v_mfma_f32_16x16x32_bf16 v[64:67], v[156:159], v[204:207], v[64:67]
	s_setprio 0
	s_barrier
	s_add_i32 vcc_lo, vcc_lo, s97
	s_mov_b64 s[86:87], s[84:85]
	s_mov_b32 m0, vcc_lo
	ds_read_b128 v[160:163], v185 offset:16384
	ds_read_b128 v[164:167], v185 offset:17408
	ds_read_b128 v[168:171], v185 offset:18432
	ds_read_b128 v[172:175], v185 offset:19456
	ds_read_b128 v[186:189], v185 offset:20480
	ds_read_b128 v[190:193], v185 offset:21504
	ds_read_b128 v[200:203], v185 offset:22528
	ds_read_b128 v[204:207], v185 offset:23552
	s_nop 0
	global_load_lds_dwordx4 v181, s[86:87]
	s_add_i32 m0, vcc_lo, 0x2000
	s_nop 0
	global_load_lds_dwordx4 v183, s[86:87]
	s_add_u32 s86, s84, 0x80000
	s_addc_u32 s87, s85, 0
	s_add_i32 vcc_lo, vcc_hi, s97
	s_mov_b32 m0, vcc_lo
	s_nop 0
	global_load_lds_dwordx4 v181, s[86:87]
	s_add_i32 m0, vcc_lo, 0x2000
	s_nop 0
	global_load_lds_dwordx4 v183, s[86:87]
	s_mov_b64 s[86:87], s[56:57]
	s_mov_b32 m0, s92
	s_nop 0
	global_load_lds_dwordx4 v179, s[86:87]
	s_mov_b32 m0, s93
	s_nop 0
	global_load_lds_dwordx4 v182, s[86:87]
	s_waitcnt vmcnt(8)
	s_waitcnt lgkmcnt(0)
	s_barrier
	s_setprio 1
	s_waitcnt lgkmcnt(0)
	v_mfma_f32_16x16x32_bf16 v[60:63], v[104:107], v[160:163], v[60:63]
	v_mfma_f32_16x16x32_bf16 v[60:63], v[108:111], v[164:167], v[60:63]
	v_mfma_f32_16x16x32_bf16 v[48:51], v[104:107], v[168:171], v[48:51]
	v_mfma_f32_16x16x32_bf16 v[48:51], v[108:111], v[172:175], v[48:51]
	v_mfma_f32_16x16x32_bf16 v[32:35], v[104:107], v[186:189], v[32:35]
	v_mfma_f32_16x16x32_bf16 v[32:35], v[108:111], v[190:193], v[32:35]
	v_mfma_f32_16x16x32_bf16 v[16:19], v[104:107], v[200:203], v[16:19]
	v_mfma_f32_16x16x32_bf16 v[16:19], v[108:111], v[204:207], v[16:19]
	v_mfma_f32_16x16x32_bf16 v[56:59], v[132:135], v[160:163], v[56:59]
	v_mfma_f32_16x16x32_bf16 v[56:59], v[136:139], v[164:167], v[56:59]
	v_mfma_f32_16x16x32_bf16 v[40:43], v[132:135], v[168:171], v[40:43]
	v_mfma_f32_16x16x32_bf16 v[40:43], v[136:139], v[172:175], v[40:43]
	v_mfma_f32_16x16x32_bf16 v[24:27], v[132:135], v[186:189], v[24:27]
	v_mfma_f32_16x16x32_bf16 v[24:27], v[136:139], v[190:193], v[24:27]
	v_mfma_f32_16x16x32_bf16 v[8:11], v[132:135], v[200:203], v[8:11]
	v_mfma_f32_16x16x32_bf16 v[8:11], v[136:139], v[204:207], v[8:11]
	s_setprio 0
	s_setprio 1
	v_mfma_f32_16x16x32_bf16 v[52:55], v[144:147], v[160:163], v[52:55]
	v_mfma_f32_16x16x32_bf16 v[52:55], v[148:151], v[164:167], v[52:55]
	v_mfma_f32_16x16x32_bf16 v[36:39], v[144:147], v[168:171], v[36:39]
	v_mfma_f32_16x16x32_bf16 v[36:39], v[148:151], v[172:175], v[36:39]
	v_mfma_f32_16x16x32_bf16 v[20:23], v[144:147], v[186:189], v[20:23]
	v_mfma_f32_16x16x32_bf16 v[20:23], v[148:151], v[190:193], v[20:23]
	v_mfma_f32_16x16x32_bf16 v[4:7], v[144:147], v[200:203], v[4:7]
	v_mfma_f32_16x16x32_bf16 v[4:7], v[148:151], v[204:207], v[4:7]
	v_mfma_f32_16x16x32_bf16 v[44:47], v[152:155], v[160:163], v[44:47]
	v_mfma_f32_16x16x32_bf16 v[44:47], v[156:159], v[164:167], v[44:47]
	v_mfma_f32_16x16x32_bf16 v[28:31], v[152:155], v[168:171], v[28:31]
	v_mfma_f32_16x16x32_bf16 v[28:31], v[156:159], v[172:175], v[28:31]
	v_mfma_f32_16x16x32_bf16 v[12:15], v[152:155], v[186:189], v[12:15]
	v_mfma_f32_16x16x32_bf16 v[12:15], v[156:159], v[190:193], v[12:15]
	v_mfma_f32_16x16x32_bf16 v[0:3], v[152:155], v[200:203], v[0:3]
	v_mfma_f32_16x16x32_bf16 v[0:3], v[156:159], v[204:207], v[0:3]
	s_setprio 0
	s_barrier
	s_add_i32 s86, 0, 0x18000
	s_add_i32 s87, 0, 0x1c000
	v_add_u32_e32 v136, s86, v184
	v_add_u32_e32 v156, s87, v184
	ds_read_b128 v[104:107], v136
	ds_read_b128 v[108:111], v136 offset:1024
	ds_read_b128 v[132:135], v136 offset:2048
	ds_read_b128 v[136:139], v136 offset:3072
	ds_read_b128 v[144:147], v156
	ds_read_b128 v[148:151], v156 offset:1024
	ds_read_b128 v[152:155], v156 offset:2048
	ds_read_b128 v[156:159], v156 offset:3072
	s_add_u32 s56, s56, 0x80000
	s_addc_u32 s57, s57, 0
	s_mov_b32 m0, s80
	ds_read_b128 v[160:163], v185 offset:32768
	ds_read_b128 v[164:167], v185 offset:33792
	ds_read_b128 v[168:171], v185 offset:34816
	ds_read_b128 v[172:175], v185 offset:35840
	ds_read_b128 v[186:189], v185 offset:36864
	ds_read_b128 v[190:193], v185 offset:37888
	ds_read_b128 v[200:203], v185 offset:38912
	ds_read_b128 v[204:207], v185 offset:39936
	s_nop 0
	global_load_lds_dwordx4 v179, s[56:57]
	s_mov_b32 m0, s48
	s_nop 0
	global_load_lds_dwordx4 v182, s[56:57]
	s_waitcnt vmcnt(8)
	s_waitcnt lgkmcnt(0)
	s_barrier
	s_setprio 1
	s_waitcnt lgkmcnt(0)
	v_mfma_f32_16x16x32_bf16 v[140:143], v[104:107], v[160:163], v[140:143]
	v_mfma_f32_16x16x32_bf16 v[140:143], v[108:111], v[164:167], v[140:143]
	v_mfma_f32_16x16x32_bf16 v[124:127], v[104:107], v[168:171], v[124:127]
	v_mfma_f32_16x16x32_bf16 v[124:127], v[108:111], v[172:175], v[124:127]
	v_mfma_f32_16x16x32_bf16 v[96:99], v[104:107], v[186:189], v[96:99]
	v_mfma_f32_16x16x32_bf16 v[96:99], v[108:111], v[190:193], v[96:99]
	v_mfma_f32_16x16x32_bf16 v[84:87], v[104:107], v[200:203], v[84:87]
	v_mfma_f32_16x16x32_bf16 v[84:87], v[108:111], v[204:207], v[84:87]
	v_mfma_f32_16x16x32_bf16 v[128:131], v[132:135], v[160:163], v[128:131]
	v_mfma_f32_16x16x32_bf16 v[128:131], v[136:139], v[164:167], v[128:131]
	v_mfma_f32_16x16x32_bf16 v[112:115], v[132:135], v[168:171], v[112:115]
	v_mfma_f32_16x16x32_bf16 v[112:115], v[136:139], v[172:175], v[112:115]
	v_mfma_f32_16x16x32_bf16 v[88:91], v[132:135], v[186:189], v[88:91]
	v_mfma_f32_16x16x32_bf16 v[88:91], v[136:139], v[190:193], v[88:91]
	v_mfma_f32_16x16x32_bf16 v[72:75], v[132:135], v[200:203], v[72:75]
	v_mfma_f32_16x16x32_bf16 v[72:75], v[136:139], v[204:207], v[72:75]
	s_setprio 0
	s_setprio 1
	v_mfma_f32_16x16x32_bf16 v[120:123], v[144:147], v[160:163], v[120:123]
	v_mfma_f32_16x16x32_bf16 v[120:123], v[148:151], v[164:167], v[120:123]
	v_mfma_f32_16x16x32_bf16 v[100:103], v[144:147], v[168:171], v[100:103]
	v_mfma_f32_16x16x32_bf16 v[100:103], v[148:151], v[172:175], v[100:103]
	v_mfma_f32_16x16x32_bf16 v[80:83], v[144:147], v[186:189], v[80:83]
	v_mfma_f32_16x16x32_bf16 v[80:83], v[148:151], v[190:193], v[80:83]
	v_mfma_f32_16x16x32_bf16 v[68:71], v[144:147], v[200:203], v[68:71]
	v_mfma_f32_16x16x32_bf16 v[68:71], v[148:151], v[204:207], v[68:71]
	v_mfma_f32_16x16x32_bf16 v[116:119], v[152:155], v[160:163], v[116:119]
	v_mfma_f32_16x16x32_bf16 v[116:119], v[156:159], v[164:167], v[116:119]
	v_mfma_f32_16x16x32_bf16 v[92:95], v[152:155], v[168:171], v[92:95]
	v_mfma_f32_16x16x32_bf16 v[92:95], v[156:159], v[172:175], v[92:95]
	v_mfma_f32_16x16x32_bf16 v[76:79], v[152:155], v[186:189], v[76:79]
	v_mfma_f32_16x16x32_bf16 v[76:79], v[156:159], v[190:193], v[76:79]
	v_mfma_f32_16x16x32_bf16 v[64:67], v[152:155], v[200:203], v[64:67]
	v_mfma_f32_16x16x32_bf16 v[64:67], v[156:159], v[204:207], v[64:67]
	s_setprio 0
	s_barrier
	s_add_u32 s56, s84, 0x80
	s_addc_u32 s57, s85, 0
	s_add_i32 s86, s86, s97
	s_mov_b32 m0, s86
	ds_read_b128 v[160:163], v185 offset:49152
	ds_read_b128 v[164:167], v185 offset:50176
	ds_read_b128 v[168:171], v185 offset:51200
	ds_read_b128 v[172:175], v185 offset:52224
	ds_read_b128 v[186:189], v185 offset:53248
	ds_read_b128 v[190:193], v185 offset:54272
	ds_read_b128 v[200:203], v185 offset:55296
	ds_read_b128 v[204:207], v185 offset:56320
	s_nop 0
	global_load_lds_dwordx4 v181, s[56:57]
	s_add_i32 m0, s86, 0x2000
	s_nop 0
	global_load_lds_dwordx4 v183, s[56:57]
	s_add_u32 s56, s84, 0x80080
	s_addc_u32 s57, s85, 0
	s_add_i32 s84, s87, s97
	s_mov_b32 m0, s84
	s_nop 0
	global_load_lds_dwordx4 v181, s[56:57]
	s_add_i32 m0, s84, 0x2000
	s_nop 0
	global_load_lds_dwordx4 v183, s[56:57]
	s_mov_b32 m0, s81
	s_nop 0
	global_load_lds_dwordx4 v179, s[12:13]
	s_mov_b32 m0, s70
	s_nop 0
	global_load_lds_dwordx4 v182, s[12:13]
	s_waitcnt vmcnt(8)
	s_waitcnt lgkmcnt(0)
	s_barrier
	s_setprio 1
	s_waitcnt lgkmcnt(0)
	v_mfma_f32_16x16x32_bf16 v[60:63], v[104:107], v[160:163], v[60:63]
	v_mfma_f32_16x16x32_bf16 v[60:63], v[108:111], v[164:167], v[60:63]
	v_mfma_f32_16x16x32_bf16 v[48:51], v[104:107], v[168:171], v[48:51]
	v_mfma_f32_16x16x32_bf16 v[48:51], v[108:111], v[172:175], v[48:51]
	v_mfma_f32_16x16x32_bf16 v[32:35], v[104:107], v[186:189], v[32:35]
	v_mfma_f32_16x16x32_bf16 v[32:35], v[108:111], v[190:193], v[32:35]
	v_mfma_f32_16x16x32_bf16 v[16:19], v[104:107], v[200:203], v[16:19]
	v_mfma_f32_16x16x32_bf16 v[16:19], v[108:111], v[204:207], v[16:19]
	v_mfma_f32_16x16x32_bf16 v[56:59], v[132:135], v[160:163], v[56:59]
	v_mfma_f32_16x16x32_bf16 v[56:59], v[136:139], v[164:167], v[56:59]
	v_mfma_f32_16x16x32_bf16 v[40:43], v[132:135], v[168:171], v[40:43]
	v_mfma_f32_16x16x32_bf16 v[40:43], v[136:139], v[172:175], v[40:43]
	v_mfma_f32_16x16x32_bf16 v[24:27], v[132:135], v[186:189], v[24:27]
	v_mfma_f32_16x16x32_bf16 v[24:27], v[136:139], v[190:193], v[24:27]
	v_mfma_f32_16x16x32_bf16 v[8:11], v[132:135], v[200:203], v[8:11]
	v_mfma_f32_16x16x32_bf16 v[8:11], v[136:139], v[204:207], v[8:11]
	s_setprio 0
	s_setprio 1
	v_mfma_f32_16x16x32_bf16 v[52:55], v[144:147], v[160:163], v[52:55]
	v_mfma_f32_16x16x32_bf16 v[52:55], v[148:151], v[164:167], v[52:55]
	v_mfma_f32_16x16x32_bf16 v[36:39], v[144:147], v[168:171], v[36:39]
	v_mfma_f32_16x16x32_bf16 v[36:39], v[148:151], v[172:175], v[36:39]
	v_mfma_f32_16x16x32_bf16 v[20:23], v[144:147], v[186:189], v[20:23]
	v_mfma_f32_16x16x32_bf16 v[20:23], v[148:151], v[190:193], v[20:23]
	v_mfma_f32_16x16x32_bf16 v[4:7], v[144:147], v[200:203], v[4:7]
	v_mfma_f32_16x16x32_bf16 v[4:7], v[148:151], v[204:207], v[4:7]
	v_mfma_f32_16x16x32_bf16 v[44:47], v[152:155], v[160:163], v[44:47]
	v_mfma_f32_16x16x32_bf16 v[44:47], v[156:159], v[164:167], v[44:47]
	v_mfma_f32_16x16x32_bf16 v[28:31], v[152:155], v[168:171], v[28:31]
	v_mfma_f32_16x16x32_bf16 v[28:31], v[156:159], v[172:175], v[28:31]
	v_mfma_f32_16x16x32_bf16 v[12:15], v[152:155], v[186:189], v[12:15]
	v_mfma_f32_16x16x32_bf16 v[12:15], v[156:159], v[190:193], v[12:15]
	v_mfma_f32_16x16x32_bf16 v[0:3], v[152:155], v[200:203], v[0:3]
	v_mfma_f32_16x16x32_bf16 v[0:3], v[156:159], v[204:207], v[0:3]
	s_setprio 0
	s_barrier
	s_add_i32 s83, s83, 2
	s_add_u32 s39, s39, 0x100
	s_addc_u32 s69, s69, 0
	s_add_u32 s72, s72, 0x100
	s_addc_u32 s74, s74, 0
	s_add_u32 s8, s8, 0x100
	s_addc_u32 s9, s9, 0
	s_cmp_gt_u32 s83, 29
	s_cbranch_scc0 .LBB0_1050
	s_and_b64 vcc, exec, s[60:61]
	s_cbranch_vccz .LBB0_1053
	s_barrier

.LBB0_1127:
	s_cmp_eq_u32 s21, 4
	s_cselect_b32 s38, s22, s4
	s_cselect_b32 s39, s23, s5
	s_cselect_b32 s36, s24, s15
	s_cselect_b32 s37, s25, s17
	s_add_u32 s34, s38, 0x80
	s_addc_u32 s35, s39, 0
	s_add_i32 s65, 0, 0x10000
	s_add_i32 s69, 0, 0x14000
	v_add_u32_e32 v132, s65, v154
	v_add_u32_e32 v148, s69, v154
	ds_read_b128 v[112:115], v132
	ds_read_b128 v[120:123], v132 offset:1024
	ds_read_b128 v[128:131], v132 offset:2048
	ds_read_b128 v[132:135], v132 offset:3072
	ds_read_b128 v[144:147], v148
	ds_read_b128 v[156:159], v148 offset:1024
	ds_read_b128 v[160:163], v148 offset:2048
	ds_read_b128 v[164:167], v148 offset:3072
	s_add_u32 s56, s4, 0x7ff80
	s_addc_u32 s57, s5, 0
	s_add_i32 m0, s27, 0xc000
	ds_read_b128 v[168:171], v155
	ds_read_b128 v[172:175], v155 offset:1024
	ds_read_b128 v[176:179], v155 offset:2048
	ds_read_b128 v[180:183], v155 offset:3072
	ds_read_b128 v[184:187], v155 offset:4096
	ds_read_b128 v[188:191], v155 offset:5120
	ds_read_b128 v[192:195], v155 offset:6144
	ds_read_b128 v[200:203], v155 offset:7168
	s_nop 0
	global_load_lds_dwordx4 v151, s[56:57]
	s_add_i32 m0, s27, 0xe000
	s_nop 0
	global_load_lds_dwordx4 v150, s[56:57]
	s_waitcnt vmcnt(8)
	s_waitcnt lgkmcnt(0)
	s_barrier
	s_setprio 1
	s_waitcnt lgkmcnt(0)
	v_mfma_f32_16x16x32_bf16 v[140:143], v[112:115], v[168:171], v[140:143]
	v_mfma_f32_16x16x32_bf16 v[140:143], v[120:123], v[172:175], v[140:143]
	v_mfma_f32_16x16x32_bf16 v[108:111], v[112:115], v[176:179], v[108:111]
	v_mfma_f32_16x16x32_bf16 v[108:111], v[120:123], v[180:183], v[108:111]
	v_mfma_f32_16x16x32_bf16 v[92:95], v[112:115], v[184:187], v[92:95]
	v_mfma_f32_16x16x32_bf16 v[92:95], v[120:123], v[188:191], v[92:95]
	v_mfma_f32_16x16x32_bf16 v[76:79], v[112:115], v[192:195], v[76:79]
	v_mfma_f32_16x16x32_bf16 v[76:79], v[120:123], v[200:203], v[76:79]
	v_mfma_f32_16x16x32_bf16 v[136:139], v[128:131], v[168:171], v[136:139]
	v_mfma_f32_16x16x32_bf16 v[136:139], v[132:135], v[172:175], v[136:139]
	v_mfma_f32_16x16x32_bf16 v[104:107], v[128:131], v[176:179], v[104:107]
	v_mfma_f32_16x16x32_bf16 v[104:107], v[132:135], v[180:183], v[104:107]
	v_mfma_f32_16x16x32_bf16 v[88:91], v[128:131], v[184:187], v[88:91]
	v_mfma_f32_16x16x32_bf16 v[88:91], v[132:135], v[188:191], v[88:91]
	v_mfma_f32_16x16x32_bf16 v[72:75], v[128:131], v[192:195], v[72:75]
	v_mfma_f32_16x16x32_bf16 v[72:75], v[132:135], v[200:203], v[72:75]
	s_setprio 0
	s_setprio 1
	v_mfma_f32_16x16x32_bf16 v[124:127], v[144:147], v[168:171], v[124:127]
	v_mfma_f32_16x16x32_bf16 v[124:127], v[156:159], v[172:175], v[124:127]
	v_mfma_f32_16x16x32_bf16 v[100:103], v[144:147], v[176:179], v[100:103]
	v_mfma_f32_16x16x32_bf16 v[100:103], v[156:159], v[180:183], v[100:103]
	v_mfma_f32_16x16x32_bf16 v[84:87], v[144:147], v[184:187], v[84:87]
	v_mfma_f32_16x16x32_bf16 v[84:87], v[156:159], v[188:191], v[84:87]
	v_mfma_f32_16x16x32_bf16 v[68:71], v[144:147], v[192:195], v[68:71]
	v_mfma_f32_16x16x32_bf16 v[68:71], v[156:159], v[200:203], v[68:71]
	v_mfma_f32_16x16x32_bf16 v[116:119], v[160:163], v[168:171], v[116:119]
	v_mfma_f32_16x16x32_bf16 v[116:119], v[164:167], v[172:175], v[116:119]
	v_mfma_f32_16x16x32_bf16 v[96:99], v[160:163], v[176:179], v[96:99]
	v_mfma_f32_16x16x32_bf16 v[96:99], v[164:167], v[180:183], v[96:99]
	v_mfma_f32_16x16x32_bf16 v[80:83], v[160:163], v[184:187], v[80:83]
	v_mfma_f32_16x16x32_bf16 v[80:83], v[164:167], v[188:191], v[80:83]
	v_mfma_f32_16x16x32_bf16 v[64:67], v[160:163], v[192:195], v[64:67]
	v_mfma_f32_16x16x32_bf16 v[64:67], v[164:167], v[200:203], v[64:67]
	s_setprio 0
	s_barrier
	s_add_i32 s65, s65, s97
	s_mov_b64 s[56:57], s[36:37]
	s_mov_b32 m0, s65
	ds_read_b128 v[168:171], v155 offset:16384
	ds_read_b128 v[172:175], v155 offset:17408
	ds_read_b128 v[176:179], v155 offset:18432
	ds_read_b128 v[180:183], v155 offset:19456
	ds_read_b128 v[184:187], v155 offset:20480
	ds_read_b128 v[188:191], v155 offset:21504
	ds_read_b128 v[192:195], v155 offset:22528
	ds_read_b128 v[200:203], v155 offset:23552
	s_nop 0
	global_load_lds_dwordx4 v152, s[56:57]
	s_add_i32 m0, s65, 0x2000
	s_nop 0
	global_load_lds_dwordx4 v153, s[56:57]
	s_add_u32 s56, s36, 0x80000
	s_addc_u32 s57, s37, 0
	s_add_i32 s65, s69, s97
	s_mov_b32 m0, s65
	s_nop 0
	global_load_lds_dwordx4 v152, s[56:57]
	s_add_i32 m0, s65, 0x2000
	s_nop 0
	global_load_lds_dwordx4 v153, s[56:57]
	s_mov_b64 s[56:57], s[38:39]
	s_mov_b32 m0, s27
	s_nop 0
	global_load_lds_dwordx4 v151, s[56:57]
	s_mov_b32 m0, s29
	s_nop 0
	global_load_lds_dwordx4 v150, s[56:57]
	s_waitcnt vmcnt(8)
	s_waitcnt lgkmcnt(0)
	s_barrier
	s_setprio 1
	s_waitcnt lgkmcnt(0)
	v_mfma_f32_16x16x32_bf16 v[60:63], v[112:115], v[168:171], v[60:63]
	v_mfma_f32_16x16x32_bf16 v[60:63], v[120:123], v[172:175], v[60:63]
	v_mfma_f32_16x16x32_bf16 v[52:55], v[112:115], v[176:179], v[52:55]
	v_mfma_f32_16x16x32_bf16 v[52:55], v[120:123], v[180:183], v[52:55]
	v_mfma_f32_16x16x32_bf16 v[36:39], v[112:115], v[184:187], v[36:39]
	v_mfma_f32_16x16x32_bf16 v[36:39], v[120:123], v[188:191], v[36:39]
	v_mfma_f32_16x16x32_bf16 v[20:23], v[112:115], v[192:195], v[20:23]
	v_mfma_f32_16x16x32_bf16 v[20:23], v[120:123], v[200:203], v[20:23]
	v_mfma_f32_16x16x32_bf16 v[56:59], v[128:131], v[168:171], v[56:59]
	v_mfma_f32_16x16x32_bf16 v[56:59], v[132:135], v[172:175], v[56:59]
	v_mfma_f32_16x16x32_bf16 v[44:47], v[128:131], v[176:179], v[44:47]
	v_mfma_f32_16x16x32_bf16 v[44:47], v[132:135], v[180:183], v[44:47]
	v_mfma_f32_16x16x32_bf16 v[28:31], v[128:131], v[184:187], v[28:31]
	v_mfma_f32_16x16x32_bf16 v[28:31], v[132:135], v[188:191], v[28:31]
	v_mfma_f32_16x16x32_bf16 v[8:11], v[128:131], v[192:195], v[8:11]
	v_mfma_f32_16x16x32_bf16 v[8:11], v[132:135], v[200:203], v[8:11]
	s_setprio 0
	s_setprio 1
	v_mfma_f32_16x16x32_bf16 v[48:51], v[144:147], v[168:171], v[48:51]
	v_mfma_f32_16x16x32_bf16 v[48:51], v[156:159], v[172:175], v[48:51]
	v_mfma_f32_16x16x32_bf16 v[32:35], v[144:147], v[176:179], v[32:35]
	v_mfma_f32_16x16x32_bf16 v[32:35], v[156:159], v[180:183], v[32:35]
	v_mfma_f32_16x16x32_bf16 v[16:19], v[144:147], v[184:187], v[16:19]
	v_mfma_f32_16x16x32_bf16 v[16:19], v[156:159], v[188:191], v[16:19]
	v_mfma_f32_16x16x32_bf16 v[4:7], v[144:147], v[192:195], v[4:7]
	v_mfma_f32_16x16x32_bf16 v[4:7], v[156:159], v[200:203], v[4:7]
	v_mfma_f32_16x16x32_bf16 v[40:43], v[160:163], v[168:171], v[40:43]
	v_mfma_f32_16x16x32_bf16 v[40:43], v[164:167], v[172:175], v[40:43]
	v_mfma_f32_16x16x32_bf16 v[24:27], v[160:163], v[176:179], v[24:27]
	v_mfma_f32_16x16x32_bf16 v[24:27], v[164:167], v[180:183], v[24:27]
	v_mfma_f32_16x16x32_bf16 v[12:15], v[160:163], v[184:187], v[12:15]
	v_mfma_f32_16x16x32_bf16 v[12:15], v[164:167], v[188:191], v[12:15]
	v_mfma_f32_16x16x32_bf16 v[0:3], v[160:163], v[192:195], v[0:3]
	v_mfma_f32_16x16x32_bf16 v[0:3], v[164:167], v[200:203], v[0:3]
	s_setprio 0
	s_barrier
	s_add_i32 s56, 0, 0x18000
	s_add_i32 s57, 0, 0x1c000
	v_add_u32_e32 v132, s56, v154
	v_add_u32_e32 v148, s57, v154
	ds_read_b128 v[112:115], v132
	ds_read_b128 v[120:123], v132 offset:1024
	ds_read_b128 v[128:131], v132 offset:2048
	ds_read_b128 v[132:135], v132 offset:3072
	ds_read_b128 v[144:147], v148
	ds_read_b128 v[156:159], v148 offset:1024
	ds_read_b128 v[160:163], v148 offset:2048
	ds_read_b128 v[164:167], v148 offset:3072
	s_add_u32 s38, s38, 0x80000
	s_addc_u32 s39, s39, 0
	s_mov_b32 m0, s31
	ds_read_b128 v[168:171], v155 offset:32768
	ds_read_b128 v[172:175], v155 offset:33792
	ds_read_b128 v[176:179], v155 offset:34816
	ds_read_b128 v[180:183], v155 offset:35840
	ds_read_b128 v[184:187], v155 offset:36864
	ds_read_b128 v[188:191], v155 offset:37888
	ds_read_b128 v[192:195], v155 offset:38912
	ds_read_b128 v[200:203], v155 offset:39936
	s_nop 0
	global_load_lds_dwordx4 v151, s[38:39]
	s_mov_b32 m0, s46
	s_nop 0
	global_load_lds_dwordx4 v150, s[38:39]
	s_waitcnt vmcnt(8)
	s_waitcnt lgkmcnt(0)
	s_barrier
	s_setprio 1
	s_waitcnt lgkmcnt(0)
	v_mfma_f32_16x16x32_bf16 v[140:143], v[112:115], v[168:171], v[140:143]
	v_mfma_f32_16x16x32_bf16 v[140:143], v[120:123], v[172:175], v[140:143]
	v_mfma_f32_16x16x32_bf16 v[108:111], v[112:115], v[176:179], v[108:111]
	v_mfma_f32_16x16x32_bf16 v[108:111], v[120:123], v[180:183], v[108:111]
	v_mfma_f32_16x16x32_bf16 v[92:95], v[112:115], v[184:187], v[92:95]
	v_mfma_f32_16x16x32_bf16 v[92:95], v[120:123], v[188:191], v[92:95]
	v_mfma_f32_16x16x32_bf16 v[76:79], v[112:115], v[192:195], v[76:79]
	v_mfma_f32_16x16x32_bf16 v[76:79], v[120:123], v[200:203], v[76:79]
	v_mfma_f32_16x16x32_bf16 v[136:139], v[128:131], v[168:171], v[136:139]
	v_mfma_f32_16x16x32_bf16 v[136:139], v[132:135], v[172:175], v[136:139]
	v_mfma_f32_16x16x32_bf16 v[104:107], v[128:131], v[176:179], v[104:107]
	v_mfma_f32_16x16x32_bf16 v[104:107], v[132:135], v[180:183], v[104:107]
	v_mfma_f32_16x16x32_bf16 v[88:91], v[128:131], v[184:187], v[88:91]
	v_mfma_f32_16x16x32_bf16 v[88:91], v[132:135], v[188:191], v[88:91]
	v_mfma_f32_16x16x32_bf16 v[72:75], v[128:131], v[192:195], v[72:75]
	v_mfma_f32_16x16x32_bf16 v[72:75], v[132:135], v[200:203], v[72:75]
	s_setprio 0
	s_setprio 1
	v_mfma_f32_16x16x32_bf16 v[124:127], v[144:147], v[168:171], v[124:127]
	v_mfma_f32_16x16x32_bf16 v[124:127], v[156:159], v[172:175], v[124:127]
	v_mfma_f32_16x16x32_bf16 v[100:103], v[144:147], v[176:179], v[100:103]
	v_mfma_f32_16x16x32_bf16 v[100:103], v[156:159], v[180:183], v[100:103]
	v_mfma_f32_16x16x32_bf16 v[84:87], v[144:147], v[184:187], v[84:87]
	v_mfma_f32_16x16x32_bf16 v[84:87], v[156:159], v[188:191], v[84:87]
	v_mfma_f32_16x16x32_bf16 v[68:71], v[144:147], v[192:195], v[68:71]
	v_mfma_f32_16x16x32_bf16 v[68:71], v[156:159], v[200:203], v[68:71]
	v_mfma_f32_16x16x32_bf16 v[116:119], v[160:163], v[168:171], v[116:119]
	v_mfma_f32_16x16x32_bf16 v[116:119], v[164:167], v[172:175], v[116:119]
	v_mfma_f32_16x16x32_bf16 v[96:99], v[160:163], v[176:179], v[96:99]
	v_mfma_f32_16x16x32_bf16 v[96:99], v[164:167], v[180:183], v[96:99]
	v_mfma_f32_16x16x32_bf16 v[80:83], v[160:163], v[184:187], v[80:83]
	v_mfma_f32_16x16x32_bf16 v[80:83], v[164:167], v[188:191], v[80:83]
	v_mfma_f32_16x16x32_bf16 v[64:67], v[160:163], v[192:195], v[64:67]
	v_mfma_f32_16x16x32_bf16 v[64:67], v[164:167], v[200:203], v[64:67]
	s_setprio 0
	s_barrier
	s_add_u32 s38, s36, 0x80
	s_addc_u32 s39, s37, 0
	s_add_i32 s56, s56, s97
	s_mov_b32 m0, s56
	ds_read_b128 v[168:171], v155 offset:49152
	ds_read_b128 v[172:175], v155 offset:50176
	ds_read_b128 v[176:179], v155 offset:51200
	ds_read_b128 v[180:183], v155 offset:52224
	ds_read_b128 v[184:187], v155 offset:53248
	ds_read_b128 v[188:191], v155 offset:54272
	ds_read_b128 v[192:195], v155 offset:55296
	ds_read_b128 v[200:203], v155 offset:56320
	s_nop 0
	global_load_lds_dwordx4 v152, s[38:39]
	s_add_i32 m0, s56, 0x2000
	s_add_u32 s36, s36, 0x80080
	s_addc_u32 s37, s37, 0
	global_load_lds_dwordx4 v153, s[38:39]
	s_add_i32 s38, s57, s97
	s_mov_b32 m0, s38
	s_nop 0
	global_load_lds_dwordx4 v152, s[36:37]
	s_add_i32 m0, s38, 0x2000
	s_nop 0
	global_load_lds_dwordx4 v153, s[36:37]
	s_mov_b32 m0, s47
	s_nop 0
	global_load_lds_dwordx4 v151, s[34:35]
	s_mov_b32 m0, s48
	s_nop 0
	global_load_lds_dwordx4 v150, s[34:35]
	s_waitcnt vmcnt(8)
	s_waitcnt lgkmcnt(0)
	s_barrier
	s_setprio 1
	s_waitcnt lgkmcnt(0)
	v_mfma_f32_16x16x32_bf16 v[60:63], v[112:115], v[168:171], v[60:63]
	v_mfma_f32_16x16x32_bf16 v[60:63], v[120:123], v[172:175], v[60:63]
	v_mfma_f32_16x16x32_bf16 v[52:55], v[112:115], v[176:179], v[52:55]
	v_mfma_f32_16x16x32_bf16 v[52:55], v[120:123], v[180:183], v[52:55]
	v_mfma_f32_16x16x32_bf16 v[36:39], v[112:115], v[184:187], v[36:39]
	v_mfma_f32_16x16x32_bf16 v[36:39], v[120:123], v[188:191], v[36:39]
	v_mfma_f32_16x16x32_bf16 v[20:23], v[112:115], v[192:195], v[20:23]
	v_mfma_f32_16x16x32_bf16 v[20:23], v[120:123], v[200:203], v[20:23]
	v_mfma_f32_16x16x32_bf16 v[56:59], v[128:131], v[168:171], v[56:59]
	v_mfma_f32_16x16x32_bf16 v[56:59], v[132:135], v[172:175], v[56:59]
	v_mfma_f32_16x16x32_bf16 v[44:47], v[128:131], v[176:179], v[44:47]
	v_mfma_f32_16x16x32_bf16 v[44:47], v[132:135], v[180:183], v[44:47]
	v_mfma_f32_16x16x32_bf16 v[28:31], v[128:131], v[184:187], v[28:31]
	v_mfma_f32_16x16x32_bf16 v[28:31], v[132:135], v[188:191], v[28:31]
	v_mfma_f32_16x16x32_bf16 v[8:11], v[128:131], v[192:195], v[8:11]
	v_mfma_f32_16x16x32_bf16 v[8:11], v[132:135], v[200:203], v[8:11]
	s_setprio 0
	s_setprio 1
	v_mfma_f32_16x16x32_bf16 v[48:51], v[144:147], v[168:171], v[48:51]
	v_mfma_f32_16x16x32_bf16 v[48:51], v[156:159], v[172:175], v[48:51]
	v_mfma_f32_16x16x32_bf16 v[32:35], v[144:147], v[176:179], v[32:35]
	v_mfma_f32_16x16x32_bf16 v[32:35], v[156:159], v[180:183], v[32:35]
	v_mfma_f32_16x16x32_bf16 v[16:19], v[144:147], v[184:187], v[16:19]
	v_mfma_f32_16x16x32_bf16 v[16:19], v[156:159], v[188:191], v[16:19]
	v_mfma_f32_16x16x32_bf16 v[4:7], v[144:147], v[192:195], v[4:7]
	v_mfma_f32_16x16x32_bf16 v[4:7], v[156:159], v[200:203], v[4:7]
	v_mfma_f32_16x16x32_bf16 v[40:43], v[160:163], v[168:171], v[40:43]
	v_mfma_f32_16x16x32_bf16 v[40:43], v[164:167], v[172:175], v[40:43]
	v_mfma_f32_16x16x32_bf16 v[24:27], v[160:163], v[176:179], v[24:27]
	v_mfma_f32_16x16x32_bf16 v[24:27], v[164:167], v[180:183], v[24:27]
	v_mfma_f32_16x16x32_bf16 v[12:15], v[160:163], v[184:187], v[12:15]
	v_mfma_f32_16x16x32_bf16 v[12:15], v[164:167], v[188:191], v[12:15]
	v_mfma_f32_16x16x32_bf16 v[0:3], v[160:163], v[192:195], v[0:3]
	v_mfma_f32_16x16x32_bf16 v[0:3], v[164:167], v[200:203], v[0:3]
	s_setprio 0
	s_barrier
	s_add_i32 s21, s21, 2
	s_add_u32 s4, s4, 0x100
	s_addc_u32 s5, s5, 0
	s_add_u32 s15, s15, 0x100
	s_addc_u32 s17, s17, 0
	s_cmp_gt_u32 s21, 5
	s_cbranch_scc0 .LBB0_1127
	s_and_b64 vcc, exec, s[60:61]
	s_cbranch_vccz .LBB0_1130
	s_barrier

.LBB0_1253:
	s_add_u32 s34, s10, 0x100
	s_addc_u32 s35, s11, 0
	s_cmp_eq_u32 vcc_hi, 28
	s_cselect_b32 s40, s5, s34
	s_cselect_b32 s41, s4, s35
	s_cselect_b32 s38, s25, s27
	s_cselect_b32 s39, s9, vcc_lo
	s_add_u32 s36, s40, 0x80
	s_addc_u32 s37, s41, 0
	s_add_i32 s75, 0, 0x10000
	s_add_i32 s46, 0, 0x14000
	v_add_u32_e32 v140, s75, v196
	v_add_u32_e32 v156, s46, v196
	ds_read_b128 v[128:131], v140
	ds_read_b128 v[132:135], v140 offset:1024
	ds_read_b128 v[136:139], v140 offset:2048
	ds_read_b128 v[140:143], v140 offset:3072
	ds_read_b128 v[144:147], v156
	ds_read_b128 v[148:151], v156 offset:1024
	ds_read_b128 v[152:155], v156 offset:2048
	ds_read_b128 v[156:159], v156 offset:3072
	s_add_u32 s10, s10, 0x80080
	s_addc_u32 s11, s11, 0
	s_add_i32 m0, s15, 0xc000
	ds_read_b128 v[160:163], v200
	ds_read_b128 v[164:167], v200 offset:1024
	ds_read_b128 v[168:171], v200 offset:2048
	ds_read_b128 v[172:175], v200 offset:3072
	ds_read_b128 v[176:179], v200 offset:4096
	ds_read_b128 v[180:183], v200 offset:5120
	ds_read_b128 v[184:187], v200 offset:6144
	ds_read_b128 v[188:191], v200 offset:7168
	s_nop 0
	global_load_lds_dwordx4 v192, s[10:11]
	s_add_i32 m0, s15, 0xe000
	s_nop 0
	global_load_lds_dwordx4 v194, s[10:11]
	s_waitcnt vmcnt(8)
	s_waitcnt lgkmcnt(0)
	s_barrier
	s_setprio 1
	s_waitcnt lgkmcnt(0)
	v_mfma_f32_16x16x32_bf16 v[124:127], v[128:131], v[160:163], v[124:127]
	v_mfma_f32_16x16x32_bf16 v[124:127], v[132:135], v[164:167], v[124:127]
	v_mfma_f32_16x16x32_bf16 v[120:123], v[128:131], v[168:171], v[120:123]
	v_mfma_f32_16x16x32_bf16 v[120:123], v[132:135], v[172:175], v[120:123]
	v_mfma_f32_16x16x32_bf16 v[116:119], v[128:131], v[176:179], v[116:119]
	v_mfma_f32_16x16x32_bf16 v[116:119], v[132:135], v[180:183], v[116:119]
	v_mfma_f32_16x16x32_bf16 v[112:115], v[128:131], v[184:187], v[112:115]
	v_mfma_f32_16x16x32_bf16 v[112:115], v[132:135], v[188:191], v[112:115]
	v_mfma_f32_16x16x32_bf16 v[60:63], v[136:139], v[160:163], v[60:63]
	v_mfma_f32_16x16x32_bf16 v[60:63], v[140:143], v[164:167], v[60:63]
	v_mfma_f32_16x16x32_bf16 v[56:59], v[136:139], v[168:171], v[56:59]
	v_mfma_f32_16x16x32_bf16 v[56:59], v[140:143], v[172:175], v[56:59]
	v_mfma_f32_16x16x32_bf16 v[52:55], v[136:139], v[176:179], v[52:55]
	v_mfma_f32_16x16x32_bf16 v[52:55], v[140:143], v[180:183], v[52:55]
	v_mfma_f32_16x16x32_bf16 v[48:51], v[136:139], v[184:187], v[48:51]
	v_mfma_f32_16x16x32_bf16 v[48:51], v[140:143], v[188:191], v[48:51]
	s_setprio 0
	s_setprio 1
	v_mfma_f32_16x16x32_bf16 v[108:111], v[144:147], v[160:163], v[108:111]
	v_mfma_f32_16x16x32_bf16 v[108:111], v[148:151], v[164:167], v[108:111]
	v_mfma_f32_16x16x32_bf16 v[104:107], v[144:147], v[168:171], v[104:107]
	v_mfma_f32_16x16x32_bf16 v[104:107], v[148:151], v[172:175], v[104:107]
	v_mfma_f32_16x16x32_bf16 v[100:103], v[144:147], v[176:179], v[100:103]
	v_mfma_f32_16x16x32_bf16 v[100:103], v[148:151], v[180:183], v[100:103]
	v_mfma_f32_16x16x32_bf16 v[96:99], v[144:147], v[184:187], v[96:99]
	v_mfma_f32_16x16x32_bf16 v[96:99], v[148:151], v[188:191], v[96:99]
	v_mfma_f32_16x16x32_bf16 v[44:47], v[152:155], v[160:163], v[44:47]
	v_mfma_f32_16x16x32_bf16 v[44:47], v[156:159], v[164:167], v[44:47]
	v_mfma_f32_16x16x32_bf16 v[40:43], v[152:155], v[168:171], v[40:43]
	v_mfma_f32_16x16x32_bf16 v[40:43], v[156:159], v[172:175], v[40:43]
	v_mfma_f32_16x16x32_bf16 v[36:39], v[152:155], v[176:179], v[36:39]
	v_mfma_f32_16x16x32_bf16 v[36:39], v[156:159], v[180:183], v[36:39]
	v_mfma_f32_16x16x32_bf16 v[32:35], v[152:155], v[184:187], v[32:35]
	v_mfma_f32_16x16x32_bf16 v[32:35], v[156:159], v[188:191], v[32:35]
	s_setprio 0
	s_barrier
	s_add_i32 s47, s75, s97
	s_mov_b64 s[10:11], s[38:39]
	s_mov_b32 m0, s47
	ds_read_b128 v[160:163], v200 offset:16384
	ds_read_b128 v[164:167], v200 offset:17408
	ds_read_b128 v[168:171], v200 offset:18432
	ds_read_b128 v[172:175], v200 offset:19456
	ds_read_b128 v[176:179], v200 offset:20480
	ds_read_b128 v[180:183], v200 offset:21504
	ds_read_b128 v[184:187], v200 offset:22528
	ds_read_b128 v[188:191], v200 offset:23552
	s_nop 0
	global_load_lds_dwordx4 v193, s[10:11]
	s_add_i32 m0, s47, 0x2000
	s_nop 0
	global_load_lds_dwordx4 v195, s[10:11]
	s_add_u32 s10, s38, 0x80000
	s_addc_u32 s11, s39, 0
	s_add_i32 s46, s46, s97
	s_mov_b32 m0, s46
	s_nop 0
	global_load_lds_dwordx4 v193, s[10:11]
	s_add_i32 m0, s46, 0x2000
	s_nop 0
	global_load_lds_dwordx4 v195, s[10:11]
	s_mov_b64 s[10:11], s[40:41]
	s_mov_b32 m0, s15
	s_nop 0
	global_load_lds_dwordx4 v192, s[10:11]
	s_mov_b32 m0, s69
	s_nop 0
	global_load_lds_dwordx4 v194, s[10:11]
	s_waitcnt vmcnt(8)
	s_waitcnt lgkmcnt(0)
	s_barrier
	s_setprio 1
	s_waitcnt lgkmcnt(0)
	v_mfma_f32_16x16x32_bf16 v[92:95], v[128:131], v[160:163], v[92:95]
	v_mfma_f32_16x16x32_bf16 v[92:95], v[132:135], v[164:167], v[92:95]
	v_mfma_f32_16x16x32_bf16 v[88:91], v[128:131], v[168:171], v[88:91]
	v_mfma_f32_16x16x32_bf16 v[88:91], v[132:135], v[172:175], v[88:91]
	v_mfma_f32_16x16x32_bf16 v[84:87], v[128:131], v[176:179], v[84:87]
	v_mfma_f32_16x16x32_bf16 v[84:87], v[132:135], v[180:183], v[84:87]
	v_mfma_f32_16x16x32_bf16 v[80:83], v[128:131], v[184:187], v[80:83]
	v_mfma_f32_16x16x32_bf16 v[80:83], v[132:135], v[188:191], v[80:83]
	v_mfma_f32_16x16x32_bf16 v[28:31], v[136:139], v[160:163], v[28:31]
	v_mfma_f32_16x16x32_bf16 v[28:31], v[140:143], v[164:167], v[28:31]
	v_mfma_f32_16x16x32_bf16 v[16:19], v[136:139], v[168:171], v[16:19]
	v_mfma_f32_16x16x32_bf16 v[16:19], v[140:143], v[172:175], v[16:19]
	v_mfma_f32_16x16x32_bf16 v[20:23], v[136:139], v[176:179], v[20:23]
	v_mfma_f32_16x16x32_bf16 v[20:23], v[140:143], v[180:183], v[20:23]
	v_mfma_f32_16x16x32_bf16 v[8:11], v[136:139], v[184:187], v[8:11]
	v_mfma_f32_16x16x32_bf16 v[8:11], v[140:143], v[188:191], v[8:11]
	s_setprio 0
	s_setprio 1
	v_mfma_f32_16x16x32_bf16 v[76:79], v[144:147], v[160:163], v[76:79]
	v_mfma_f32_16x16x32_bf16 v[76:79], v[148:151], v[164:167], v[76:79]
	v_mfma_f32_16x16x32_bf16 v[72:75], v[144:147], v[168:171], v[72:75]
	v_mfma_f32_16x16x32_bf16 v[72:75], v[148:151], v[172:175], v[72:75]
	v_mfma_f32_16x16x32_bf16 v[68:71], v[144:147], v[176:179], v[68:71]
	v_mfma_f32_16x16x32_bf16 v[68:71], v[148:151], v[180:183], v[68:71]
	v_mfma_f32_16x16x32_bf16 v[64:67], v[144:147], v[184:187], v[64:67]
	v_mfma_f32_16x16x32_bf16 v[64:67], v[148:151], v[188:191], v[64:67]
	v_mfma_f32_16x16x32_bf16 v[24:27], v[152:155], v[160:163], v[24:27]
	v_mfma_f32_16x16x32_bf16 v[24:27], v[156:159], v[164:167], v[24:27]
	v_mfma_f32_16x16x32_bf16 v[12:15], v[152:155], v[168:171], v[12:15]
	v_mfma_f32_16x16x32_bf16 v[12:15], v[156:159], v[172:175], v[12:15]
	v_mfma_f32_16x16x32_bf16 v[4:7], v[152:155], v[176:179], v[4:7]
	v_mfma_f32_16x16x32_bf16 v[4:7], v[156:159], v[180:183], v[4:7]
	v_mfma_f32_16x16x32_bf16 v[0:3], v[152:155], v[184:187], v[0:3]
	v_mfma_f32_16x16x32_bf16 v[0:3], v[156:159], v[188:191], v[0:3]
	s_setprio 0
	s_barrier
	s_add_i32 s46, 0, 0x18000
	s_add_i32 s47, 0, 0x1c000
	v_add_u32_e32 v140, s46, v196
	v_add_u32_e32 v156, s47, v196
	ds_read_b128 v[128:131], v140
	ds_read_b128 v[132:135], v140 offset:1024
	ds_read_b128 v[136:139], v140 offset:2048
	ds_read_b128 v[140:143], v140 offset:3072
	ds_read_b128 v[144:147], v156
	ds_read_b128 v[148:151], v156 offset:1024
	ds_read_b128 v[152:155], v156 offset:2048
	ds_read_b128 v[156:159], v156 offset:3072
	s_add_u32 s10, s40, 0x80000
	s_addc_u32 s11, s41, 0
	s_mov_b32 m0, s78
	ds_read_b128 v[160:163], v200 offset:32768
	ds_read_b128 v[164:167], v200 offset:33792
	ds_read_b128 v[168:171], v200 offset:34816
	ds_read_b128 v[172:175], v200 offset:35840
	ds_read_b128 v[176:179], v200 offset:36864
	ds_read_b128 v[180:183], v200 offset:37888
	ds_read_b128 v[184:187], v200 offset:38912
	ds_read_b128 v[188:191], v200 offset:39936
	s_nop 0
	global_load_lds_dwordx4 v192, s[10:11]
	s_mov_b32 m0, s80
	s_nop 0
	global_load_lds_dwordx4 v194, s[10:11]
	s_waitcnt vmcnt(8)
	s_waitcnt lgkmcnt(0)
	s_barrier
	s_setprio 1
	s_waitcnt lgkmcnt(0)
	v_mfma_f32_16x16x32_bf16 v[124:127], v[128:131], v[160:163], v[124:127]
	v_mfma_f32_16x16x32_bf16 v[124:127], v[132:135], v[164:167], v[124:127]
	v_mfma_f32_16x16x32_bf16 v[120:123], v[128:131], v[168:171], v[120:123]
	v_mfma_f32_16x16x32_bf16 v[120:123], v[132:135], v[172:175], v[120:123]
	v_mfma_f32_16x16x32_bf16 v[116:119], v[128:131], v[176:179], v[116:119]
	v_mfma_f32_16x16x32_bf16 v[116:119], v[132:135], v[180:183], v[116:119]
	v_mfma_f32_16x16x32_bf16 v[112:115], v[128:131], v[184:187], v[112:115]
	v_mfma_f32_16x16x32_bf16 v[112:115], v[132:135], v[188:191], v[112:115]
	v_mfma_f32_16x16x32_bf16 v[60:63], v[136:139], v[160:163], v[60:63]
	v_mfma_f32_16x16x32_bf16 v[60:63], v[140:143], v[164:167], v[60:63]
	v_mfma_f32_16x16x32_bf16 v[56:59], v[136:139], v[168:171], v[56:59]
	v_mfma_f32_16x16x32_bf16 v[56:59], v[140:143], v[172:175], v[56:59]
	v_mfma_f32_16x16x32_bf16 v[52:55], v[136:139], v[176:179], v[52:55]
	v_mfma_f32_16x16x32_bf16 v[52:55], v[140:143], v[180:183], v[52:55]
	v_mfma_f32_16x16x32_bf16 v[48:51], v[136:139], v[184:187], v[48:51]
	v_mfma_f32_16x16x32_bf16 v[48:51], v[140:143], v[188:191], v[48:51]
	s_setprio 0
	s_setprio 1
	v_mfma_f32_16x16x32_bf16 v[108:111], v[144:147], v[160:163], v[108:111]
	v_mfma_f32_16x16x32_bf16 v[108:111], v[148:151], v[164:167], v[108:111]
	v_mfma_f32_16x16x32_bf16 v[104:107], v[144:147], v[168:171], v[104:107]
	v_mfma_f32_16x16x32_bf16 v[104:107], v[148:151], v[172:175], v[104:107]
	v_mfma_f32_16x16x32_bf16 v[100:103], v[144:147], v[176:179], v[100:103]
	v_mfma_f32_16x16x32_bf16 v[100:103], v[148:151], v[180:183], v[100:103]
	v_mfma_f32_16x16x32_bf16 v[96:99], v[144:147], v[184:187], v[96:99]
	v_mfma_f32_16x16x32_bf16 v[96:99], v[148:151], v[188:191], v[96:99]
	v_mfma_f32_16x16x32_bf16 v[44:47], v[152:155], v[160:163], v[44:47]
	v_mfma_f32_16x16x32_bf16 v[44:47], v[156:159], v[164:167], v[44:47]
	v_mfma_f32_16x16x32_bf16 v[40:43], v[152:155], v[168:171], v[40:43]
	v_mfma_f32_16x16x32_bf16 v[40:43], v[156:159], v[172:175], v[40:43]
	v_mfma_f32_16x16x32_bf16 v[36:39], v[152:155], v[176:179], v[36:39]
	v_mfma_f32_16x16x32_bf16 v[36:39], v[156:159], v[180:183], v[36:39]
	v_mfma_f32_16x16x32_bf16 v[32:35], v[152:155], v[184:187], v[32:35]
	v_mfma_f32_16x16x32_bf16 v[32:35], v[156:159], v[188:191], v[32:35]
	s_setprio 0
	s_barrier
	s_add_u32 s10, s38, 0x80
	s_addc_u32 s11, s39, 0
	s_add_i32 s40, s46, s97
	s_mov_b32 m0, s40
	ds_read_b128 v[160:163], v200 offset:49152
	ds_read_b128 v[164:167], v200 offset:50176
	ds_read_b128 v[168:171], v200 offset:51200
	ds_read_b128 v[172:175], v200 offset:52224
	ds_read_b128 v[176:179], v200 offset:53248
	ds_read_b128 v[180:183], v200 offset:54272
	ds_read_b128 v[184:187], v200 offset:55296
	ds_read_b128 v[188:191], v200 offset:56320
	s_nop 0
	global_load_lds_dwordx4 v193, s[10:11]
	s_add_i32 m0, s40, 0x2000
	s_nop 0
	global_load_lds_dwordx4 v195, s[10:11]
	s_add_u32 s10, s38, 0x80080
	s_addc_u32 s11, s39, 0
	s_add_i32 s38, s47, s97
	s_mov_b32 m0, s38
	s_nop 0
	global_load_lds_dwordx4 v193, s[10:11]
	s_add_i32 m0, s38, 0x2000
	s_nop 0
	global_load_lds_dwordx4 v195, s[10:11]
	s_mov_b32 m0, s85
	s_nop 0
	global_load_lds_dwordx4 v192, s[36:37]
	s_mov_b32 m0, s86
	s_nop 0
	global_load_lds_dwordx4 v194, s[36:37]
	s_waitcnt vmcnt(8)
	s_waitcnt lgkmcnt(0)
	s_barrier
	s_setprio 1
	s_waitcnt lgkmcnt(0)
	v_mfma_f32_16x16x32_bf16 v[92:95], v[128:131], v[160:163], v[92:95]
	v_mfma_f32_16x16x32_bf16 v[92:95], v[132:135], v[164:167], v[92:95]
	v_mfma_f32_16x16x32_bf16 v[88:91], v[128:131], v[168:171], v[88:91]
	v_mfma_f32_16x16x32_bf16 v[88:91], v[132:135], v[172:175], v[88:91]
	v_mfma_f32_16x16x32_bf16 v[84:87], v[128:131], v[176:179], v[84:87]
	v_mfma_f32_16x16x32_bf16 v[84:87], v[132:135], v[180:183], v[84:87]
	v_mfma_f32_16x16x32_bf16 v[80:83], v[128:131], v[184:187], v[80:83]
	v_mfma_f32_16x16x32_bf16 v[80:83], v[132:135], v[188:191], v[80:83]
	v_mfma_f32_16x16x32_bf16 v[28:31], v[136:139], v[160:163], v[28:31]
	v_mfma_f32_16x16x32_bf16 v[28:31], v[140:143], v[164:167], v[28:31]
	v_mfma_f32_16x16x32_bf16 v[16:19], v[136:139], v[168:171], v[16:19]
	v_mfma_f32_16x16x32_bf16 v[16:19], v[140:143], v[172:175], v[16:19]
	v_mfma_f32_16x16x32_bf16 v[20:23], v[136:139], v[176:179], v[20:23]
	v_mfma_f32_16x16x32_bf16 v[20:23], v[140:143], v[180:183], v[20:23]
	v_mfma_f32_16x16x32_bf16 v[8:11], v[136:139], v[184:187], v[8:11]
	v_mfma_f32_16x16x32_bf16 v[8:11], v[140:143], v[188:191], v[8:11]
	s_setprio 0
	s_setprio 1
	v_mfma_f32_16x16x32_bf16 v[76:79], v[144:147], v[160:163], v[76:79]
	v_mfma_f32_16x16x32_bf16 v[76:79], v[148:151], v[164:167], v[76:79]
	v_mfma_f32_16x16x32_bf16 v[72:75], v[144:147], v[168:171], v[72:75]
	v_mfma_f32_16x16x32_bf16 v[72:75], v[148:151], v[172:175], v[72:75]
	v_mfma_f32_16x16x32_bf16 v[68:71], v[144:147], v[176:179], v[68:71]
	v_mfma_f32_16x16x32_bf16 v[68:71], v[148:151], v[180:183], v[68:71]
	v_mfma_f32_16x16x32_bf16 v[64:67], v[144:147], v[184:187], v[64:67]
	v_mfma_f32_16x16x32_bf16 v[64:67], v[148:151], v[188:191], v[64:67]
	v_mfma_f32_16x16x32_bf16 v[24:27], v[152:155], v[160:163], v[24:27]
	v_mfma_f32_16x16x32_bf16 v[24:27], v[156:159], v[164:167], v[24:27]
	v_mfma_f32_16x16x32_bf16 v[12:15], v[152:155], v[168:171], v[12:15]
	v_mfma_f32_16x16x32_bf16 v[12:15], v[156:159], v[172:175], v[12:15]
	v_mfma_f32_16x16x32_bf16 v[4:7], v[152:155], v[176:179], v[4:7]
	v_mfma_f32_16x16x32_bf16 v[4:7], v[156:159], v[180:183], v[4:7]
	v_mfma_f32_16x16x32_bf16 v[0:3], v[152:155], v[184:187], v[0:3]
	v_mfma_f32_16x16x32_bf16 v[0:3], v[156:159], v[188:191], v[0:3]
	s_setprio 0
	s_barrier
	s_add_i32 vcc_hi, vcc_hi, 2
	s_add_u32 s27, s27, 0x100
	s_addc_u32 vcc_lo, vcc_lo, 0
	s_cmp_gt_u32 vcc_hi, 29
	s_mov_b64 s[10:11], s[34:35]
	s_cbranch_scc0 .LBB0_1253
	s_and_b64 vcc, exec, s[60:61]
	s_cbranch_vccz .LBB0_1256
	s_barrier

.LBB0_1290:
	s_cmp_eq_u32 s21, 12
	s_cselect_b32 s40, s24, s4
	s_cselect_b32 s41, s25, s5
	s_cselect_b32 s38, s30, s15
	s_cselect_b32 s39, s31, s17
	s_add_u32 s36, s40, 0x80
	s_addc_u32 s37, s41, 0
	s_add_i32 s23, 0, 0x10000
	v_add_u32_e32 v128, s23, v134
	s_add_i32 s46, 0, 0x14000
	ds_read_b128 v[136:139], v128
	ds_read_b128 v[140:143], v128 offset:1024
	ds_read_b128 v[144:147], v128 offset:2048
	ds_read_b128 v[148:151], v128 offset:3072
	v_add_u32_e32 v128, s46, v134
	ds_read_b128 v[152:155], v128
	ds_read_b128 v[156:159], v128 offset:1024
	ds_read_b128 v[160:163], v128 offset:2048
	ds_read_b128 v[164:167], v128 offset:3072
	s_mov_b64 s[74:75], s[34:35]
	s_add_i32 m0, s27, 0xc000
	ds_read_b128 v[168:171], v135
	ds_read_b128 v[172:175], v135 offset:1024
	ds_read_b128 v[176:179], v135 offset:2048
	ds_read_b128 v[180:183], v135 offset:3072
	ds_read_b128 v[184:187], v135 offset:4096
	ds_read_b128 v[188:191], v135 offset:5120
	ds_read_b128 v[192:195], v135 offset:6144
	ds_read_b128 v[200:203], v135 offset:7168
	s_nop 0
	global_load_lds_dwordx4 v133, s[74:75]
	s_add_i32 m0, s27, 0xe000
	s_nop 0
	global_load_lds_dwordx4 v131, s[74:75]
	s_waitcnt vmcnt(8)
	s_waitcnt lgkmcnt(0)
	s_barrier
	s_setprio 1
	s_waitcnt lgkmcnt(0)
	v_mfma_f32_16x16x32_bf16 v[124:127], v[136:139], v[168:171], v[124:127]
	v_mfma_f32_16x16x32_bf16 v[124:127], v[140:143], v[172:175], v[124:127]
	v_mfma_f32_16x16x32_bf16 v[116:119], v[136:139], v[176:179], v[116:119]
	v_mfma_f32_16x16x32_bf16 v[116:119], v[140:143], v[180:183], v[116:119]
	v_mfma_f32_16x16x32_bf16 v[100:103], v[136:139], v[184:187], v[100:103]
	v_mfma_f32_16x16x32_bf16 v[100:103], v[140:143], v[188:191], v[100:103]
	v_mfma_f32_16x16x32_bf16 v[84:87], v[136:139], v[192:195], v[84:87]
	v_mfma_f32_16x16x32_bf16 v[84:87], v[140:143], v[200:203], v[84:87]
	v_mfma_f32_16x16x32_bf16 v[120:123], v[144:147], v[168:171], v[120:123]
	v_mfma_f32_16x16x32_bf16 v[120:123], v[148:151], v[172:175], v[120:123]
	v_mfma_f32_16x16x32_bf16 v[108:111], v[144:147], v[176:179], v[108:111]
	v_mfma_f32_16x16x32_bf16 v[108:111], v[148:151], v[180:183], v[108:111]
	v_mfma_f32_16x16x32_bf16 v[92:95], v[144:147], v[184:187], v[92:95]
	v_mfma_f32_16x16x32_bf16 v[92:95], v[148:151], v[188:191], v[92:95]
	v_mfma_f32_16x16x32_bf16 v[76:79], v[144:147], v[192:195], v[76:79]
	v_mfma_f32_16x16x32_bf16 v[76:79], v[148:151], v[200:203], v[76:79]
	s_setprio 0
	s_setprio 1
	v_mfma_f32_16x16x32_bf16 v[112:115], v[152:155], v[168:171], v[112:115]
	v_mfma_f32_16x16x32_bf16 v[112:115], v[156:159], v[172:175], v[112:115]
	v_mfma_f32_16x16x32_bf16 v[96:99], v[152:155], v[176:179], v[96:99]
	v_mfma_f32_16x16x32_bf16 v[96:99], v[156:159], v[180:183], v[96:99]
	v_mfma_f32_16x16x32_bf16 v[80:83], v[152:155], v[184:187], v[80:83]
	v_mfma_f32_16x16x32_bf16 v[80:83], v[156:159], v[188:191], v[80:83]
	v_mfma_f32_16x16x32_bf16 v[68:71], v[152:155], v[192:195], v[68:71]
	v_mfma_f32_16x16x32_bf16 v[68:71], v[156:159], v[200:203], v[68:71]
	v_mfma_f32_16x16x32_bf16 v[104:107], v[160:163], v[168:171], v[104:107]
	v_mfma_f32_16x16x32_bf16 v[104:107], v[164:167], v[172:175], v[104:107]
	v_mfma_f32_16x16x32_bf16 v[88:91], v[160:163], v[176:179], v[88:91]
	v_mfma_f32_16x16x32_bf16 v[88:91], v[164:167], v[180:183], v[88:91]
	v_mfma_f32_16x16x32_bf16 v[72:75], v[160:163], v[184:187], v[72:75]
	v_mfma_f32_16x16x32_bf16 v[72:75], v[164:167], v[188:191], v[72:75]
	v_mfma_f32_16x16x32_bf16 v[64:67], v[160:163], v[192:195], v[64:67]
	v_mfma_f32_16x16x32_bf16 v[64:67], v[164:167], v[200:203], v[64:67]
	s_setprio 0
	s_barrier
	s_add_i32 s23, s23, s97
	s_mov_b64 s[74:75], s[38:39]
	s_mov_b32 m0, s23
	ds_read_b128 v[168:171], v135 offset:16384
	ds_read_b128 v[172:175], v135 offset:17408
	ds_read_b128 v[176:179], v135 offset:18432
	ds_read_b128 v[180:183], v135 offset:19456
	ds_read_b128 v[184:187], v135 offset:20480
	ds_read_b128 v[188:191], v135 offset:21504
	ds_read_b128 v[192:195], v135 offset:22528
	ds_read_b128 v[200:203], v135 offset:23552
	s_nop 0
	global_load_lds_dwordx4 v132, s[74:75]
	s_add_i32 m0, s23, 0x2000
	s_nop 0
	global_load_lds_dwordx4 v130, s[74:75]
	s_add_u32 s74, s38, 0x80000
	s_addc_u32 s75, s39, 0
	s_add_i32 s23, s46, s97
	s_mov_b32 m0, s23
	s_nop 0
	global_load_lds_dwordx4 v132, s[74:75]
	s_add_i32 m0, s23, 0x2000
	s_nop 0
	global_load_lds_dwordx4 v130, s[74:75]
	s_mov_b64 s[74:75], s[40:41]
	s_mov_b32 m0, s27
	s_nop 0
	global_load_lds_dwordx4 v133, s[74:75]
	s_mov_b32 m0, s29
	s_nop 0
	global_load_lds_dwordx4 v131, s[74:75]
	s_waitcnt vmcnt(8)
	s_waitcnt lgkmcnt(0)
	s_barrier
	s_setprio 1
	s_waitcnt lgkmcnt(0)
	v_mfma_f32_16x16x32_bf16 v[60:63], v[136:139], v[168:171], v[60:63]
	v_mfma_f32_16x16x32_bf16 v[60:63], v[140:143], v[172:175], v[60:63]
	v_mfma_f32_16x16x32_bf16 v[52:55], v[136:139], v[176:179], v[52:55]
	v_mfma_f32_16x16x32_bf16 v[52:55], v[140:143], v[180:183], v[52:55]
	v_mfma_f32_16x16x32_bf16 v[36:39], v[136:139], v[184:187], v[36:39]
	v_mfma_f32_16x16x32_bf16 v[36:39], v[140:143], v[188:191], v[36:39]
	v_mfma_f32_16x16x32_bf16 v[20:23], v[136:139], v[192:195], v[20:23]
	v_mfma_f32_16x16x32_bf16 v[20:23], v[140:143], v[200:203], v[20:23]
	v_mfma_f32_16x16x32_bf16 v[56:59], v[144:147], v[168:171], v[56:59]
	v_mfma_f32_16x16x32_bf16 v[56:59], v[148:151], v[172:175], v[56:59]
	v_mfma_f32_16x16x32_bf16 v[44:47], v[144:147], v[176:179], v[44:47]
	v_mfma_f32_16x16x32_bf16 v[44:47], v[148:151], v[180:183], v[44:47]
	v_mfma_f32_16x16x32_bf16 v[28:31], v[144:147], v[184:187], v[28:31]
	v_mfma_f32_16x16x32_bf16 v[28:31], v[148:151], v[188:191], v[28:31]
	v_mfma_f32_16x16x32_bf16 v[12:15], v[144:147], v[192:195], v[12:15]
	v_mfma_f32_16x16x32_bf16 v[12:15], v[148:151], v[200:203], v[12:15]
	s_setprio 0
	s_setprio 1
	v_mfma_f32_16x16x32_bf16 v[48:51], v[152:155], v[168:171], v[48:51]
	v_mfma_f32_16x16x32_bf16 v[48:51], v[156:159], v[172:175], v[48:51]
	v_mfma_f32_16x16x32_bf16 v[32:35], v[152:155], v[176:179], v[32:35]
	v_mfma_f32_16x16x32_bf16 v[32:35], v[156:159], v[180:183], v[32:35]
	v_mfma_f32_16x16x32_bf16 v[16:19], v[152:155], v[184:187], v[16:19]
	v_mfma_f32_16x16x32_bf16 v[16:19], v[156:159], v[188:191], v[16:19]
	v_mfma_f32_16x16x32_bf16 v[4:7], v[152:155], v[192:195], v[4:7]
	v_mfma_f32_16x16x32_bf16 v[4:7], v[156:159], v[200:203], v[4:7]
	v_mfma_f32_16x16x32_bf16 v[40:43], v[160:163], v[168:171], v[40:43]
	v_mfma_f32_16x16x32_bf16 v[40:43], v[164:167], v[172:175], v[40:43]
	v_mfma_f32_16x16x32_bf16 v[24:27], v[160:163], v[176:179], v[24:27]
	v_mfma_f32_16x16x32_bf16 v[24:27], v[164:167], v[180:183], v[24:27]
	v_mfma_f32_16x16x32_bf16 v[8:11], v[160:163], v[184:187], v[8:11]
	v_mfma_f32_16x16x32_bf16 v[8:11], v[164:167], v[188:191], v[8:11]
	v_mfma_f32_16x16x32_bf16 v[0:3], v[160:163], v[192:195], v[0:3]
	v_mfma_f32_16x16x32_bf16 v[0:3], v[164:167], v[200:203], v[0:3]
	s_setprio 0
	s_barrier
	s_add_i32 s23, 0, 0x18000
	v_add_u32_e32 v128, s23, v134
	s_add_i32 s46, 0, 0x1c000
	ds_read_b128 v[136:139], v128
	ds_read_b128 v[140:143], v128 offset:1024
	ds_read_b128 v[144:147], v128 offset:2048
	ds_read_b128 v[148:151], v128 offset:3072
	v_add_u32_e32 v128, s46, v134
	ds_read_b128 v[152:155], v128
	ds_read_b128 v[156:159], v128 offset:1024
	ds_read_b128 v[160:163], v128 offset:2048
	ds_read_b128 v[164:167], v128 offset:3072
	s_add_u32 s40, s40, 0x80000
	s_addc_u32 s41, s41, 0
	s_mov_b32 m0, s56
	ds_read_b128 v[168:171], v135 offset:32768
	ds_read_b128 v[172:175], v135 offset:33792
	ds_read_b128 v[176:179], v135 offset:34816
	ds_read_b128 v[180:183], v135 offset:35840
	ds_read_b128 v[184:187], v135 offset:36864
	ds_read_b128 v[188:191], v135 offset:37888
	ds_read_b128 v[192:195], v135 offset:38912
	ds_read_b128 v[200:203], v135 offset:39936
	s_nop 0
	global_load_lds_dwordx4 v133, s[40:41]
	s_mov_b32 m0, s57
	s_nop 0
	global_load_lds_dwordx4 v131, s[40:41]
	s_waitcnt vmcnt(8)
	s_waitcnt lgkmcnt(0)
	s_barrier
	s_setprio 1
	s_waitcnt lgkmcnt(0)
	v_mfma_f32_16x16x32_bf16 v[124:127], v[136:139], v[168:171], v[124:127]
	v_mfma_f32_16x16x32_bf16 v[124:127], v[140:143], v[172:175], v[124:127]
	v_mfma_f32_16x16x32_bf16 v[116:119], v[136:139], v[176:179], v[116:119]
	v_mfma_f32_16x16x32_bf16 v[116:119], v[140:143], v[180:183], v[116:119]
	v_mfma_f32_16x16x32_bf16 v[100:103], v[136:139], v[184:187], v[100:103]
	v_mfma_f32_16x16x32_bf16 v[100:103], v[140:143], v[188:191], v[100:103]
	v_mfma_f32_16x16x32_bf16 v[84:87], v[136:139], v[192:195], v[84:87]
	v_mfma_f32_16x16x32_bf16 v[84:87], v[140:143], v[200:203], v[84:87]
	v_mfma_f32_16x16x32_bf16 v[120:123], v[144:147], v[168:171], v[120:123]
	v_mfma_f32_16x16x32_bf16 v[120:123], v[148:151], v[172:175], v[120:123]
	v_mfma_f32_16x16x32_bf16 v[108:111], v[144:147], v[176:179], v[108:111]
	v_mfma_f32_16x16x32_bf16 v[108:111], v[148:151], v[180:183], v[108:111]
	v_mfma_f32_16x16x32_bf16 v[92:95], v[144:147], v[184:187], v[92:95]
	v_mfma_f32_16x16x32_bf16 v[92:95], v[148:151], v[188:191], v[92:95]
	v_mfma_f32_16x16x32_bf16 v[76:79], v[144:147], v[192:195], v[76:79]
	v_mfma_f32_16x16x32_bf16 v[76:79], v[148:151], v[200:203], v[76:79]
	s_setprio 0
	s_setprio 1
	v_mfma_f32_16x16x32_bf16 v[112:115], v[152:155], v[168:171], v[112:115]
	v_mfma_f32_16x16x32_bf16 v[112:115], v[156:159], v[172:175], v[112:115]
	v_mfma_f32_16x16x32_bf16 v[96:99], v[152:155], v[176:179], v[96:99]
	v_mfma_f32_16x16x32_bf16 v[96:99], v[156:159], v[180:183], v[96:99]
	v_mfma_f32_16x16x32_bf16 v[80:83], v[152:155], v[184:187], v[80:83]
	v_mfma_f32_16x16x32_bf16 v[80:83], v[156:159], v[188:191], v[80:83]
	v_mfma_f32_16x16x32_bf16 v[68:71], v[152:155], v[192:195], v[68:71]
	v_mfma_f32_16x16x32_bf16 v[68:71], v[156:159], v[200:203], v[68:71]
	v_mfma_f32_16x16x32_bf16 v[104:107], v[160:163], v[168:171], v[104:107]
	v_mfma_f32_16x16x32_bf16 v[104:107], v[164:167], v[172:175], v[104:107]
	v_mfma_f32_16x16x32_bf16 v[88:91], v[160:163], v[176:179], v[88:91]
	v_mfma_f32_16x16x32_bf16 v[88:91], v[164:167], v[180:183], v[88:91]
	v_mfma_f32_16x16x32_bf16 v[72:75], v[160:163], v[184:187], v[72:75]
	v_mfma_f32_16x16x32_bf16 v[72:75], v[164:167], v[188:191], v[72:75]
	v_mfma_f32_16x16x32_bf16 v[64:67], v[160:163], v[192:195], v[64:67]
	v_mfma_f32_16x16x32_bf16 v[64:67], v[164:167], v[200:203], v[64:67]
	s_setprio 0
	s_barrier
	s_add_u32 s40, s38, 0x80
	s_addc_u32 s41, s39, 0
	s_add_i32 s23, s23, s97
	s_mov_b32 m0, s23
	ds_read_b128 v[168:171], v135 offset:49152
	ds_read_b128 v[172:175], v135 offset:50176
	ds_read_b128 v[176:179], v135 offset:51200
	ds_read_b128 v[180:183], v135 offset:52224
	ds_read_b128 v[184:187], v135 offset:53248
	ds_read_b128 v[188:191], v135 offset:54272
	ds_read_b128 v[192:195], v135 offset:55296
	ds_read_b128 v[200:203], v135 offset:56320
	s_nop 0
	global_load_lds_dwordx4 v132, s[40:41]
	s_add_i32 m0, s23, 0x2000
	s_add_u32 s38, s38, 0x80080
	s_addc_u32 s39, s39, 0
	s_add_i32 s23, s46, s97
	s_nop 0
	global_load_lds_dwordx4 v130, s[40:41]
	s_mov_b32 m0, s23
	s_nop 0
	global_load_lds_dwordx4 v132, s[38:39]
	s_add_i32 m0, s23, 0x2000
	s_nop 0
	global_load_lds_dwordx4 v130, s[38:39]
	s_mov_b32 m0, s70
	s_nop 0
	global_load_lds_dwordx4 v133, s[36:37]
	s_mov_b32 m0, s71
	s_nop 0
	global_load_lds_dwordx4 v131, s[36:37]
	s_waitcnt vmcnt(8)
	s_waitcnt lgkmcnt(0)
	s_barrier
	s_setprio 1
	s_waitcnt lgkmcnt(0)
	v_mfma_f32_16x16x32_bf16 v[60:63], v[136:139], v[168:171], v[60:63]
	v_mfma_f32_16x16x32_bf16 v[60:63], v[140:143], v[172:175], v[60:63]
	v_mfma_f32_16x16x32_bf16 v[52:55], v[136:139], v[176:179], v[52:55]
	v_mfma_f32_16x16x32_bf16 v[52:55], v[140:143], v[180:183], v[52:55]
	v_mfma_f32_16x16x32_bf16 v[36:39], v[136:139], v[184:187], v[36:39]
	v_mfma_f32_16x16x32_bf16 v[36:39], v[140:143], v[188:191], v[36:39]
	v_mfma_f32_16x16x32_bf16 v[20:23], v[136:139], v[192:195], v[20:23]
	v_mfma_f32_16x16x32_bf16 v[20:23], v[140:143], v[200:203], v[20:23]
	v_mfma_f32_16x16x32_bf16 v[56:59], v[144:147], v[168:171], v[56:59]
	v_mfma_f32_16x16x32_bf16 v[56:59], v[148:151], v[172:175], v[56:59]
	v_mfma_f32_16x16x32_bf16 v[44:47], v[144:147], v[176:179], v[44:47]
	v_mfma_f32_16x16x32_bf16 v[44:47], v[148:151], v[180:183], v[44:47]
	v_mfma_f32_16x16x32_bf16 v[28:31], v[144:147], v[184:187], v[28:31]
	v_mfma_f32_16x16x32_bf16 v[28:31], v[148:151], v[188:191], v[28:31]
	v_mfma_f32_16x16x32_bf16 v[12:15], v[144:147], v[192:195], v[12:15]
	v_mfma_f32_16x16x32_bf16 v[12:15], v[148:151], v[200:203], v[12:15]
	s_setprio 0
	s_setprio 1
	v_mfma_f32_16x16x32_bf16 v[48:51], v[152:155], v[168:171], v[48:51]
	v_mfma_f32_16x16x32_bf16 v[48:51], v[156:159], v[172:175], v[48:51]
	v_mfma_f32_16x16x32_bf16 v[32:35], v[152:155], v[176:179], v[32:35]
	v_mfma_f32_16x16x32_bf16 v[32:35], v[156:159], v[180:183], v[32:35]
	v_mfma_f32_16x16x32_bf16 v[16:19], v[152:155], v[184:187], v[16:19]
	v_mfma_f32_16x16x32_bf16 v[16:19], v[156:159], v[188:191], v[16:19]
	v_mfma_f32_16x16x32_bf16 v[4:7], v[152:155], v[192:195], v[4:7]
	v_mfma_f32_16x16x32_bf16 v[4:7], v[156:159], v[200:203], v[4:7]
	v_mfma_f32_16x16x32_bf16 v[40:43], v[160:163], v[168:171], v[40:43]
	v_mfma_f32_16x16x32_bf16 v[40:43], v[164:167], v[172:175], v[40:43]
	v_mfma_f32_16x16x32_bf16 v[24:27], v[160:163], v[176:179], v[24:27]
	v_mfma_f32_16x16x32_bf16 v[24:27], v[164:167], v[180:183], v[24:27]
	v_mfma_f32_16x16x32_bf16 v[8:11], v[160:163], v[184:187], v[8:11]
	v_mfma_f32_16x16x32_bf16 v[8:11], v[164:167], v[188:191], v[8:11]
	v_mfma_f32_16x16x32_bf16 v[0:3], v[160:163], v[192:195], v[0:3]
	v_mfma_f32_16x16x32_bf16 v[0:3], v[164:167], v[200:203], v[0:3]
	s_setprio 0
	s_barrier
	s_add_i32 s21, s21, 2
	s_add_u32 s4, s4, 0x100
	s_addc_u32 s5, s5, 0
	s_add_u32 s15, s15, 0x100
	s_addc_u32 s17, s17, 0
	s_add_u32 s34, s34, 0x100
	s_addc_u32 s35, s35, 0
	s_cmp_gt_u32 s21, 13
	s_cbranch_scc0 .LBB0_1290
	s_and_b64 vcc, exec, s[60:61]
	s_cbranch_vccz .LBB0_1293
	s_barrier

.LBB0_1425:
	s_cmpk_eq_i32 s80, 0x54
	s_cselect_b32 s56, s48, s4
	s_cselect_b32 s57, s49, s5
	s_cselect_b32 s74, s70, s15
	s_cselect_b32 s75, s71, s72
	s_add_u32 s16, s56, 0x80
	s_addc_u32 s17, s57, 0
	s_add_i32 s81, 0, 0x10000
	s_add_i32 vcc_lo, 0, 0x14000
	v_add_u32_e32 v136, s81, v172
	v_add_u32_e32 v156, vcc_lo, v172
	ds_read_b128 v[120:123], v136
	ds_read_b128 v[124:127], v136 offset:1024
	ds_read_b128 v[132:135], v136 offset:2048
	ds_read_b128 v[136:139], v136 offset:3072
	ds_read_b128 v[144:147], v156
	ds_read_b128 v[148:151], v156 offset:1024
	ds_read_b128 v[152:155], v156 offset:2048
	ds_read_b128 v[156:159], v156 offset:3072
	s_mov_b64 s[12:13], s[28:29]
	s_add_i32 m0, s2, 0xc000
	ds_read_b128 v[160:163], v173
	ds_read_b128 v[164:167], v173 offset:1024
	ds_read_b128 v[174:177], v173 offset:2048
	ds_read_b128 v[178:181], v173 offset:3072
	ds_read_b128 v[182:185], v173 offset:4096
	ds_read_b128 v[186:189], v173 offset:5120
	ds_read_b128 v[190:193], v173 offset:6144
	ds_read_b128 v[200:203], v173 offset:7168
	s_nop 0
	global_load_lds_dwordx4 v168, s[12:13]
	s_add_i32 m0, s2, 0xe000
	s_nop 0
	global_load_lds_dwordx4 v170, s[12:13]
	s_waitcnt vmcnt(8)
	s_waitcnt lgkmcnt(0)
	s_barrier
	s_setprio 1
	s_waitcnt lgkmcnt(0)
	v_mfma_f32_16x16x32_bf16 v[140:143], v[120:123], v[160:163], v[140:143]
	v_mfma_f32_16x16x32_bf16 v[140:143], v[124:127], v[164:167], v[140:143]
	v_mfma_f32_16x16x32_bf16 v[116:119], v[120:123], v[174:177], v[116:119]
	v_mfma_f32_16x16x32_bf16 v[116:119], v[124:127], v[178:181], v[116:119]
	v_mfma_f32_16x16x32_bf16 v[96:99], v[120:123], v[182:185], v[96:99]
	v_mfma_f32_16x16x32_bf16 v[96:99], v[124:127], v[186:189], v[96:99]
	v_mfma_f32_16x16x32_bf16 v[84:87], v[120:123], v[190:193], v[84:87]
	v_mfma_f32_16x16x32_bf16 v[84:87], v[124:127], v[200:203], v[84:87]
	v_mfma_f32_16x16x32_bf16 v[128:131], v[132:135], v[160:163], v[128:131]
	v_mfma_f32_16x16x32_bf16 v[128:131], v[136:139], v[164:167], v[128:131]
	v_mfma_f32_16x16x32_bf16 v[104:107], v[132:135], v[174:177], v[104:107]
	v_mfma_f32_16x16x32_bf16 v[104:107], v[136:139], v[178:181], v[104:107]
	v_mfma_f32_16x16x32_bf16 v[88:91], v[132:135], v[182:185], v[88:91]
	v_mfma_f32_16x16x32_bf16 v[88:91], v[136:139], v[186:189], v[88:91]
	v_mfma_f32_16x16x32_bf16 v[72:75], v[132:135], v[190:193], v[72:75]
	v_mfma_f32_16x16x32_bf16 v[72:75], v[136:139], v[200:203], v[72:75]
	s_setprio 0
	s_setprio 1
	v_mfma_f32_16x16x32_bf16 v[112:115], v[144:147], v[160:163], v[112:115]
	v_mfma_f32_16x16x32_bf16 v[112:115], v[148:151], v[164:167], v[112:115]
	v_mfma_f32_16x16x32_bf16 v[100:103], v[144:147], v[174:177], v[100:103]
	v_mfma_f32_16x16x32_bf16 v[100:103], v[148:151], v[178:181], v[100:103]
	v_mfma_f32_16x16x32_bf16 v[80:83], v[144:147], v[182:185], v[80:83]
	v_mfma_f32_16x16x32_bf16 v[80:83], v[148:151], v[186:189], v[80:83]
	v_mfma_f32_16x16x32_bf16 v[68:71], v[144:147], v[190:193], v[68:71]
	v_mfma_f32_16x16x32_bf16 v[68:71], v[148:151], v[200:203], v[68:71]
	v_mfma_f32_16x16x32_bf16 v[108:111], v[152:155], v[160:163], v[108:111]
	v_mfma_f32_16x16x32_bf16 v[108:111], v[156:159], v[164:167], v[108:111]
	v_mfma_f32_16x16x32_bf16 v[92:95], v[152:155], v[174:177], v[92:95]
	v_mfma_f32_16x16x32_bf16 v[92:95], v[156:159], v[178:181], v[92:95]
	v_mfma_f32_16x16x32_bf16 v[76:79], v[152:155], v[182:185], v[76:79]
	v_mfma_f32_16x16x32_bf16 v[76:79], v[156:159], v[186:189], v[76:79]
	v_mfma_f32_16x16x32_bf16 v[64:67], v[152:155], v[190:193], v[64:67]
	v_mfma_f32_16x16x32_bf16 v[64:67], v[156:159], v[200:203], v[64:67]
	s_setprio 0
	s_barrier
	s_add_i32 s81, s81, s97
	s_mov_b64 s[12:13], s[74:75]
	s_mov_b32 m0, s81
	ds_read_b128 v[160:163], v173 offset:16384
	ds_read_b128 v[164:167], v173 offset:17408
	ds_read_b128 v[174:177], v173 offset:18432
	ds_read_b128 v[178:181], v173 offset:19456
	ds_read_b128 v[182:185], v173 offset:20480
	ds_read_b128 v[186:189], v173 offset:21504
	ds_read_b128 v[190:193], v173 offset:22528
	ds_read_b128 v[200:203], v173 offset:23552
	s_nop 0
	global_load_lds_dwordx4 v169, s[12:13]
	s_add_i32 m0, s81, 0x2000
	s_nop 0
	global_load_lds_dwordx4 v171, s[12:13]
	s_add_u32 s12, s74, 0x160000
	s_addc_u32 s13, s75, 0
	s_add_i32 s81, vcc_lo, s97
	s_mov_b32 m0, s81
	s_nop 0
	global_load_lds_dwordx4 v169, s[12:13]
	s_add_i32 m0, s81, 0x2000
	s_nop 0
	global_load_lds_dwordx4 v171, s[12:13]
	s_mov_b64 s[12:13], s[56:57]
	s_mov_b32 m0, s2
	s_nop 0
	global_load_lds_dwordx4 v168, s[12:13]
	s_mov_b32 m0, s65
	s_nop 0
	global_load_lds_dwordx4 v170, s[12:13]
	s_waitcnt vmcnt(8)
	s_waitcnt lgkmcnt(0)
	s_barrier
	s_setprio 1
	s_waitcnt lgkmcnt(0)
	v_mfma_f32_16x16x32_bf16 v[60:63], v[120:123], v[160:163], v[60:63]
	v_mfma_f32_16x16x32_bf16 v[60:63], v[124:127], v[164:167], v[60:63]
	v_mfma_f32_16x16x32_bf16 v[48:51], v[120:123], v[174:177], v[48:51]
	v_mfma_f32_16x16x32_bf16 v[48:51], v[124:127], v[178:181], v[48:51]
	v_mfma_f32_16x16x32_bf16 v[32:35], v[120:123], v[182:185], v[32:35]
	v_mfma_f32_16x16x32_bf16 v[32:35], v[124:127], v[186:189], v[32:35]
	v_mfma_f32_16x16x32_bf16 v[16:19], v[120:123], v[190:193], v[16:19]
	v_mfma_f32_16x16x32_bf16 v[16:19], v[124:127], v[200:203], v[16:19]
	v_mfma_f32_16x16x32_bf16 v[56:59], v[132:135], v[160:163], v[56:59]
	v_mfma_f32_16x16x32_bf16 v[56:59], v[136:139], v[164:167], v[56:59]
	v_mfma_f32_16x16x32_bf16 v[40:43], v[132:135], v[174:177], v[40:43]
	v_mfma_f32_16x16x32_bf16 v[40:43], v[136:139], v[178:181], v[40:43]
	v_mfma_f32_16x16x32_bf16 v[24:27], v[132:135], v[182:185], v[24:27]
	v_mfma_f32_16x16x32_bf16 v[24:27], v[136:139], v[186:189], v[24:27]
	v_mfma_f32_16x16x32_bf16 v[8:11], v[132:135], v[190:193], v[8:11]
	v_mfma_f32_16x16x32_bf16 v[8:11], v[136:139], v[200:203], v[8:11]
	s_setprio 0
	s_setprio 1
	v_mfma_f32_16x16x32_bf16 v[52:55], v[144:147], v[160:163], v[52:55]
	v_mfma_f32_16x16x32_bf16 v[52:55], v[148:151], v[164:167], v[52:55]
	v_mfma_f32_16x16x32_bf16 v[36:39], v[144:147], v[174:177], v[36:39]
	v_mfma_f32_16x16x32_bf16 v[36:39], v[148:151], v[178:181], v[36:39]
	v_mfma_f32_16x16x32_bf16 v[20:23], v[144:147], v[182:185], v[20:23]
	v_mfma_f32_16x16x32_bf16 v[20:23], v[148:151], v[186:189], v[20:23]
	v_mfma_f32_16x16x32_bf16 v[4:7], v[144:147], v[190:193], v[4:7]
	v_mfma_f32_16x16x32_bf16 v[4:7], v[148:151], v[200:203], v[4:7]
	v_mfma_f32_16x16x32_bf16 v[44:47], v[152:155], v[160:163], v[44:47]
	v_mfma_f32_16x16x32_bf16 v[44:47], v[156:159], v[164:167], v[44:47]
	v_mfma_f32_16x16x32_bf16 v[28:31], v[152:155], v[174:177], v[28:31]
	v_mfma_f32_16x16x32_bf16 v[28:31], v[156:159], v[178:181], v[28:31]
	v_mfma_f32_16x16x32_bf16 v[12:15], v[152:155], v[182:185], v[12:15]
	v_mfma_f32_16x16x32_bf16 v[12:15], v[156:159], v[186:189], v[12:15]
	v_mfma_f32_16x16x32_bf16 v[0:3], v[152:155], v[190:193], v[0:3]
	v_mfma_f32_16x16x32_bf16 v[0:3], v[156:159], v[200:203], v[0:3]
	s_setprio 0
	s_barrier
	s_add_i32 s81, 0, 0x18000
	s_add_i32 vcc_lo, 0, 0x1c000
	v_add_u32_e32 v136, s81, v172
	v_add_u32_e32 v156, vcc_lo, v172
	ds_read_b128 v[120:123], v136
	ds_read_b128 v[124:127], v136 offset:1024
	ds_read_b128 v[132:135], v136 offset:2048
	ds_read_b128 v[136:139], v136 offset:3072
	ds_read_b128 v[144:147], v156
	ds_read_b128 v[148:151], v156 offset:1024
	ds_read_b128 v[152:155], v156 offset:2048
	ds_read_b128 v[156:159], v156 offset:3072
	s_add_u32 s12, s56, 0x160000
	s_addc_u32 s13, s57, 0
	s_mov_b32 m0, s93
	ds_read_b128 v[160:163], v173 offset:32768
	ds_read_b128 v[164:167], v173 offset:33792
	ds_read_b128 v[174:177], v173 offset:34816
	ds_read_b128 v[178:181], v173 offset:35840
	ds_read_b128 v[182:185], v173 offset:36864
	ds_read_b128 v[186:189], v173 offset:37888
	ds_read_b128 v[190:193], v173 offset:38912
	ds_read_b128 v[200:203], v173 offset:39936
	s_nop 0
	global_load_lds_dwordx4 v168, s[12:13]
	s_mov_b32 m0, s92
	s_nop 0
	global_load_lds_dwordx4 v170, s[12:13]
	s_waitcnt vmcnt(8)
	s_waitcnt lgkmcnt(0)
	s_barrier
	s_setprio 1
	s_waitcnt lgkmcnt(0)
	v_mfma_f32_16x16x32_bf16 v[140:143], v[120:123], v[160:163], v[140:143]
	v_mfma_f32_16x16x32_bf16 v[140:143], v[124:127], v[164:167], v[140:143]
	v_mfma_f32_16x16x32_bf16 v[116:119], v[120:123], v[174:177], v[116:119]
	v_mfma_f32_16x16x32_bf16 v[116:119], v[124:127], v[178:181], v[116:119]
	v_mfma_f32_16x16x32_bf16 v[96:99], v[120:123], v[182:185], v[96:99]
	v_mfma_f32_16x16x32_bf16 v[96:99], v[124:127], v[186:189], v[96:99]
	v_mfma_f32_16x16x32_bf16 v[84:87], v[120:123], v[190:193], v[84:87]
	v_mfma_f32_16x16x32_bf16 v[84:87], v[124:127], v[200:203], v[84:87]
	v_mfma_f32_16x16x32_bf16 v[128:131], v[132:135], v[160:163], v[128:131]
	v_mfma_f32_16x16x32_bf16 v[128:131], v[136:139], v[164:167], v[128:131]
	v_mfma_f32_16x16x32_bf16 v[104:107], v[132:135], v[174:177], v[104:107]
	v_mfma_f32_16x16x32_bf16 v[104:107], v[136:139], v[178:181], v[104:107]
	v_mfma_f32_16x16x32_bf16 v[88:91], v[132:135], v[182:185], v[88:91]
	v_mfma_f32_16x16x32_bf16 v[88:91], v[136:139], v[186:189], v[88:91]
	v_mfma_f32_16x16x32_bf16 v[72:75], v[132:135], v[190:193], v[72:75]
	v_mfma_f32_16x16x32_bf16 v[72:75], v[136:139], v[200:203], v[72:75]
	s_setprio 0
	s_setprio 1
	v_mfma_f32_16x16x32_bf16 v[112:115], v[144:147], v[160:163], v[112:115]
	v_mfma_f32_16x16x32_bf16 v[112:115], v[148:151], v[164:167], v[112:115]
	v_mfma_f32_16x16x32_bf16 v[100:103], v[144:147], v[174:177], v[100:103]
	v_mfma_f32_16x16x32_bf16 v[100:103], v[148:151], v[178:181], v[100:103]
	v_mfma_f32_16x16x32_bf16 v[80:83], v[144:147], v[182:185], v[80:83]
	v_mfma_f32_16x16x32_bf16 v[80:83], v[148:151], v[186:189], v[80:83]
	v_mfma_f32_16x16x32_bf16 v[68:71], v[144:147], v[190:193], v[68:71]
	v_mfma_f32_16x16x32_bf16 v[68:71], v[148:151], v[200:203], v[68:71]
	v_mfma_f32_16x16x32_bf16 v[108:111], v[152:155], v[160:163], v[108:111]
	v_mfma_f32_16x16x32_bf16 v[108:111], v[156:159], v[164:167], v[108:111]
	v_mfma_f32_16x16x32_bf16 v[92:95], v[152:155], v[174:177], v[92:95]
	v_mfma_f32_16x16x32_bf16 v[92:95], v[156:159], v[178:181], v[92:95]
	v_mfma_f32_16x16x32_bf16 v[76:79], v[152:155], v[182:185], v[76:79]
	v_mfma_f32_16x16x32_bf16 v[76:79], v[156:159], v[186:189], v[76:79]
	v_mfma_f32_16x16x32_bf16 v[64:67], v[152:155], v[190:193], v[64:67]
	v_mfma_f32_16x16x32_bf16 v[64:67], v[156:159], v[200:203], v[64:67]
	s_setprio 0
	s_barrier
	s_add_u32 s12, s74, 0x80
	s_addc_u32 s13, s75, 0
	s_add_i32 s56, s81, s97
	s_mov_b32 m0, s56
	ds_read_b128 v[160:163], v173 offset:49152
	ds_read_b128 v[164:167], v173 offset:50176
	ds_read_b128 v[174:177], v173 offset:51200
	ds_read_b128 v[178:181], v173 offset:52224
	ds_read_b128 v[182:185], v173 offset:53248
	ds_read_b128 v[186:189], v173 offset:54272
	ds_read_b128 v[190:193], v173 offset:55296
	ds_read_b128 v[200:203], v173 offset:56320
	s_nop 0
	global_load_lds_dwordx4 v169, s[12:13]
	s_add_i32 m0, s56, 0x2000
	s_nop 0
	global_load_lds_dwordx4 v171, s[12:13]
	s_add_u32 s12, s74, 0x160080
	s_addc_u32 s13, s75, 0
	s_add_i32 s56, vcc_lo, s97
	s_mov_b32 m0, s56
	s_nop 0
	global_load_lds_dwordx4 v169, s[12:13]
	s_add_i32 m0, s56, 0x2000
	s_nop 0
	global_load_lds_dwordx4 v171, s[12:13]
	s_mov_b32 m0, s19
	s_nop 0
	global_load_lds_dwordx4 v168, s[16:17]
	s_mov_b32 m0, s89
	s_nop 0
	global_load_lds_dwordx4 v170, s[16:17]
	s_waitcnt vmcnt(8)
	s_waitcnt lgkmcnt(0)
	s_barrier
	s_setprio 1
	s_waitcnt lgkmcnt(0)
	v_mfma_f32_16x16x32_bf16 v[60:63], v[120:123], v[160:163], v[60:63]
	v_mfma_f32_16x16x32_bf16 v[60:63], v[124:127], v[164:167], v[60:63]
	v_mfma_f32_16x16x32_bf16 v[48:51], v[120:123], v[174:177], v[48:51]
	v_mfma_f32_16x16x32_bf16 v[48:51], v[124:127], v[178:181], v[48:51]
	v_mfma_f32_16x16x32_bf16 v[32:35], v[120:123], v[182:185], v[32:35]
	v_mfma_f32_16x16x32_bf16 v[32:35], v[124:127], v[186:189], v[32:35]
	v_mfma_f32_16x16x32_bf16 v[16:19], v[120:123], v[190:193], v[16:19]
	v_mfma_f32_16x16x32_bf16 v[16:19], v[124:127], v[200:203], v[16:19]
	v_mfma_f32_16x16x32_bf16 v[56:59], v[132:135], v[160:163], v[56:59]
	v_mfma_f32_16x16x32_bf16 v[56:59], v[136:139], v[164:167], v[56:59]
	v_mfma_f32_16x16x32_bf16 v[40:43], v[132:135], v[174:177], v[40:43]
	v_mfma_f32_16x16x32_bf16 v[40:43], v[136:139], v[178:181], v[40:43]
	v_mfma_f32_16x16x32_bf16 v[24:27], v[132:135], v[182:185], v[24:27]
	v_mfma_f32_16x16x32_bf16 v[24:27], v[136:139], v[186:189], v[24:27]
	v_mfma_f32_16x16x32_bf16 v[8:11], v[132:135], v[190:193], v[8:11]
	v_mfma_f32_16x16x32_bf16 v[8:11], v[136:139], v[200:203], v[8:11]
	s_setprio 0
	s_setprio 1
	v_mfma_f32_16x16x32_bf16 v[52:55], v[144:147], v[160:163], v[52:55]
	v_mfma_f32_16x16x32_bf16 v[52:55], v[148:151], v[164:167], v[52:55]
	v_mfma_f32_16x16x32_bf16 v[36:39], v[144:147], v[174:177], v[36:39]
	v_mfma_f32_16x16x32_bf16 v[36:39], v[148:151], v[178:181], v[36:39]
	v_mfma_f32_16x16x32_bf16 v[20:23], v[144:147], v[182:185], v[20:23]
	v_mfma_f32_16x16x32_bf16 v[20:23], v[148:151], v[186:189], v[20:23]
	v_mfma_f32_16x16x32_bf16 v[4:7], v[144:147], v[190:193], v[4:7]
	v_mfma_f32_16x16x32_bf16 v[4:7], v[148:151], v[200:203], v[4:7]
	v_mfma_f32_16x16x32_bf16 v[44:47], v[152:155], v[160:163], v[44:47]
	v_mfma_f32_16x16x32_bf16 v[44:47], v[156:159], v[164:167], v[44:47]
	v_mfma_f32_16x16x32_bf16 v[28:31], v[152:155], v[174:177], v[28:31]
	v_mfma_f32_16x16x32_bf16 v[28:31], v[156:159], v[178:181], v[28:31]
	v_mfma_f32_16x16x32_bf16 v[12:15], v[152:155], v[182:185], v[12:15]
	v_mfma_f32_16x16x32_bf16 v[12:15], v[156:159], v[186:189], v[12:15]
	v_mfma_f32_16x16x32_bf16 v[0:3], v[152:155], v[190:193], v[0:3]
	v_mfma_f32_16x16x32_bf16 v[0:3], v[156:159], v[200:203], v[0:3]
	s_setprio 0
	s_barrier
	s_add_i32 s80, s80, 2
	s_add_u32 s4, s4, 0x100
	s_addc_u32 s5, s5, 0
	s_add_u32 s15, s15, 0x100
	s_addc_u32 s72, s72, 0
	s_add_u32 s28, s28, 0x100
	s_addc_u32 s29, s29, 0
	s_cmpk_gt_u32 s80, 0x55
	s_cbranch_scc0 .LBB0_1425
	s_and_b64 vcc, exec, s[60:61]
	s_cbranch_vccz .LBB0_1428
	s_barrier

.LBB0_1579:
	s_cmp_eq_u32 s49, 4
	s_cselect_b32 s26, s14, s13
	s_cselect_b32 s27, s15, s21
	s_cselect_b32 s24, s16, s47
	s_cselect_b32 s25, s17, s48
	s_add_u32 s22, s26, 0x80
	s_addc_u32 s23, s27, 0
	s_add_i32 s65, 0, 0x10000
	s_add_i32 s69, 0, 0x14000
	v_add_u32_e32 v132, s65, v154
	v_add_u32_e32 v148, s69, v154
	ds_read_b128 v[112:115], v132
	ds_read_b128 v[120:123], v132 offset:1024
	ds_read_b128 v[128:131], v132 offset:2048
	ds_read_b128 v[132:135], v132 offset:3072
	ds_read_b128 v[144:147], v148
	ds_read_b128 v[156:159], v148 offset:1024
	ds_read_b128 v[160:163], v148 offset:2048
	ds_read_b128 v[164:167], v148 offset:3072
	s_add_u32 s56, s13, 0x15ff80
	s_addc_u32 s57, s21, 0
	s_add_i32 m0, s31, 0xc000
	ds_read_b128 v[168:171], v155
	ds_read_b128 v[172:175], v155 offset:1024
	ds_read_b128 v[176:179], v155 offset:2048
	ds_read_b128 v[180:183], v155 offset:3072
	ds_read_b128 v[184:187], v155 offset:4096
	ds_read_b128 v[188:191], v155 offset:5120
	ds_read_b128 v[192:195], v155 offset:6144
	ds_read_b128 v[200:203], v155 offset:7168
	s_nop 0
	global_load_lds_dwordx4 v151, s[56:57]
	s_add_i32 m0, s31, 0xe000
	s_nop 0
	global_load_lds_dwordx4 v150, s[56:57]
	s_waitcnt vmcnt(8)
	s_waitcnt lgkmcnt(0)
	s_barrier
	s_setprio 1
	s_waitcnt lgkmcnt(0)
	v_mfma_f32_16x16x32_bf16 v[140:143], v[112:115], v[168:171], v[140:143]
	v_mfma_f32_16x16x32_bf16 v[140:143], v[120:123], v[172:175], v[140:143]
	v_mfma_f32_16x16x32_bf16 v[108:111], v[112:115], v[176:179], v[108:111]
	v_mfma_f32_16x16x32_bf16 v[108:111], v[120:123], v[180:183], v[108:111]
	v_mfma_f32_16x16x32_bf16 v[92:95], v[112:115], v[184:187], v[92:95]
	v_mfma_f32_16x16x32_bf16 v[92:95], v[120:123], v[188:191], v[92:95]
	v_mfma_f32_16x16x32_bf16 v[76:79], v[112:115], v[192:195], v[76:79]
	v_mfma_f32_16x16x32_bf16 v[76:79], v[120:123], v[200:203], v[76:79]
	v_mfma_f32_16x16x32_bf16 v[136:139], v[128:131], v[168:171], v[136:139]
	v_mfma_f32_16x16x32_bf16 v[136:139], v[132:135], v[172:175], v[136:139]
	v_mfma_f32_16x16x32_bf16 v[104:107], v[128:131], v[176:179], v[104:107]
	v_mfma_f32_16x16x32_bf16 v[104:107], v[132:135], v[180:183], v[104:107]
	v_mfma_f32_16x16x32_bf16 v[88:91], v[128:131], v[184:187], v[88:91]
	v_mfma_f32_16x16x32_bf16 v[88:91], v[132:135], v[188:191], v[88:91]
	v_mfma_f32_16x16x32_bf16 v[72:75], v[128:131], v[192:195], v[72:75]
	v_mfma_f32_16x16x32_bf16 v[72:75], v[132:135], v[200:203], v[72:75]
	s_setprio 0
	s_setprio 1
	v_mfma_f32_16x16x32_bf16 v[124:127], v[144:147], v[168:171], v[124:127]
	v_mfma_f32_16x16x32_bf16 v[124:127], v[156:159], v[172:175], v[124:127]
	v_mfma_f32_16x16x32_bf16 v[100:103], v[144:147], v[176:179], v[100:103]
	v_mfma_f32_16x16x32_bf16 v[100:103], v[156:159], v[180:183], v[100:103]
	v_mfma_f32_16x16x32_bf16 v[84:87], v[144:147], v[184:187], v[84:87]
	v_mfma_f32_16x16x32_bf16 v[84:87], v[156:159], v[188:191], v[84:87]
	v_mfma_f32_16x16x32_bf16 v[68:71], v[144:147], v[192:195], v[68:71]
	v_mfma_f32_16x16x32_bf16 v[68:71], v[156:159], v[200:203], v[68:71]
	v_mfma_f32_16x16x32_bf16 v[116:119], v[160:163], v[168:171], v[116:119]
	v_mfma_f32_16x16x32_bf16 v[116:119], v[164:167], v[172:175], v[116:119]
	v_mfma_f32_16x16x32_bf16 v[96:99], v[160:163], v[176:179], v[96:99]
	v_mfma_f32_16x16x32_bf16 v[96:99], v[164:167], v[180:183], v[96:99]
	v_mfma_f32_16x16x32_bf16 v[80:83], v[160:163], v[184:187], v[80:83]
	v_mfma_f32_16x16x32_bf16 v[80:83], v[164:167], v[188:191], v[80:83]
	v_mfma_f32_16x16x32_bf16 v[64:67], v[160:163], v[192:195], v[64:67]
	v_mfma_f32_16x16x32_bf16 v[64:67], v[164:167], v[200:203], v[64:67]
	s_setprio 0
	s_barrier
	s_add_i32 s65, s65, s97
	s_mov_b64 s[56:57], s[24:25]
	s_mov_b32 m0, s65
	ds_read_b128 v[168:171], v155 offset:16384
	ds_read_b128 v[172:175], v155 offset:17408
	ds_read_b128 v[176:179], v155 offset:18432
	ds_read_b128 v[180:183], v155 offset:19456
	ds_read_b128 v[184:187], v155 offset:20480
	ds_read_b128 v[188:191], v155 offset:21504
	ds_read_b128 v[192:195], v155 offset:22528
	ds_read_b128 v[200:203], v155 offset:23552
	s_nop 0
	global_load_lds_dwordx4 v152, s[56:57]
	s_add_i32 m0, s65, 0x2000
	s_nop 0
	global_load_lds_dwordx4 v153, s[56:57]
	s_add_u32 s56, s24, 0x160000
	s_addc_u32 s57, s25, 0
	s_add_i32 s65, s69, s97
	s_mov_b32 m0, s65
	s_nop 0
	global_load_lds_dwordx4 v152, s[56:57]
	s_add_i32 m0, s65, 0x2000
	s_nop 0
	global_load_lds_dwordx4 v153, s[56:57]
	s_mov_b64 s[56:57], s[26:27]
	s_mov_b32 m0, s31
	s_nop 0
	global_load_lds_dwordx4 v151, s[56:57]
	s_mov_b32 m0, s34
	s_nop 0
	global_load_lds_dwordx4 v150, s[56:57]
	s_waitcnt vmcnt(8)
	s_waitcnt lgkmcnt(0)
	s_barrier
	s_setprio 1
	s_waitcnt lgkmcnt(0)
	v_mfma_f32_16x16x32_bf16 v[60:63], v[112:115], v[168:171], v[60:63]
	v_mfma_f32_16x16x32_bf16 v[60:63], v[120:123], v[172:175], v[60:63]
	v_mfma_f32_16x16x32_bf16 v[52:55], v[112:115], v[176:179], v[52:55]
	v_mfma_f32_16x16x32_bf16 v[52:55], v[120:123], v[180:183], v[52:55]
	v_mfma_f32_16x16x32_bf16 v[36:39], v[112:115], v[184:187], v[36:39]
	v_mfma_f32_16x16x32_bf16 v[36:39], v[120:123], v[188:191], v[36:39]
	v_mfma_f32_16x16x32_bf16 v[20:23], v[112:115], v[192:195], v[20:23]
	v_mfma_f32_16x16x32_bf16 v[20:23], v[120:123], v[200:203], v[20:23]
	v_mfma_f32_16x16x32_bf16 v[56:59], v[128:131], v[168:171], v[56:59]
	v_mfma_f32_16x16x32_bf16 v[56:59], v[132:135], v[172:175], v[56:59]
	v_mfma_f32_16x16x32_bf16 v[44:47], v[128:131], v[176:179], v[44:47]
	v_mfma_f32_16x16x32_bf16 v[44:47], v[132:135], v[180:183], v[44:47]
	v_mfma_f32_16x16x32_bf16 v[28:31], v[128:131], v[184:187], v[28:31]
	v_mfma_f32_16x16x32_bf16 v[28:31], v[132:135], v[188:191], v[28:31]
	v_mfma_f32_16x16x32_bf16 v[8:11], v[128:131], v[192:195], v[8:11]
	v_mfma_f32_16x16x32_bf16 v[8:11], v[132:135], v[200:203], v[8:11]
	s_setprio 0
	s_setprio 1
	v_mfma_f32_16x16x32_bf16 v[48:51], v[144:147], v[168:171], v[48:51]
	v_mfma_f32_16x16x32_bf16 v[48:51], v[156:159], v[172:175], v[48:51]
	v_mfma_f32_16x16x32_bf16 v[32:35], v[144:147], v[176:179], v[32:35]
	v_mfma_f32_16x16x32_bf16 v[32:35], v[156:159], v[180:183], v[32:35]
	v_mfma_f32_16x16x32_bf16 v[16:19], v[144:147], v[184:187], v[16:19]
	v_mfma_f32_16x16x32_bf16 v[16:19], v[156:159], v[188:191], v[16:19]
	v_mfma_f32_16x16x32_bf16 v[4:7], v[144:147], v[192:195], v[4:7]
	v_mfma_f32_16x16x32_bf16 v[4:7], v[156:159], v[200:203], v[4:7]
	v_mfma_f32_16x16x32_bf16 v[40:43], v[160:163], v[168:171], v[40:43]
	v_mfma_f32_16x16x32_bf16 v[40:43], v[164:167], v[172:175], v[40:43]
	v_mfma_f32_16x16x32_bf16 v[24:27], v[160:163], v[176:179], v[24:27]
	v_mfma_f32_16x16x32_bf16 v[24:27], v[164:167], v[180:183], v[24:27]
	v_mfma_f32_16x16x32_bf16 v[12:15], v[160:163], v[184:187], v[12:15]
	v_mfma_f32_16x16x32_bf16 v[12:15], v[164:167], v[188:191], v[12:15]
	v_mfma_f32_16x16x32_bf16 v[0:3], v[160:163], v[192:195], v[0:3]
	v_mfma_f32_16x16x32_bf16 v[0:3], v[164:167], v[200:203], v[0:3]
	s_setprio 0
	s_barrier
	s_add_i32 s56, 0, 0x18000
	s_add_i32 s57, 0, 0x1c000
	v_add_u32_e32 v132, s56, v154
	v_add_u32_e32 v148, s57, v154
	ds_read_b128 v[112:115], v132
	ds_read_b128 v[120:123], v132 offset:1024
	ds_read_b128 v[128:131], v132 offset:2048
	ds_read_b128 v[132:135], v132 offset:3072
	ds_read_b128 v[144:147], v148
	ds_read_b128 v[156:159], v148 offset:1024
	ds_read_b128 v[160:163], v148 offset:2048
	ds_read_b128 v[164:167], v148 offset:3072
	s_add_u32 s26, s26, 0x160000
	s_addc_u32 s27, s27, 0
	s_mov_b32 m0, s35
	ds_read_b128 v[168:171], v155 offset:32768
	ds_read_b128 v[172:175], v155 offset:33792
	ds_read_b128 v[176:179], v155 offset:34816
	ds_read_b128 v[180:183], v155 offset:35840
	ds_read_b128 v[184:187], v155 offset:36864
	ds_read_b128 v[188:191], v155 offset:37888
	ds_read_b128 v[192:195], v155 offset:38912
	ds_read_b128 v[200:203], v155 offset:39936
	s_nop 0
	global_load_lds_dwordx4 v151, s[26:27]
	s_mov_b32 m0, s36
	s_nop 0
	global_load_lds_dwordx4 v150, s[26:27]
	s_waitcnt vmcnt(8)
	s_waitcnt lgkmcnt(0)
	s_barrier
	s_setprio 1
	s_waitcnt lgkmcnt(0)
	v_mfma_f32_16x16x32_bf16 v[140:143], v[112:115], v[168:171], v[140:143]
	v_mfma_f32_16x16x32_bf16 v[140:143], v[120:123], v[172:175], v[140:143]
	v_mfma_f32_16x16x32_bf16 v[108:111], v[112:115], v[176:179], v[108:111]
	v_mfma_f32_16x16x32_bf16 v[108:111], v[120:123], v[180:183], v[108:111]
	v_mfma_f32_16x16x32_bf16 v[92:95], v[112:115], v[184:187], v[92:95]
	v_mfma_f32_16x16x32_bf16 v[92:95], v[120:123], v[188:191], v[92:95]
	v_mfma_f32_16x16x32_bf16 v[76:79], v[112:115], v[192:195], v[76:79]
	v_mfma_f32_16x16x32_bf16 v[76:79], v[120:123], v[200:203], v[76:79]
	v_mfma_f32_16x16x32_bf16 v[136:139], v[128:131], v[168:171], v[136:139]
	v_mfma_f32_16x16x32_bf16 v[136:139], v[132:135], v[172:175], v[136:139]
	v_mfma_f32_16x16x32_bf16 v[104:107], v[128:131], v[176:179], v[104:107]
	v_mfma_f32_16x16x32_bf16 v[104:107], v[132:135], v[180:183], v[104:107]
	v_mfma_f32_16x16x32_bf16 v[88:91], v[128:131], v[184:187], v[88:91]
	v_mfma_f32_16x16x32_bf16 v[88:91], v[132:135], v[188:191], v[88:91]
	v_mfma_f32_16x16x32_bf16 v[72:75], v[128:131], v[192:195], v[72:75]
	v_mfma_f32_16x16x32_bf16 v[72:75], v[132:135], v[200:203], v[72:75]
	s_setprio 0
	s_setprio 1
	v_mfma_f32_16x16x32_bf16 v[124:127], v[144:147], v[168:171], v[124:127]
	v_mfma_f32_16x16x32_bf16 v[124:127], v[156:159], v[172:175], v[124:127]
	v_mfma_f32_16x16x32_bf16 v[100:103], v[144:147], v[176:179], v[100:103]
	v_mfma_f32_16x16x32_bf16 v[100:103], v[156:159], v[180:183], v[100:103]
	v_mfma_f32_16x16x32_bf16 v[84:87], v[144:147], v[184:187], v[84:87]
	v_mfma_f32_16x16x32_bf16 v[84:87], v[156:159], v[188:191], v[84:87]
	v_mfma_f32_16x16x32_bf16 v[68:71], v[144:147], v[192:195], v[68:71]
	v_mfma_f32_16x16x32_bf16 v[68:71], v[156:159], v[200:203], v[68:71]
	v_mfma_f32_16x16x32_bf16 v[116:119], v[160:163], v[168:171], v[116:119]
	v_mfma_f32_16x16x32_bf16 v[116:119], v[164:167], v[172:175], v[116:119]
	v_mfma_f32_16x16x32_bf16 v[96:99], v[160:163], v[176:179], v[96:99]
	v_mfma_f32_16x16x32_bf16 v[96:99], v[164:167], v[180:183], v[96:99]
	v_mfma_f32_16x16x32_bf16 v[80:83], v[160:163], v[184:187], v[80:83]
	v_mfma_f32_16x16x32_bf16 v[80:83], v[164:167], v[188:191], v[80:83]
	v_mfma_f32_16x16x32_bf16 v[64:67], v[160:163], v[192:195], v[64:67]
	v_mfma_f32_16x16x32_bf16 v[64:67], v[164:167], v[200:203], v[64:67]
	s_setprio 0
	s_barrier
	s_add_u32 s26, s24, 0x80
	s_addc_u32 s27, s25, 0
	s_add_i32 s56, s56, s97
	s_mov_b32 m0, s56
	ds_read_b128 v[168:171], v155 offset:49152
	ds_read_b128 v[172:175], v155 offset:50176
	ds_read_b128 v[176:179], v155 offset:51200
	ds_read_b128 v[180:183], v155 offset:52224
	ds_read_b128 v[184:187], v155 offset:53248
	ds_read_b128 v[188:191], v155 offset:54272
	ds_read_b128 v[192:195], v155 offset:55296
	ds_read_b128 v[200:203], v155 offset:56320
	s_nop 0
	global_load_lds_dwordx4 v152, s[26:27]
	s_add_i32 m0, s56, 0x2000
	s_add_u32 s24, s24, 0x160080
	s_addc_u32 s25, s25, 0
	global_load_lds_dwordx4 v153, s[26:27]
	s_add_i32 s26, s57, s97
	s_mov_b32 m0, s26
	s_nop 0
	global_load_lds_dwordx4 v152, s[24:25]
	s_add_i32 m0, s26, 0x2000
	s_nop 0
	global_load_lds_dwordx4 v153, s[24:25]
	s_mov_b32 m0, s37
	s_nop 0
	global_load_lds_dwordx4 v151, s[22:23]
	s_mov_b32 m0, s38
	s_nop 0
	global_load_lds_dwordx4 v150, s[22:23]
	s_waitcnt vmcnt(8)
	s_waitcnt lgkmcnt(0)
	s_barrier
	s_setprio 1
	s_waitcnt lgkmcnt(0)
	v_mfma_f32_16x16x32_bf16 v[60:63], v[112:115], v[168:171], v[60:63]
	v_mfma_f32_16x16x32_bf16 v[60:63], v[120:123], v[172:175], v[60:63]
	v_mfma_f32_16x16x32_bf16 v[52:55], v[112:115], v[176:179], v[52:55]
	v_mfma_f32_16x16x32_bf16 v[52:55], v[120:123], v[180:183], v[52:55]
	v_mfma_f32_16x16x32_bf16 v[36:39], v[112:115], v[184:187], v[36:39]
	v_mfma_f32_16x16x32_bf16 v[36:39], v[120:123], v[188:191], v[36:39]
	v_mfma_f32_16x16x32_bf16 v[20:23], v[112:115], v[192:195], v[20:23]
	v_mfma_f32_16x16x32_bf16 v[20:23], v[120:123], v[200:203], v[20:23]
	v_mfma_f32_16x16x32_bf16 v[56:59], v[128:131], v[168:171], v[56:59]
	v_mfma_f32_16x16x32_bf16 v[56:59], v[132:135], v[172:175], v[56:59]
	v_mfma_f32_16x16x32_bf16 v[44:47], v[128:131], v[176:179], v[44:47]
	v_mfma_f32_16x16x32_bf16 v[44:47], v[132:135], v[180:183], v[44:47]
	v_mfma_f32_16x16x32_bf16 v[28:31], v[128:131], v[184:187], v[28:31]
	v_mfma_f32_16x16x32_bf16 v[28:31], v[132:135], v[188:191], v[28:31]
	v_mfma_f32_16x16x32_bf16 v[8:11], v[128:131], v[192:195], v[8:11]
	v_mfma_f32_16x16x32_bf16 v[8:11], v[132:135], v[200:203], v[8:11]
	s_setprio 0
	s_setprio 1
	v_mfma_f32_16x16x32_bf16 v[48:51], v[144:147], v[168:171], v[48:51]
	v_mfma_f32_16x16x32_bf16 v[48:51], v[156:159], v[172:175], v[48:51]
	v_mfma_f32_16x16x32_bf16 v[32:35], v[144:147], v[176:179], v[32:35]
	v_mfma_f32_16x16x32_bf16 v[32:35], v[156:159], v[180:183], v[32:35]
	v_mfma_f32_16x16x32_bf16 v[16:19], v[144:147], v[184:187], v[16:19]
	v_mfma_f32_16x16x32_bf16 v[16:19], v[156:159], v[188:191], v[16:19]
	v_mfma_f32_16x16x32_bf16 v[4:7], v[144:147], v[192:195], v[4:7]
	v_mfma_f32_16x16x32_bf16 v[4:7], v[156:159], v[200:203], v[4:7]
	v_mfma_f32_16x16x32_bf16 v[40:43], v[160:163], v[168:171], v[40:43]
	v_mfma_f32_16x16x32_bf16 v[40:43], v[164:167], v[172:175], v[40:43]
	v_mfma_f32_16x16x32_bf16 v[24:27], v[160:163], v[176:179], v[24:27]
	v_mfma_f32_16x16x32_bf16 v[24:27], v[164:167], v[180:183], v[24:27]
	v_mfma_f32_16x16x32_bf16 v[12:15], v[160:163], v[184:187], v[12:15]
	v_mfma_f32_16x16x32_bf16 v[12:15], v[164:167], v[188:191], v[12:15]
	v_mfma_f32_16x16x32_bf16 v[0:3], v[160:163], v[192:195], v[0:3]
	v_mfma_f32_16x16x32_bf16 v[0:3], v[164:167], v[200:203], v[0:3]
	s_setprio 0
	s_barrier
	s_add_i32 s49, s49, 2
	s_add_u32 s13, s13, 0x100
	s_addc_u32 s21, s21, 0
	s_add_u32 s47, s47, 0x100
	s_addc_u32 s48, s48, 0
	s_cmp_gt_u32 s49, 5
	s_cbranch_scc0 .LBB0_1579
	s_and_b64 vcc, exec, s[60:61]
	s_cbranch_vccz .LBB0_1582
	s_barrier
